# vmcnt+lgkmcnt waits merged into one s_waitcnt at 28 load-segment ends; SP3-head A-address v_add hoisted into preceding MFMA run (7 sites), on top of SALU-shadow stack
# baseline (speedup 1.0000x reference)
;     __host__ __device__ bool next(int i, Unit& u) const { const int t = i / 3, b = i - 3 * t; Unit v; if (!StaticOrder::next(t, v)) return false; u.pm = v.pm; u.pn = 8 * b + v.pn; return true; }
; #define PG8_STAGE(bufoff, gbase, voff) do { const int so_ = (int)(unsigned)((const char*)(gbase) - base_##voff); _Pragma("unroll") for (int _i = 0; _i < 2; ++_i) \
;         __builtin_amdgcn_raw_ptr_buffer_load_lds(rs_##voff, (PG8_LAS unsigned*)(lds + (bufoff) + ldsw + _i * 8192), 16, (int)(voff)[_i], so_, 0, 0); } while (0)
; #define PG8_LDA(dst, b, h) do { _Pragma("unroll") for (int m = 0; m < 4; ++m) _Pragma("unroll") for (int k = 0; k < 2; ++k) dst[m][k] = *(const PG8_LAS bf16x8*)(lds + PG8_SA(b, h) + aoff + m * 2048 + k * 1024); } while (0)
; #define PG8_WAIT_V(n) asm volatile("s_waitcnt vmcnt(" #n ")" ::: "memory")
; #define PG8_WAIT_L(n) asm volatile("s_waitcnt lgkmcnt(" #n ")" ::: "memory")
; #define PG8_BAR __builtin_amdgcn_s_barrier()
; template <class Epi, class Sched, bool ALIGN_EPI = false, bool SP2 = false>
; __device__ __forceinline__ void gemm_phase(PG8_LAS unsigned char* lds, const Gemm g, const Sched& S, const Epi& E, int tid_in) {
;     ...
;         const bool has_next = S.next(ui + 1, nxt);
;         const char* nA = has_next ? (const char*)g.A + (size_t)nxt.pm * tstepA + (g.grp ? (size_t)(nxt.pn / g.grp) * g.agrp : (size_t)0) : cA; const char* nB = has_next ? (const char*)g.Bt + (size_t)nxt.pn * tstepB : cB;
;         for (int t = 0; t < nt; t += 2) {
;             const bool last = (t == nt - 2);
;             const char* a1 = cA + (size_t)(t + 1) * kstep;
;             const char* a2 = last ? nA : cA + (size_t)(t + 2) * kstep; const char* b2 = last ? nB : cB + (size_t)(t + 2) * kstep;
;             const char* a3 = a2 + kstep; const char* b3 = b2 + kstep;
;             if (last && has_next) S.a_ready(nxt);
;             if constexpr (SP2) {
;             PG8_LDB(B0, 0, 0); PG8_LDB(B1, 0, 1); PG8_SCHED; PG8_LDA(At, 0, 0); PG8_STAGE(PG8_SA(1, 1), a1 + hstepA, voffA);
;             PG8_WAIT_V(8); PG8_WAIT_L(0); PG8_BAR; PG8_MMA(0, 0, At, B0); PG8_MMA(0, 1, At, B1); PG8_BAR; PG8_SCHED;
;             PG8_LDA(At, 0, 1); PG8_STAGE(PG8_SB(0, 0), b2, voffB); PG8_STAGE(PG8_SB(0, 1), b2 + hstepB, voffB); PG8_STAGE(PG8_SA(0, 0), a2, voffA);
;             PG8_WAIT_V(8); PG8_WAIT_L(0); PG8_BAR; PG8_MMA(1, 0, At, B0); PG8_MMA(1, 1, At, B1); PG8_BAR; PG8_SCHED;
.LBB0_311:
	s_ashr_i32 s23, s22, 31
	s_lshl_b64 s[10:11], s[22:23], 20
	s_add_u32 s24, s4, s10
	s_addc_u32 s25, s26, s11
	s_and_b64 s[10:11], s[34:35], exec
	s_cselect_b32 s19, s24, s12
	s_ashr_i32 s15, s14, 31
	s_lshl_b64 s[10:11], s[14:15], 20
	s_add_u32 s10, s40, s10
	s_addc_u32 s11, s60, s11
	s_and_b64 s[20:21], s[34:35], exec
	s_cselect_b32 s15, s10, s16
	s_add_u32 s20, s16, 0x100
	v_mov_b32_e32 v2, 0
	s_addc_u32 s21, s17, 0
	s_mov_b32 s23, -2
	v_add_u32_e32 v0, 0x10000, v237
	ds_read_b128 v[130:133], v0
	ds_read_b128 v[134:137], v0 offset:1024
	ds_read_b128 v[138:141], v0 offset:2048
	ds_read_b128 v[142:145], v0 offset:3072
	v_add_u32_e32 v0, 0x14000, v237
	ds_read_b128 v[146:149], v0
	ds_read_b128 v[150:153], v0 offset:1024
	ds_read_b128 v[154:157], v0 offset:2048
	ds_read_b128 v[158:161], v0 offset:3072
	s_add_u32 s16, s12, 0x100
	s_addc_u32 s17, s13, 0
	s_sub_i32 s12, s12, s4
	s_add_i32 s12, s12, 0x80080
	s_sub_i32 s36, s12, 0x80000
	s_cmp_eq_u32 s23, 28
	s_cselect_b32 s13, s19, s16
	s_mov_b32 m0, s69
	ds_read_b128 v[162:165], v238
	ds_read_b128 v[166:169], v238 offset:1024
	ds_read_b128 v[170:173], v238 offset:2048
	ds_read_b128 v[174:177], v238 offset:3072
	ds_read_b128 v[178:181], v238 offset:4096
	ds_read_b128 v[182:185], v238 offset:5120
	ds_read_b128 v[186:189], v238 offset:6144
	ds_read_b128 v[190:193], v238 offset:7168
	s_mov_b32 m0, s78
	s_nop 0
	buffer_load_dwordx4 v211, s[4:7], s36 offen lds
	s_mov_b32 m0, s69
	s_nop 0
	buffer_load_dwordx4 v195, s[4:7], s12 offen lds
	s_mov_b32 m0, s67
	s_nop 0
	buffer_load_dwordx4 v211, s[4:7], s12 offen lds
	s_waitcnt vmcnt(8) lgkmcnt(0)
	s_setprio 1
	s_barrier
	v_mfma_f32_16x16x32_bf16 v[126:129], v[130:133], v[162:165], 0
	v_mfma_f32_16x16x32_bf16 v[122:125], v[138:141], v[162:165], 0
	v_mfma_f32_16x16x32_bf16 v[106:109], v[138:141], v[170:173], 0
	v_mfma_f32_16x16x32_bf16 v[110:113], v[130:133], v[170:173], 0
	v_mfma_f32_16x16x32_bf16 v[94:97], v[130:133], v[178:181], 0
	v_mfma_f32_16x16x32_bf16 v[90:93], v[138:141], v[178:181], 0
	v_mfma_f32_16x16x32_bf16 v[74:77], v[138:141], v[186:189], 0
	v_mfma_f32_16x16x32_bf16 v[78:81], v[130:133], v[186:189], 0
	s_cselect_b32 s12, s15, s20
	v_mfma_f32_16x16x32_bf16 v[126:129], v[134:137], v[166:169], v[126:129]
	s_mov_b32 m0, s61
	v_mfma_f32_16x16x32_bf16 v[122:125], v[142:145], v[166:169], v[122:125]
	s_mov_b32 s42, s6
	v_mfma_f32_16x16x32_bf16 v[106:109], v[142:145], v[174:177], v[106:109]
	s_mov_b32 s43, s7
	v_mfma_f32_16x16x32_bf16 v[110:113], v[134:137], v[174:177], v[110:113]
	s_sub_i32 s12, s12, s40
	v_mfma_f32_16x16x32_bf16 v[94:97], v[134:137], v[182:185], v[94:97]
	v_mfma_f32_16x16x32_bf16 v[90:93], v[142:145], v[182:185], v[90:93]
	v_mfma_f32_16x16x32_bf16 v[74:77], v[142:145], v[190:193], v[74:77]
	v_mfma_f32_16x16x32_bf16 v[78:81], v[134:137], v[190:193], v[78:81]
	v_mfma_f32_16x16x32_bf16 v[118:121], v[146:149], v[162:165], 0
	v_mfma_f32_16x16x32_bf16 v[114:117], v[154:157], v[162:165], 0
	v_mfma_f32_16x16x32_bf16 v[98:101], v[154:157], v[170:173], 0
	v_mfma_f32_16x16x32_bf16 v[102:105], v[146:149], v[170:173], 0
	v_mfma_f32_16x16x32_bf16 v[86:89], v[146:149], v[178:181], 0
	v_mfma_f32_16x16x32_bf16 v[82:85], v[154:157], v[178:181], 0
	v_mfma_f32_16x16x32_bf16 v[66:69], v[154:157], v[186:189], 0
	v_mfma_f32_16x16x32_bf16 v[70:73], v[146:149], v[186:189], 0
	v_mfma_f32_16x16x32_bf16 v[118:121], v[150:153], v[166:169], v[118:121]
	v_mfma_f32_16x16x32_bf16 v[114:117], v[158:161], v[166:169], v[114:117]
	v_mfma_f32_16x16x32_bf16 v[98:101], v[158:161], v[174:177], v[98:101]
	v_mfma_f32_16x16x32_bf16 v[102:105], v[150:153], v[174:177], v[102:105]
	v_mfma_f32_16x16x32_bf16 v[86:89], v[150:153], v[182:185], v[86:89]
	v_mfma_f32_16x16x32_bf16 v[82:85], v[158:161], v[182:185], v[82:85]
	v_mfma_f32_16x16x32_bf16 v[66:69], v[158:161], v[190:193], v[66:69]
	v_mfma_f32_16x16x32_bf16 v[70:73], v[150:153], v[190:193], v[70:73]
	s_barrier
	s_setprio 0
	ds_read_b128 v[162:165], v238 offset:16384
	ds_read_b128 v[166:169], v238 offset:17408
	ds_read_b128 v[170:173], v238 offset:18432
	ds_read_b128 v[174:177], v238 offset:19456
	ds_read_b128 v[178:181], v238 offset:20480
	ds_read_b128 v[182:185], v238 offset:21504
	ds_read_b128 v[186:189], v238 offset:22528
	ds_read_b128 v[190:193], v238 offset:23552
	buffer_load_dwordx4 v207, s[40:43], s12 offen lds
	s_mov_b32 m0, s62
	s_add_i32 s36, s12, 0x80000
	buffer_load_dwordx4 v224, s[40:43], s12 offen lds
	s_mov_b32 m0, s63
	s_sub_i32 s13, s13, s4
	buffer_load_dwordx4 v207, s[40:43], s36 offen lds
	s_mov_b32 m0, s71
	s_nop 0
	buffer_load_dwordx4 v224, s[40:43], s36 offen lds
	s_mov_b32 m0, s53
	s_nop 0
	buffer_load_dwordx4 v195, s[4:7], s13 offen lds
	s_waitcnt vmcnt(7) lgkmcnt(0)
	s_setprio 1
	s_barrier
; #define PG8_STAGE(bufoff, gbase, voff) do { const int so_ = (int)(unsigned)((const char*)(gbase) - base_##voff); _Pragma("unroll") for (int _i = 0; _i < 2; ++_i) \
;         __builtin_amdgcn_raw_ptr_buffer_load_lds(rs_##voff, (PG8_LAS unsigned*)(lds + (bufoff) + ldsw + _i * 8192), 16, (int)(voff)[_i], so_, 0, 0); } while (0)
; #define PG8_LDA(dst, b, h) do { _Pragma("unroll") for (int m = 0; m < 4; ++m) _Pragma("unroll") for (int k = 0; k < 2; ++k) dst[m][k] = *(const PG8_LAS bf16x8*)(lds + PG8_SA(b, h) + aoff + m * 2048 + k * 1024); } while (0)
; #define PG8_LDB(dst, b, h) do { _Pragma("unroll") for (int n = 0; n < 2; ++n) _Pragma("unroll") for (int k = 0; k < 2; ++k) dst[n][k] = *(const PG8_LAS bf16x8*)(lds + PG8_SB(b, h) + boff + n * 2048 + k * 1024); } while (0)
; #define PG8_MMA(ai, bj, At, Bt) do { __builtin_amdgcn_s_setprio(1); _Pragma("unroll") for (int m = 0; m < 4; ++m) _Pragma("unroll") for (int n = 0; n < 2; ++n) _Pragma("unroll") for (int k = 0; k < 2; ++k) \
;         acc[ai][bj][m][n] = __builtin_amdgcn_mfma_f32_16x16x32_bf16(Bt[n][k], At[m][k], acc[ai][bj][m][n], 0, 0, 0); __builtin_amdgcn_s_setprio(0); } while (0)
; #define PG8_WAIT_V(n) asm volatile("s_waitcnt vmcnt(" #n ")" ::: "memory")
; #define PG8_WAIT_L(n) asm volatile("s_waitcnt lgkmcnt(" #n ")" ::: "memory")
; #define PG8_BAR __builtin_amdgcn_s_barrier()
; #define PG8_SCHED __builtin_amdgcn_sched_barrier(0)
; template <class Epi, class Sched, bool ALIGN_EPI = false, bool SP2 = false>
; __device__ __forceinline__ void gemm_phase(PG8_LAS unsigned char* lds, const Gemm g, const Sched& S, const Epi& E, int tid_in) {
;     ...
;             PG8_LDA(At, 0, 1); PG8_STAGE(PG8_SB(0, 0), b2, voffB); PG8_STAGE(PG8_SB(0, 1), b2 + hstepB, voffB); PG8_STAGE(PG8_SA(0, 0), a2, voffA);
;             PG8_WAIT_V(8); PG8_WAIT_L(0); PG8_BAR; PG8_MMA(1, 0, At, B0); PG8_MMA(1, 1, At, B1); PG8_BAR; PG8_SCHED;
;             PG8_LDB(B0, 1, 0); PG8_LDB(B1, 1, 1); PG8_SCHED; PG8_LDA(At, 1, 0); PG8_STAGE(PG8_SA(0, 1), a2 + hstepA, voffA);
;             PG8_WAIT_V(8); PG8_WAIT_L(0); PG8_BAR; PG8_MMA(0, 0, At, B0); PG8_MMA(0, 1, At, B1); PG8_BAR; PG8_SCHED;
	v_mfma_f32_16x16x32_bf16 v[62:65], v[130:133], v[162:165], 0
	v_mfma_f32_16x16x32_bf16 v[58:61], v[138:141], v[162:165], 0
	v_mfma_f32_16x16x32_bf16 v[42:45], v[138:141], v[170:173], 0
	v_mfma_f32_16x16x32_bf16 v[46:49], v[130:133], v[170:173], 0
	v_mfma_f32_16x16x32_bf16 v[30:33], v[130:133], v[178:181], 0
	v_mfma_f32_16x16x32_bf16 v[26:29], v[138:141], v[178:181], 0
	v_mfma_f32_16x16x32_bf16 v[10:13], v[138:141], v[186:189], 0
	v_mfma_f32_16x16x32_bf16 v[14:17], v[130:133], v[186:189], 0
	v_mfma_f32_16x16x32_bf16 v[62:65], v[134:137], v[166:169], v[62:65]
	v_mfma_f32_16x16x32_bf16 v[58:61], v[142:145], v[166:169], v[58:61]
	v_mfma_f32_16x16x32_bf16 v[42:45], v[142:145], v[174:177], v[42:45]
	v_mfma_f32_16x16x32_bf16 v[46:49], v[134:137], v[174:177], v[46:49]
	v_mfma_f32_16x16x32_bf16 v[30:33], v[134:137], v[182:185], v[30:33]
	v_mfma_f32_16x16x32_bf16 v[26:29], v[142:145], v[182:185], v[26:29]
	v_mfma_f32_16x16x32_bf16 v[10:13], v[142:145], v[190:193], v[10:13]
	v_mfma_f32_16x16x32_bf16 v[14:17], v[134:137], v[190:193], v[14:17]
	v_mfma_f32_16x16x32_bf16 v[54:57], v[146:149], v[162:165], 0
	v_mfma_f32_16x16x32_bf16 v[50:53], v[154:157], v[162:165], 0
	v_mfma_f32_16x16x32_bf16 v[34:37], v[154:157], v[170:173], 0
	v_mfma_f32_16x16x32_bf16 v[38:41], v[146:149], v[170:173], 0
	v_mfma_f32_16x16x32_bf16 v[22:25], v[146:149], v[178:181], 0
	v_mfma_f32_16x16x32_bf16 v[18:21], v[154:157], v[178:181], 0
	v_mfma_f32_16x16x32_bf16 v[2:5], v[154:157], v[186:189], 0
	v_mfma_f32_16x16x32_bf16 v[6:9], v[146:149], v[186:189], 0
	v_add_u32_e32 v0, 0x18000, v237
	v_mfma_f32_16x16x32_bf16 v[54:57], v[150:153], v[166:169], v[54:57]
	v_mfma_f32_16x16x32_bf16 v[50:53], v[158:161], v[166:169], v[50:53]
	v_mfma_f32_16x16x32_bf16 v[34:37], v[158:161], v[174:177], v[34:37]
	v_mfma_f32_16x16x32_bf16 v[38:41], v[150:153], v[174:177], v[38:41]
	v_mfma_f32_16x16x32_bf16 v[22:25], v[150:153], v[182:185], v[22:25]
	v_mfma_f32_16x16x32_bf16 v[18:21], v[158:161], v[182:185], v[18:21]
	v_mfma_f32_16x16x32_bf16 v[2:5], v[158:161], v[190:193], v[2:5]
	v_mfma_f32_16x16x32_bf16 v[6:9], v[150:153], v[190:193], v[6:9]
	s_barrier
	s_setprio 0
	ds_read_b128 v[130:133], v0
	ds_read_b128 v[134:137], v0 offset:1024
	ds_read_b128 v[138:141], v0 offset:2048
	ds_read_b128 v[142:145], v0 offset:3072
	v_add_u32_e32 v0, 0x1c000, v237
	ds_read_b128 v[146:149], v0
	ds_read_b128 v[150:153], v0 offset:1024
	ds_read_b128 v[154:157], v0 offset:2048
	ds_read_b128 v[158:161], v0 offset:3072
	s_add_i32 s36, s13, 0x80000
	s_mov_b32 m0, s73
	ds_read_b128 v[162:165], v238 offset:32768
	ds_read_b128 v[166:169], v238 offset:33792
	ds_read_b128 v[170:173], v238 offset:34816
	ds_read_b128 v[174:177], v238 offset:35840
	ds_read_b128 v[178:181], v238 offset:36864
	ds_read_b128 v[182:185], v238 offset:37888
	ds_read_b128 v[186:189], v238 offset:38912
	ds_read_b128 v[190:193], v238 offset:39936
	s_mov_b32 m0, s72
	s_nop 0
	buffer_load_dwordx4 v211, s[4:7], s13 offen lds
	s_mov_b32 m0, s73
	s_nop 0
	buffer_load_dwordx4 v195, s[4:7], s36 offen lds
	s_mov_b32 m0, s74
	s_nop 0
	buffer_load_dwordx4 v211, s[4:7], s36 offen lds
	s_waitcnt vmcnt(8) lgkmcnt(0)
	s_setprio 1
	s_barrier
	v_mfma_f32_16x16x32_bf16 v[126:129], v[130:133], v[162:165], v[126:129]
	v_mfma_f32_16x16x32_bf16 v[122:125], v[138:141], v[162:165], v[122:125]
	v_mfma_f32_16x16x32_bf16 v[106:109], v[138:141], v[170:173], v[106:109]
	v_mfma_f32_16x16x32_bf16 v[110:113], v[130:133], v[170:173], v[110:113]
	v_mfma_f32_16x16x32_bf16 v[94:97], v[130:133], v[178:181], v[94:97]
	v_mfma_f32_16x16x32_bf16 v[90:93], v[138:141], v[178:181], v[90:93]
	v_mfma_f32_16x16x32_bf16 v[74:77], v[138:141], v[186:189], v[74:77]
	v_mfma_f32_16x16x32_bf16 v[78:81], v[130:133], v[186:189], v[78:81]
	s_mov_b32 m0, s75
	v_mfma_f32_16x16x32_bf16 v[70:73], v[146:149], v[186:189], v[70:73]
	s_add_i32 s36, s12, 0x80
	v_mfma_f32_16x16x32_bf16 v[66:69], v[154:157], v[186:189], v[66:69]
	v_mfma_f32_16x16x32_bf16 v[82:85], v[154:157], v[178:181], v[82:85]
	v_mfma_f32_16x16x32_bf16 v[86:89], v[146:149], v[178:181], v[86:89]
	v_mfma_f32_16x16x32_bf16 v[102:105], v[146:149], v[170:173], v[102:105]
	v_mfma_f32_16x16x32_bf16 v[98:101], v[154:157], v[170:173], v[98:101]
	v_mfma_f32_16x16x32_bf16 v[114:117], v[154:157], v[162:165], v[114:117]
	v_mfma_f32_16x16x32_bf16 v[118:121], v[146:149], v[162:165], v[118:121]
	v_mfma_f32_16x16x32_bf16 v[126:129], v[134:137], v[166:169], v[126:129]
	v_mfma_f32_16x16x32_bf16 v[122:125], v[142:145], v[166:169], v[122:125]
	v_mfma_f32_16x16x32_bf16 v[106:109], v[142:145], v[174:177], v[106:109]
	v_mfma_f32_16x16x32_bf16 v[110:113], v[134:137], v[174:177], v[110:113]
	v_mfma_f32_16x16x32_bf16 v[94:97], v[134:137], v[182:185], v[94:97]
	v_mfma_f32_16x16x32_bf16 v[90:93], v[142:145], v[182:185], v[90:93]
	v_mfma_f32_16x16x32_bf16 v[74:77], v[142:145], v[190:193], v[74:77]
	v_mfma_f32_16x16x32_bf16 v[78:81], v[134:137], v[190:193], v[78:81]
	v_mfma_f32_16x16x32_bf16 v[70:73], v[150:153], v[190:193], v[70:73]
	v_mfma_f32_16x16x32_bf16 v[66:69], v[158:161], v[190:193], v[66:69]
	v_mfma_f32_16x16x32_bf16 v[82:85], v[158:161], v[182:185], v[82:85]
	v_mfma_f32_16x16x32_bf16 v[86:89], v[150:153], v[182:185], v[86:89]
	v_mfma_f32_16x16x32_bf16 v[102:105], v[150:153], v[174:177], v[102:105]
	v_mfma_f32_16x16x32_bf16 v[98:101], v[158:161], v[174:177], v[98:101]
	v_mfma_f32_16x16x32_bf16 v[114:117], v[158:161], v[166:169], v[114:117]
	v_mfma_f32_16x16x32_bf16 v[118:121], v[150:153], v[166:169], v[118:121]
	s_barrier
; #define PG8_STAGE(bufoff, gbase, voff) do { const int so_ = (int)(unsigned)((const char*)(gbase) - base_##voff); _Pragma("unroll") for (int _i = 0; _i < 2; ++_i) \
;         __builtin_amdgcn_raw_ptr_buffer_load_lds(rs_##voff, (PG8_LAS unsigned*)(lds + (bufoff) + ldsw + _i * 8192), 16, (int)(voff)[_i], so_, 0, 0); } while (0)
; #define PG8_LDA(dst, b, h) do { _Pragma("unroll") for (int m = 0; m < 4; ++m) _Pragma("unroll") for (int k = 0; k < 2; ++k) dst[m][k] = *(const PG8_LAS bf16x8*)(lds + PG8_SA(b, h) + aoff + m * 2048 + k * 1024); } while (0)
; #define PG8_LDB(dst, b, h) do { _Pragma("unroll") for (int n = 0; n < 2; ++n) _Pragma("unroll") for (int k = 0; k < 2; ++k) dst[n][k] = *(const PG8_LAS bf16x8*)(lds + PG8_SB(b, h) + boff + n * 2048 + k * 1024); } while (0)
; #define PG8_MMA(ai, bj, At, Bt) do { __builtin_amdgcn_s_setprio(1); _Pragma("unroll") for (int m = 0; m < 4; ++m) _Pragma("unroll") for (int n = 0; n < 2; ++n) _Pragma("unroll") for (int k = 0; k < 2; ++k) \
;         acc[ai][bj][m][n] = __builtin_amdgcn_mfma_f32_16x16x32_bf16(Bt[n][k], At[m][k], acc[ai][bj][m][n], 0, 0, 0); __builtin_amdgcn_s_setprio(0); } while (0)
; #define PG8_WAIT_V(n) asm volatile("s_waitcnt vmcnt(" #n ")" ::: "memory")
; #define PG8_WAIT_L(n) asm volatile("s_waitcnt lgkmcnt(" #n ")" ::: "memory")
; #define PG8_BAR __builtin_amdgcn_s_barrier()
; #define PG8_SCHED __builtin_amdgcn_sched_barrier(0)
; template <class Epi, class Sched, bool ALIGN_EPI = false, bool SP2 = false>
; __device__ __forceinline__ void gemm_phase(PG8_LAS unsigned char* lds, const Gemm g, const Sched& S, const Epi& E, int tid_in) {
;     ...
;             PG8_LDB(B0, 0, 0); PG8_LDB(B1, 0, 1); PG8_SCHED; PG8_LDA(At, 0, 0); PG8_STAGE(PG8_SA(1, 1), a1 + hstepA, voffA);
;             PG8_WAIT_V(8); PG8_WAIT_L(0); PG8_BAR; PG8_MMA(0, 0, At, B0); PG8_MMA(0, 1, At, B1); PG8_BAR; PG8_SCHED;
;     ...
;             PG8_LDB(B0, 1, 0); PG8_LDB(B1, 1, 1); PG8_SCHED; PG8_LDA(At, 1, 0); PG8_STAGE(PG8_SA(0, 1), a2 + hstepA, voffA);
;             PG8_WAIT_V(8); PG8_WAIT_L(0); PG8_BAR; PG8_MMA(0, 0, At, B0); PG8_MMA(0, 1, At, B1); PG8_BAR; PG8_SCHED;
;             PG8_LDA(At, 1, 1); PG8_STAGE(PG8_SB(1, 0), b3, voffB); PG8_STAGE(PG8_SB(1, 1), b3 + hstepB, voffB); PG8_STAGE(PG8_SA(1, 0), a3, voffA);
;             PG8_WAIT_V(8); PG8_WAIT_L(0); PG8_BAR; PG8_MMA(1, 0, At, B0); PG8_MMA(1, 1, At, B1); PG8_BAR; PG8_SCHED;
	s_setprio 0
	ds_read_b128 v[162:165], v238 offset:49152
	ds_read_b128 v[166:169], v238 offset:50176
	ds_read_b128 v[170:173], v238 offset:51200
	ds_read_b128 v[174:177], v238 offset:52224
	ds_read_b128 v[178:181], v238 offset:53248
	ds_read_b128 v[182:185], v238 offset:54272
	ds_read_b128 v[186:189], v238 offset:55296
	ds_read_b128 v[190:193], v238 offset:56320
	buffer_load_dwordx4 v207, s[40:43], s36 offen lds
	s_mov_b32 m0, s76
	s_add_i32 s12, s12, 0x80080
	buffer_load_dwordx4 v224, s[40:43], s36 offen lds
	s_mov_b32 m0, s79
	s_addk_i32 s13, 0x80
	buffer_load_dwordx4 v207, s[40:43], s12 offen lds
	s_mov_b32 m0, s68
	s_nop 0
	buffer_load_dwordx4 v224, s[40:43], s12 offen lds
	s_mov_b32 m0, s77
	s_nop 0
	buffer_load_dwordx4 v195, s[4:7], s13 offen lds
	s_waitcnt vmcnt(7) lgkmcnt(0)
	s_setprio 1
	s_barrier
	v_mfma_f32_16x16x32_bf16 v[62:65], v[130:133], v[162:165], v[62:65]
	v_mfma_f32_16x16x32_bf16 v[58:61], v[138:141], v[162:165], v[58:61]
	v_mfma_f32_16x16x32_bf16 v[42:45], v[138:141], v[170:173], v[42:45]
	v_mfma_f32_16x16x32_bf16 v[46:49], v[130:133], v[170:173], v[46:49]
	v_mfma_f32_16x16x32_bf16 v[30:33], v[130:133], v[178:181], v[30:33]
	v_mfma_f32_16x16x32_bf16 v[26:29], v[138:141], v[178:181], v[26:29]
	v_mfma_f32_16x16x32_bf16 v[10:13], v[138:141], v[186:189], v[10:13]
	v_mfma_f32_16x16x32_bf16 v[14:17], v[130:133], v[186:189], v[14:17]
	s_add_i32 s23, s23, 2
	v_mfma_f32_16x16x32_bf16 v[6:9], v[146:149], v[186:189], v[6:9]
	s_add_u32 s20, s20, 0x100
	v_mfma_f32_16x16x32_bf16 v[2:5], v[154:157], v[186:189], v[2:5]
	s_addc_u32 s21, s21, 0
	v_mfma_f32_16x16x32_bf16 v[18:21], v[154:157], v[178:181], v[18:21]
	s_cmp_gt_u32 s23, 29
	v_mfma_f32_16x16x32_bf16 v[22:25], v[146:149], v[178:181], v[22:25]
	s_mov_b64 s[12:13], s[16:17]
	v_mfma_f32_16x16x32_bf16 v[38:41], v[146:149], v[170:173], v[38:41]
	v_mfma_f32_16x16x32_bf16 v[34:37], v[154:157], v[170:173], v[34:37]
	v_mfma_f32_16x16x32_bf16 v[50:53], v[154:157], v[162:165], v[50:53]
	v_mfma_f32_16x16x32_bf16 v[54:57], v[146:149], v[162:165], v[54:57]
	v_mfma_f32_16x16x32_bf16 v[62:65], v[134:137], v[166:169], v[62:65]
	v_mfma_f32_16x16x32_bf16 v[58:61], v[142:145], v[166:169], v[58:61]
	v_mfma_f32_16x16x32_bf16 v[42:45], v[142:145], v[174:177], v[42:45]
	v_mfma_f32_16x16x32_bf16 v[46:49], v[134:137], v[174:177], v[46:49]
	v_mfma_f32_16x16x32_bf16 v[30:33], v[134:137], v[182:185], v[30:33]
	v_mfma_f32_16x16x32_bf16 v[26:29], v[142:145], v[182:185], v[26:29]
	v_mfma_f32_16x16x32_bf16 v[10:13], v[142:145], v[190:193], v[10:13]
	v_mfma_f32_16x16x32_bf16 v[14:17], v[134:137], v[190:193], v[14:17]
	v_mfma_f32_16x16x32_bf16 v[6:9], v[150:153], v[190:193], v[6:9]
	v_mfma_f32_16x16x32_bf16 v[2:5], v[158:161], v[190:193], v[2:5]
	v_mfma_f32_16x16x32_bf16 v[18:21], v[158:161], v[182:185], v[18:21]
	v_mfma_f32_16x16x32_bf16 v[22:25], v[150:153], v[182:185], v[22:25]
	v_mfma_f32_16x16x32_bf16 v[38:41], v[150:153], v[174:177], v[38:41]
	v_mfma_f32_16x16x32_bf16 v[34:37], v[158:161], v[174:177], v[34:37]
	v_mfma_f32_16x16x32_bf16 v[50:53], v[158:161], v[166:169], v[50:53]
	v_mfma_f32_16x16x32_bf16 v[54:57], v[150:153], v[166:169], v[54:57]
	s_barrier
	s_setprio 0
.LBB0_312:
	v_add_u32_e32 v0, 0x10000, v237
	ds_read_b128 v[130:133], v0
	ds_read_b128 v[134:137], v0 offset:1024
	ds_read_b128 v[138:141], v0 offset:2048
	ds_read_b128 v[142:145], v0 offset:3072
	v_add_u32_e32 v0, 0x14000, v237
	ds_read_b128 v[146:149], v0
	ds_read_b128 v[150:153], v0 offset:1024
	ds_read_b128 v[154:157], v0 offset:2048
	ds_read_b128 v[158:161], v0 offset:3072
	s_add_u32 s16, s12, 0x100
	s_addc_u32 s17, s13, 0
	s_sub_i32 s12, s12, s4
	s_add_i32 s12, s12, 0x80080
	s_sub_i32 s36, s12, 0x80000
	s_cmp_eq_u32 s23, 28
	s_cselect_b32 s13, s19, s16
	s_mov_b32 m0, s69
	ds_read_b128 v[162:165], v238
	ds_read_b128 v[166:169], v238 offset:1024
	ds_read_b128 v[170:173], v238 offset:2048
	ds_read_b128 v[174:177], v238 offset:3072
	ds_read_b128 v[178:181], v238 offset:4096
	ds_read_b128 v[182:185], v238 offset:5120
	ds_read_b128 v[186:189], v238 offset:6144
	ds_read_b128 v[190:193], v238 offset:7168
	s_mov_b32 m0, s78
	s_nop 0
	buffer_load_dwordx4 v211, s[4:7], s36 offen lds
	s_mov_b32 m0, s69
	s_nop 0
	buffer_load_dwordx4 v195, s[4:7], s12 offen lds
	s_mov_b32 m0, s67
	s_nop 0
	buffer_load_dwordx4 v211, s[4:7], s12 offen lds
	s_waitcnt vmcnt(8) lgkmcnt(0)
	s_setprio 1
	s_barrier
	v_mfma_f32_16x16x32_bf16 v[126:129], v[130:133], v[162:165], v[126:129]
	v_mfma_f32_16x16x32_bf16 v[122:125], v[138:141], v[162:165], v[122:125]
	v_mfma_f32_16x16x32_bf16 v[106:109], v[138:141], v[170:173], v[106:109]
	v_mfma_f32_16x16x32_bf16 v[110:113], v[130:133], v[170:173], v[110:113]
	v_mfma_f32_16x16x32_bf16 v[94:97], v[130:133], v[178:181], v[94:97]
	v_mfma_f32_16x16x32_bf16 v[90:93], v[138:141], v[178:181], v[90:93]
	v_mfma_f32_16x16x32_bf16 v[74:77], v[138:141], v[186:189], v[74:77]
	v_mfma_f32_16x16x32_bf16 v[78:81], v[130:133], v[186:189], v[78:81]
	s_cselect_b32 s12, s15, s20
	v_mfma_f32_16x16x32_bf16 v[70:73], v[146:149], v[186:189], v[70:73]
	s_mov_b32 m0, s61
	v_mfma_f32_16x16x32_bf16 v[66:69], v[154:157], v[186:189], v[66:69]
	s_mov_b32 s42, s6
	v_mfma_f32_16x16x32_bf16 v[82:85], v[154:157], v[178:181], v[82:85]
	s_mov_b32 s43, s7
	v_mfma_f32_16x16x32_bf16 v[86:89], v[146:149], v[178:181], v[86:89]
	s_sub_i32 s12, s12, s40
	v_mfma_f32_16x16x32_bf16 v[102:105], v[146:149], v[170:173], v[102:105]
	v_mfma_f32_16x16x32_bf16 v[98:101], v[154:157], v[170:173], v[98:101]
	v_mfma_f32_16x16x32_bf16 v[114:117], v[154:157], v[162:165], v[114:117]
	v_mfma_f32_16x16x32_bf16 v[118:121], v[146:149], v[162:165], v[118:121]
	v_mfma_f32_16x16x32_bf16 v[126:129], v[134:137], v[166:169], v[126:129]
	v_mfma_f32_16x16x32_bf16 v[122:125], v[142:145], v[166:169], v[122:125]
	v_mfma_f32_16x16x32_bf16 v[106:109], v[142:145], v[174:177], v[106:109]
	v_mfma_f32_16x16x32_bf16 v[110:113], v[134:137], v[174:177], v[110:113]
	v_mfma_f32_16x16x32_bf16 v[94:97], v[134:137], v[182:185], v[94:97]
	v_mfma_f32_16x16x32_bf16 v[90:93], v[142:145], v[182:185], v[90:93]
	v_mfma_f32_16x16x32_bf16 v[74:77], v[142:145], v[190:193], v[74:77]
	v_mfma_f32_16x16x32_bf16 v[78:81], v[134:137], v[190:193], v[78:81]
	v_mfma_f32_16x16x32_bf16 v[70:73], v[150:153], v[190:193], v[70:73]
	v_mfma_f32_16x16x32_bf16 v[66:69], v[158:161], v[190:193], v[66:69]
	v_mfma_f32_16x16x32_bf16 v[82:85], v[158:161], v[182:185], v[82:85]
	v_mfma_f32_16x16x32_bf16 v[86:89], v[150:153], v[182:185], v[86:89]
	v_mfma_f32_16x16x32_bf16 v[102:105], v[150:153], v[174:177], v[102:105]
	v_mfma_f32_16x16x32_bf16 v[98:101], v[158:161], v[174:177], v[98:101]
	v_mfma_f32_16x16x32_bf16 v[114:117], v[158:161], v[166:169], v[114:117]
	v_mfma_f32_16x16x32_bf16 v[118:121], v[150:153], v[166:169], v[118:121]
	s_barrier
; #define PG8_STAGE(bufoff, gbase, voff) do { const int so_ = (int)(unsigned)((const char*)(gbase) - base_##voff); _Pragma("unroll") for (int _i = 0; _i < 2; ++_i) \
;         __builtin_amdgcn_raw_ptr_buffer_load_lds(rs_##voff, (PG8_LAS unsigned*)(lds + (bufoff) + ldsw + _i * 8192), 16, (int)(voff)[_i], so_, 0, 0); } while (0)
; #define PG8_LDA(dst, b, h) do { _Pragma("unroll") for (int m = 0; m < 4; ++m) _Pragma("unroll") for (int k = 0; k < 2; ++k) dst[m][k] = *(const PG8_LAS bf16x8*)(lds + PG8_SA(b, h) + aoff + m * 2048 + k * 1024); } while (0)
; #define PG8_LDB(dst, b, h) do { _Pragma("unroll") for (int n = 0; n < 2; ++n) _Pragma("unroll") for (int k = 0; k < 2; ++k) dst[n][k] = *(const PG8_LAS bf16x8*)(lds + PG8_SB(b, h) + boff + n * 2048 + k * 1024); } while (0)
; #define PG8_MMA(ai, bj, At, Bt) do { __builtin_amdgcn_s_setprio(1); _Pragma("unroll") for (int m = 0; m < 4; ++m) _Pragma("unroll") for (int n = 0; n < 2; ++n) _Pragma("unroll") for (int k = 0; k < 2; ++k) \
;         acc[ai][bj][m][n] = __builtin_amdgcn_mfma_f32_16x16x32_bf16(Bt[n][k], At[m][k], acc[ai][bj][m][n], 0, 0, 0); __builtin_amdgcn_s_setprio(0); } while (0)
; #define PG8_WAIT_V(n) asm volatile("s_waitcnt vmcnt(" #n ")" ::: "memory")
; #define PG8_WAIT_L(n) asm volatile("s_waitcnt lgkmcnt(" #n ")" ::: "memory")
; #define PG8_BAR __builtin_amdgcn_s_barrier()
; #define PG8_SCHED __builtin_amdgcn_sched_barrier(0)
; template <class Epi, class Sched, bool ALIGN_EPI = false, bool SP2 = false>
; __device__ __forceinline__ void gemm_phase(PG8_LAS unsigned char* lds, const Gemm g, const Sched& S, const Epi& E, int tid_in) {
;     ...
;             PG8_LDA(At, 0, 1); PG8_STAGE(PG8_SB(0, 0), b2, voffB); PG8_STAGE(PG8_SB(0, 1), b2 + hstepB, voffB); PG8_STAGE(PG8_SA(0, 0), a2, voffA);
;             PG8_WAIT_V(8); PG8_WAIT_L(0); PG8_BAR; PG8_MMA(1, 0, At, B0); PG8_MMA(1, 1, At, B1); PG8_BAR; PG8_SCHED;
;             PG8_LDB(B0, 1, 0); PG8_LDB(B1, 1, 1); PG8_SCHED; PG8_LDA(At, 1, 0); PG8_STAGE(PG8_SA(0, 1), a2 + hstepA, voffA);
;             PG8_WAIT_V(8); PG8_WAIT_L(0); PG8_BAR; PG8_MMA(0, 0, At, B0); PG8_MMA(0, 1, At, B1); PG8_BAR; PG8_SCHED;
	s_setprio 0
	ds_read_b128 v[162:165], v238 offset:16384
	ds_read_b128 v[166:169], v238 offset:17408
	ds_read_b128 v[170:173], v238 offset:18432
	ds_read_b128 v[174:177], v238 offset:19456
	ds_read_b128 v[178:181], v238 offset:20480
	ds_read_b128 v[182:185], v238 offset:21504
	ds_read_b128 v[186:189], v238 offset:22528
	ds_read_b128 v[190:193], v238 offset:23552
	buffer_load_dwordx4 v207, s[40:43], s12 offen lds
	s_mov_b32 m0, s62
	s_add_i32 s36, s12, 0x80000
	buffer_load_dwordx4 v224, s[40:43], s12 offen lds
	s_mov_b32 m0, s63
	s_sub_i32 s13, s13, s4
	buffer_load_dwordx4 v207, s[40:43], s36 offen lds
	s_mov_b32 m0, s71
	s_nop 0
	buffer_load_dwordx4 v224, s[40:43], s36 offen lds
	s_mov_b32 m0, s53
	s_nop 0
	buffer_load_dwordx4 v195, s[4:7], s13 offen lds
	s_waitcnt vmcnt(7) lgkmcnt(0)
	s_setprio 1
	s_barrier
	v_mfma_f32_16x16x32_bf16 v[62:65], v[130:133], v[162:165], v[62:65]
	v_mfma_f32_16x16x32_bf16 v[58:61], v[138:141], v[162:165], v[58:61]
	v_mfma_f32_16x16x32_bf16 v[42:45], v[138:141], v[170:173], v[42:45]
	v_mfma_f32_16x16x32_bf16 v[46:49], v[130:133], v[170:173], v[46:49]
	v_mfma_f32_16x16x32_bf16 v[30:33], v[130:133], v[178:181], v[30:33]
	v_mfma_f32_16x16x32_bf16 v[26:29], v[138:141], v[178:181], v[26:29]
	v_mfma_f32_16x16x32_bf16 v[10:13], v[138:141], v[186:189], v[10:13]
	v_mfma_f32_16x16x32_bf16 v[14:17], v[130:133], v[186:189], v[14:17]
	v_mfma_f32_16x16x32_bf16 v[6:9], v[146:149], v[186:189], v[6:9]
	v_mfma_f32_16x16x32_bf16 v[2:5], v[154:157], v[186:189], v[2:5]
	v_mfma_f32_16x16x32_bf16 v[18:21], v[154:157], v[178:181], v[18:21]
	v_mfma_f32_16x16x32_bf16 v[22:25], v[146:149], v[178:181], v[22:25]
	v_mfma_f32_16x16x32_bf16 v[38:41], v[146:149], v[170:173], v[38:41]
	v_mfma_f32_16x16x32_bf16 v[34:37], v[154:157], v[170:173], v[34:37]
	v_mfma_f32_16x16x32_bf16 v[50:53], v[154:157], v[162:165], v[50:53]
	v_mfma_f32_16x16x32_bf16 v[54:57], v[146:149], v[162:165], v[54:57]
	v_mfma_f32_16x16x32_bf16 v[62:65], v[134:137], v[166:169], v[62:65]
	v_mfma_f32_16x16x32_bf16 v[58:61], v[142:145], v[166:169], v[58:61]
	v_mfma_f32_16x16x32_bf16 v[42:45], v[142:145], v[174:177], v[42:45]
	v_mfma_f32_16x16x32_bf16 v[46:49], v[134:137], v[174:177], v[46:49]
	v_mfma_f32_16x16x32_bf16 v[30:33], v[134:137], v[182:185], v[30:33]
	v_mfma_f32_16x16x32_bf16 v[26:29], v[142:145], v[182:185], v[26:29]
	v_mfma_f32_16x16x32_bf16 v[10:13], v[142:145], v[190:193], v[10:13]
	v_mfma_f32_16x16x32_bf16 v[14:17], v[134:137], v[190:193], v[14:17]
	v_add_u32_e32 v0, 0x18000, v237
	v_mfma_f32_16x16x32_bf16 v[6:9], v[150:153], v[190:193], v[6:9]
	v_mfma_f32_16x16x32_bf16 v[2:5], v[158:161], v[190:193], v[2:5]
	v_mfma_f32_16x16x32_bf16 v[18:21], v[158:161], v[182:185], v[18:21]
	v_mfma_f32_16x16x32_bf16 v[22:25], v[150:153], v[182:185], v[22:25]
	v_mfma_f32_16x16x32_bf16 v[38:41], v[150:153], v[174:177], v[38:41]
	v_mfma_f32_16x16x32_bf16 v[34:37], v[158:161], v[174:177], v[34:37]
	v_mfma_f32_16x16x32_bf16 v[50:53], v[158:161], v[166:169], v[50:53]
	v_mfma_f32_16x16x32_bf16 v[54:57], v[150:153], v[166:169], v[54:57]
	s_barrier
	s_setprio 0
	ds_read_b128 v[130:133], v0
	ds_read_b128 v[134:137], v0 offset:1024
	ds_read_b128 v[138:141], v0 offset:2048
	ds_read_b128 v[142:145], v0 offset:3072
	v_add_u32_e32 v0, 0x1c000, v237
	ds_read_b128 v[146:149], v0
	ds_read_b128 v[150:153], v0 offset:1024
	ds_read_b128 v[154:157], v0 offset:2048
	ds_read_b128 v[158:161], v0 offset:3072
	s_add_i32 s36, s13, 0x80000
	s_mov_b32 m0, s73
	ds_read_b128 v[162:165], v238 offset:32768
	ds_read_b128 v[166:169], v238 offset:33792
	ds_read_b128 v[170:173], v238 offset:34816
	ds_read_b128 v[174:177], v238 offset:35840
	ds_read_b128 v[178:181], v238 offset:36864
	ds_read_b128 v[182:185], v238 offset:37888
	ds_read_b128 v[186:189], v238 offset:38912
	ds_read_b128 v[190:193], v238 offset:39936
	s_mov_b32 m0, s72
	s_nop 0
	buffer_load_dwordx4 v211, s[4:7], s13 offen lds
	s_mov_b32 m0, s73
	s_nop 0
	buffer_load_dwordx4 v195, s[4:7], s36 offen lds
	s_mov_b32 m0, s74
	s_nop 0
	buffer_load_dwordx4 v211, s[4:7], s36 offen lds
	s_waitcnt vmcnt(8) lgkmcnt(0)
	s_setprio 1
	s_barrier
; #define PG8_STAGE(bufoff, gbase, voff) do { const int so_ = (int)(unsigned)((const char*)(gbase) - base_##voff); _Pragma("unroll") for (int _i = 0; _i < 2; ++_i) \
;         __builtin_amdgcn_raw_ptr_buffer_load_lds(rs_##voff, (PG8_LAS unsigned*)(lds + (bufoff) + ldsw + _i * 8192), 16, (int)(voff)[_i], so_, 0, 0); } while (0)
; #define PG8_LDA(dst, b, h) do { _Pragma("unroll") for (int m = 0; m < 4; ++m) _Pragma("unroll") for (int k = 0; k < 2; ++k) dst[m][k] = *(const PG8_LAS bf16x8*)(lds + PG8_SA(b, h) + aoff + m * 2048 + k * 1024); } while (0)
; #define PG8_LDB(dst, b, h) do { _Pragma("unroll") for (int n = 0; n < 2; ++n) _Pragma("unroll") for (int k = 0; k < 2; ++k) dst[n][k] = *(const PG8_LAS bf16x8*)(lds + PG8_SB(b, h) + boff + n * 2048 + k * 1024); } while (0)
; #define PG8_MMA(ai, bj, At, Bt) do { __builtin_amdgcn_s_setprio(1); _Pragma("unroll") for (int m = 0; m < 4; ++m) _Pragma("unroll") for (int n = 0; n < 2; ++n) _Pragma("unroll") for (int k = 0; k < 2; ++k) \
;         acc[ai][bj][m][n] = __builtin_amdgcn_mfma_f32_16x16x32_bf16(Bt[n][k], At[m][k], acc[ai][bj][m][n], 0, 0, 0); __builtin_amdgcn_s_setprio(0); } while (0)
; #define PG8_WAIT_V(n) asm volatile("s_waitcnt vmcnt(" #n ")" ::: "memory")
; #define PG8_WAIT_L(n) asm volatile("s_waitcnt lgkmcnt(" #n ")" ::: "memory")
; #define PG8_BAR __builtin_amdgcn_s_barrier()
; #define PG8_SCHED __builtin_amdgcn_sched_barrier(0)
; template <class Epi, class Sched, bool ALIGN_EPI = false, bool SP2 = false>
; __device__ __forceinline__ void gemm_phase(PG8_LAS unsigned char* lds, const Gemm g, const Sched& S, const Epi& E, int tid_in) {
;     ...
;             PG8_LDB(B0, 1, 0); PG8_LDB(B1, 1, 1); PG8_SCHED; PG8_LDA(At, 1, 0); PG8_STAGE(PG8_SA(0, 1), a2 + hstepA, voffA);
;             PG8_WAIT_V(8); PG8_WAIT_L(0); PG8_BAR; PG8_MMA(0, 0, At, B0); PG8_MMA(0, 1, At, B1); PG8_BAR; PG8_SCHED;
;             PG8_LDA(At, 1, 1); PG8_STAGE(PG8_SB(1, 0), b3, voffB); PG8_STAGE(PG8_SB(1, 1), b3 + hstepB, voffB); PG8_STAGE(PG8_SA(1, 0), a3, voffA);
;             PG8_WAIT_V(8); PG8_WAIT_L(0); PG8_BAR; PG8_MMA(1, 0, At, B0); PG8_MMA(1, 1, At, B1); PG8_BAR; PG8_SCHED;
	v_mfma_f32_16x16x32_bf16 v[126:129], v[130:133], v[162:165], v[126:129]
	v_mfma_f32_16x16x32_bf16 v[122:125], v[138:141], v[162:165], v[122:125]
	v_mfma_f32_16x16x32_bf16 v[106:109], v[138:141], v[170:173], v[106:109]
	v_mfma_f32_16x16x32_bf16 v[110:113], v[130:133], v[170:173], v[110:113]
	v_mfma_f32_16x16x32_bf16 v[94:97], v[130:133], v[178:181], v[94:97]
	v_mfma_f32_16x16x32_bf16 v[90:93], v[138:141], v[178:181], v[90:93]
	v_mfma_f32_16x16x32_bf16 v[74:77], v[138:141], v[186:189], v[74:77]
	v_mfma_f32_16x16x32_bf16 v[78:81], v[130:133], v[186:189], v[78:81]
	s_mov_b32 m0, s75
	v_mfma_f32_16x16x32_bf16 v[70:73], v[146:149], v[186:189], v[70:73]
	s_add_i32 s36, s12, 0x80
	v_mfma_f32_16x16x32_bf16 v[66:69], v[154:157], v[186:189], v[66:69]
	v_mfma_f32_16x16x32_bf16 v[82:85], v[154:157], v[178:181], v[82:85]
	v_mfma_f32_16x16x32_bf16 v[86:89], v[146:149], v[178:181], v[86:89]
	v_mfma_f32_16x16x32_bf16 v[102:105], v[146:149], v[170:173], v[102:105]
	v_mfma_f32_16x16x32_bf16 v[98:101], v[154:157], v[170:173], v[98:101]
	v_mfma_f32_16x16x32_bf16 v[114:117], v[154:157], v[162:165], v[114:117]
	v_mfma_f32_16x16x32_bf16 v[118:121], v[146:149], v[162:165], v[118:121]
	v_mfma_f32_16x16x32_bf16 v[126:129], v[134:137], v[166:169], v[126:129]
	v_mfma_f32_16x16x32_bf16 v[122:125], v[142:145], v[166:169], v[122:125]
	v_mfma_f32_16x16x32_bf16 v[106:109], v[142:145], v[174:177], v[106:109]
	v_mfma_f32_16x16x32_bf16 v[110:113], v[134:137], v[174:177], v[110:113]
	v_mfma_f32_16x16x32_bf16 v[94:97], v[134:137], v[182:185], v[94:97]
	v_mfma_f32_16x16x32_bf16 v[90:93], v[142:145], v[182:185], v[90:93]
	v_mfma_f32_16x16x32_bf16 v[74:77], v[142:145], v[190:193], v[74:77]
	v_mfma_f32_16x16x32_bf16 v[78:81], v[134:137], v[190:193], v[78:81]
	v_mfma_f32_16x16x32_bf16 v[70:73], v[150:153], v[190:193], v[70:73]
	v_mfma_f32_16x16x32_bf16 v[66:69], v[158:161], v[190:193], v[66:69]
	v_mfma_f32_16x16x32_bf16 v[82:85], v[158:161], v[182:185], v[82:85]
	v_mfma_f32_16x16x32_bf16 v[86:89], v[150:153], v[182:185], v[86:89]
	v_mfma_f32_16x16x32_bf16 v[102:105], v[150:153], v[174:177], v[102:105]
	v_mfma_f32_16x16x32_bf16 v[98:101], v[158:161], v[174:177], v[98:101]
	v_mfma_f32_16x16x32_bf16 v[114:117], v[158:161], v[166:169], v[114:117]
	v_mfma_f32_16x16x32_bf16 v[118:121], v[150:153], v[166:169], v[118:121]
	s_barrier
	s_setprio 0
	ds_read_b128 v[162:165], v238 offset:49152
	ds_read_b128 v[166:169], v238 offset:50176
	ds_read_b128 v[170:173], v238 offset:51200
	ds_read_b128 v[174:177], v238 offset:52224
	ds_read_b128 v[178:181], v238 offset:53248
	ds_read_b128 v[182:185], v238 offset:54272
	ds_read_b128 v[186:189], v238 offset:55296
	ds_read_b128 v[190:193], v238 offset:56320
	buffer_load_dwordx4 v207, s[40:43], s36 offen lds
	s_mov_b32 m0, s76
	s_add_i32 s12, s12, 0x80080
	buffer_load_dwordx4 v224, s[40:43], s36 offen lds
	s_mov_b32 m0, s79
	s_addk_i32 s13, 0x80
	buffer_load_dwordx4 v207, s[40:43], s12 offen lds
	s_mov_b32 m0, s68
	s_nop 0
	buffer_load_dwordx4 v224, s[40:43], s12 offen lds
	s_mov_b32 m0, s77
	s_nop 0
	buffer_load_dwordx4 v195, s[4:7], s13 offen lds
	s_waitcnt vmcnt(7) lgkmcnt(0)
	s_setprio 1
	s_barrier
	v_mfma_f32_16x16x32_bf16 v[62:65], v[130:133], v[162:165], v[62:65]
	v_mfma_f32_16x16x32_bf16 v[58:61], v[138:141], v[162:165], v[58:61]
	v_mfma_f32_16x16x32_bf16 v[42:45], v[138:141], v[170:173], v[42:45]
	v_mfma_f32_16x16x32_bf16 v[46:49], v[130:133], v[170:173], v[46:49]
	v_mfma_f32_16x16x32_bf16 v[30:33], v[130:133], v[178:181], v[30:33]
	v_mfma_f32_16x16x32_bf16 v[26:29], v[138:141], v[178:181], v[26:29]
	v_mfma_f32_16x16x32_bf16 v[10:13], v[138:141], v[186:189], v[10:13]
	v_mfma_f32_16x16x32_bf16 v[14:17], v[130:133], v[186:189], v[14:17]
	s_add_i32 s23, s23, 2
	v_mfma_f32_16x16x32_bf16 v[6:9], v[146:149], v[186:189], v[6:9]
	s_add_u32 s20, s20, 0x100
	v_mfma_f32_16x16x32_bf16 v[2:5], v[154:157], v[186:189], v[2:5]
	s_addc_u32 s21, s21, 0
	v_mfma_f32_16x16x32_bf16 v[18:21], v[154:157], v[178:181], v[18:21]
	s_cmp_gt_u32 s23, 29
	v_mfma_f32_16x16x32_bf16 v[22:25], v[146:149], v[178:181], v[22:25]
	s_mov_b64 s[12:13], s[16:17]
	v_mfma_f32_16x16x32_bf16 v[38:41], v[146:149], v[170:173], v[38:41]
	v_mfma_f32_16x16x32_bf16 v[34:37], v[154:157], v[170:173], v[34:37]
	v_mfma_f32_16x16x32_bf16 v[50:53], v[154:157], v[162:165], v[50:53]
	v_mfma_f32_16x16x32_bf16 v[54:57], v[146:149], v[162:165], v[54:57]
	v_mfma_f32_16x16x32_bf16 v[62:65], v[134:137], v[166:169], v[62:65]
	v_mfma_f32_16x16x32_bf16 v[58:61], v[142:145], v[166:169], v[58:61]
	v_mfma_f32_16x16x32_bf16 v[42:45], v[142:145], v[174:177], v[42:45]
	v_mfma_f32_16x16x32_bf16 v[46:49], v[134:137], v[174:177], v[46:49]
	v_mfma_f32_16x16x32_bf16 v[30:33], v[134:137], v[182:185], v[30:33]
	v_mfma_f32_16x16x32_bf16 v[26:29], v[142:145], v[182:185], v[26:29]
	v_mfma_f32_16x16x32_bf16 v[10:13], v[142:145], v[190:193], v[10:13]
	v_mfma_f32_16x16x32_bf16 v[14:17], v[134:137], v[190:193], v[14:17]
	v_mfma_f32_16x16x32_bf16 v[6:9], v[150:153], v[190:193], v[6:9]
	v_mfma_f32_16x16x32_bf16 v[2:5], v[158:161], v[190:193], v[2:5]
	v_mfma_f32_16x16x32_bf16 v[18:21], v[158:161], v[182:185], v[18:21]
	v_mfma_f32_16x16x32_bf16 v[22:25], v[150:153], v[182:185], v[22:25]
	v_mfma_f32_16x16x32_bf16 v[38:41], v[150:153], v[174:177], v[38:41]
	v_mfma_f32_16x16x32_bf16 v[34:37], v[158:161], v[174:177], v[34:37]
	v_mfma_f32_16x16x32_bf16 v[50:53], v[158:161], v[166:169], v[50:53]
	v_mfma_f32_16x16x32_bf16 v[54:57], v[150:153], v[166:169], v[54:57]
	s_barrier
	s_setprio 0
	s_cbranch_scc0 .LBB0_312
	s_and_b64 vcc, exec, s[48:49]
	s_cbranch_vccz .LBB0_315
	s_barrier

; #define PG8_STAGE(bufoff, gbase, voff) do { const int so_ = (int)(unsigned)((const char*)(gbase) - base_##voff); _Pragma("unroll") for (int _i = 0; _i < 2; ++_i) \
;         __builtin_amdgcn_raw_ptr_buffer_load_lds(rs_##voff, (PG8_LAS unsigned*)(lds + (bufoff) + ldsw + _i * 8192), 16, (int)(voff)[_i], so_, 0, 0); } while (0)
; #define PG8_LDA(dst, b, h) do { _Pragma("unroll") for (int m = 0; m < 4; ++m) _Pragma("unroll") for (int k = 0; k < 2; ++k) dst[m][k] = *(const PG8_LAS bf16x8*)(lds + PG8_SA(b, h) + aoff + m * 2048 + k * 1024); } while (0)
; #define PG8_LDB(dst, b, h) do { _Pragma("unroll") for (int n = 0; n < 2; ++n) _Pragma("unroll") for (int k = 0; k < 2; ++k) dst[n][k] = *(const PG8_LAS bf16x8*)(lds + PG8_SB(b, h) + boff + n * 2048 + k * 1024); } while (0)
; #define PG8_MMA(ai, bj, At, Bt) do { __builtin_amdgcn_s_setprio(1); _Pragma("unroll") for (int m = 0; m < 4; ++m) _Pragma("unroll") for (int n = 0; n < 2; ++n) _Pragma("unroll") for (int k = 0; k < 2; ++k) \
;         acc[ai][bj][m][n] = __builtin_amdgcn_mfma_f32_16x16x32_bf16(Bt[n][k], At[m][k], acc[ai][bj][m][n], 0, 0, 0); __builtin_amdgcn_s_setprio(0); } while (0)
; #define PG8_WAIT_V(n) asm volatile("s_waitcnt vmcnt(" #n ")" ::: "memory")
; #define PG8_WAIT_L(n) asm volatile("s_waitcnt lgkmcnt(" #n ")" ::: "memory")
; #define PG8_BAR __builtin_amdgcn_s_barrier()
; #define PG8_SCHED __builtin_amdgcn_sched_barrier(0)
; template <class Epi, class Sched, bool ALIGN_EPI = false, bool SP2 = false>
; __device__ __forceinline__ void gemm_phase(PG8_LAS unsigned char* lds, const Gemm g, const Sched& S, const Epi& E, int tid_in) {
;     ...
;             PG8_LDB(B0, 0, 0); PG8_LDB(B1, 0, 1); PG8_SCHED; PG8_LDA(At, 0, 0); PG8_STAGE(PG8_SA(1, 1), a1 + hstepA, voffA);
;             PG8_WAIT_V(8); PG8_WAIT_L(0); PG8_BAR; PG8_MMA(0, 0, At, B0); PG8_MMA(0, 1, At, B1); PG8_BAR; PG8_SCHED;
;             PG8_LDA(At, 0, 1); PG8_STAGE(PG8_SB(0, 0), b2, voffB); PG8_STAGE(PG8_SB(0, 1), b2 + hstepB, voffB); PG8_STAGE(PG8_SA(0, 0), a2, voffA);
;             PG8_WAIT_V(8); PG8_WAIT_L(0); PG8_BAR; PG8_MMA(1, 0, At, B0); PG8_MMA(1, 1, At, B1); PG8_BAR; PG8_SCHED;
;             PG8_LDB(B0, 1, 0); PG8_LDB(B1, 1, 1); PG8_SCHED; PG8_LDA(At, 1, 0); PG8_STAGE(PG8_SA(0, 1), a2 + hstepA, voffA);
;             PG8_WAIT_V(8); PG8_WAIT_L(0); PG8_BAR; PG8_MMA(0, 0, At, B0); PG8_MMA(0, 1, At, B1); PG8_BAR; PG8_SCHED;
.LBB0_1037:
	v_add_u32_e32 v0, 0x10000, v236
	ds_read_b128 v[132:135], v0
	ds_read_b128 v[136:139], v0 offset:1024
	ds_read_b128 v[140:143], v0 offset:2048
	ds_read_b128 v[144:147], v0 offset:3072
	v_add_u32_e32 v0, 0x14000, v236
	ds_read_b128 v[148:151], v0
	ds_read_b128 v[152:155], v0 offset:1024
	ds_read_b128 v[156:159], v0 offset:2048
	ds_read_b128 v[160:163], v0 offset:3072
	s_add_u32 s16, s12, 0x100
	s_addc_u32 s17, s13, 0
	s_sub_i32 s12, s12, s4
	s_add_i32 s12, s12, 0xc0080
	s_sub_i32 s39, s12, 0xc0000
	s_cmp_eq_u32 s38, 12
	s_cselect_b32 s13, s24, s16
	s_mov_b32 m0, s76
	ds_read_b128 v[164:167], v237
	ds_read_b128 v[168:171], v237 offset:1024
	ds_read_b128 v[172:175], v237 offset:2048
	ds_read_b128 v[176:179], v237 offset:3072
	ds_read_b128 v[180:183], v237 offset:4096
	ds_read_b128 v[184:187], v237 offset:5120
	ds_read_b128 v[188:191], v237 offset:6144
	ds_read_b128 v[192:195], v237 offset:7168
	s_mov_b32 m0, s73
	s_nop 0
	buffer_load_dwordx4 v222, s[4:7], s39 offen lds
	s_mov_b32 m0, s76
	s_nop 0
	buffer_load_dwordx4 v220, s[4:7], s12 offen lds
	s_mov_b32 m0, s77
	s_nop 0
	buffer_load_dwordx4 v222, s[4:7], s12 offen lds
	s_waitcnt vmcnt(8) lgkmcnt(0)
	s_setprio 1
	s_barrier
	v_mfma_f32_16x16x32_bf16 v[128:131], v[132:135], v[164:167], v[128:131]
	v_mfma_f32_16x16x32_bf16 v[124:127], v[140:143], v[164:167], v[124:127]
	v_mfma_f32_16x16x32_bf16 v[116:119], v[140:143], v[172:175], v[116:119]
	v_mfma_f32_16x16x32_bf16 v[120:123], v[132:135], v[172:175], v[120:123]
	v_mfma_f32_16x16x32_bf16 v[112:115], v[132:135], v[180:183], v[112:115]
	v_mfma_f32_16x16x32_bf16 v[108:111], v[140:143], v[180:183], v[108:111]
	v_mfma_f32_16x16x32_bf16 v[100:103], v[140:143], v[188:191], v[100:103]
	v_mfma_f32_16x16x32_bf16 v[104:107], v[132:135], v[188:191], v[104:107]
	s_cselect_b32 s12, s18, s19
	v_mfma_f32_16x16x32_bf16 v[72:75], v[148:151], v[188:191], v[72:75]
	s_mov_b32 m0, s26
	v_mfma_f32_16x16x32_bf16 v[68:71], v[156:159], v[188:191], v[68:71]
	s_mov_b32 s46, s6
	v_mfma_f32_16x16x32_bf16 v[76:79], v[156:159], v[180:183], v[76:79]
	s_mov_b32 s47, s7
	v_mfma_f32_16x16x32_bf16 v[80:83], v[148:151], v[180:183], v[80:83]
	s_sub_i32 s12, s12, s44
	v_mfma_f32_16x16x32_bf16 v[88:91], v[148:151], v[172:175], v[88:91]
	v_mfma_f32_16x16x32_bf16 v[84:87], v[156:159], v[172:175], v[84:87]
	v_mfma_f32_16x16x32_bf16 v[92:95], v[156:159], v[164:167], v[92:95]
	v_mfma_f32_16x16x32_bf16 v[96:99], v[148:151], v[164:167], v[96:99]
	v_mfma_f32_16x16x32_bf16 v[128:131], v[136:139], v[168:171], v[128:131]
	v_mfma_f32_16x16x32_bf16 v[124:127], v[144:147], v[168:171], v[124:127]
	v_mfma_f32_16x16x32_bf16 v[116:119], v[144:147], v[176:179], v[116:119]
	v_mfma_f32_16x16x32_bf16 v[120:123], v[136:139], v[176:179], v[120:123]
	v_mfma_f32_16x16x32_bf16 v[112:115], v[136:139], v[184:187], v[112:115]
	v_mfma_f32_16x16x32_bf16 v[108:111], v[144:147], v[184:187], v[108:111]
	v_mfma_f32_16x16x32_bf16 v[100:103], v[144:147], v[192:195], v[100:103]
	v_mfma_f32_16x16x32_bf16 v[104:107], v[136:139], v[192:195], v[104:107]
	v_mfma_f32_16x16x32_bf16 v[72:75], v[152:155], v[192:195], v[72:75]
	v_mfma_f32_16x16x32_bf16 v[68:71], v[160:163], v[192:195], v[68:71]
	v_mfma_f32_16x16x32_bf16 v[76:79], v[160:163], v[184:187], v[76:79]
	v_mfma_f32_16x16x32_bf16 v[80:83], v[152:155], v[184:187], v[80:83]
	v_mfma_f32_16x16x32_bf16 v[88:91], v[152:155], v[176:179], v[88:91]
	v_mfma_f32_16x16x32_bf16 v[84:87], v[160:163], v[176:179], v[84:87]
	v_mfma_f32_16x16x32_bf16 v[92:95], v[160:163], v[168:171], v[92:95]
	v_mfma_f32_16x16x32_bf16 v[96:99], v[152:155], v[168:171], v[96:99]
	s_barrier
	s_setprio 0
	ds_read_b128 v[164:167], v237 offset:16384
	ds_read_b128 v[168:171], v237 offset:17408
	ds_read_b128 v[172:175], v237 offset:18432
	ds_read_b128 v[176:179], v237 offset:19456
	ds_read_b128 v[180:183], v237 offset:20480
	ds_read_b128 v[184:187], v237 offset:21504
	ds_read_b128 v[188:191], v237 offset:22528
	ds_read_b128 v[192:195], v237 offset:23552
	buffer_load_dwordx4 v221, s[44:47], s12 offen lds
	s_mov_b32 m0, s53
	s_add_i32 s39, s12, 0x40000
	buffer_load_dwordx4 v223, s[44:47], s12 offen lds
	s_mov_b32 m0, s60
	s_sub_i32 s13, s13, s4
	buffer_load_dwordx4 v221, s[44:47], s39 offen lds
	s_mov_b32 m0, s61
	s_nop 0
	buffer_load_dwordx4 v223, s[44:47], s39 offen lds
	s_mov_b32 m0, s21
	s_nop 0
	buffer_load_dwordx4 v220, s[4:7], s13 offen lds
	s_waitcnt vmcnt(7) lgkmcnt(0)
	s_setprio 1
	s_barrier
	v_mfma_f32_16x16x32_bf16 v[64:67], v[132:135], v[164:167], v[64:67]
	v_mfma_f32_16x16x32_bf16 v[60:63], v[140:143], v[164:167], v[60:63]
	v_mfma_f32_16x16x32_bf16 v[52:55], v[140:143], v[172:175], v[52:55]
	v_mfma_f32_16x16x32_bf16 v[56:59], v[132:135], v[172:175], v[56:59]
	v_mfma_f32_16x16x32_bf16 v[48:51], v[132:135], v[180:183], v[48:51]
	v_mfma_f32_16x16x32_bf16 v[44:47], v[140:143], v[180:183], v[44:47]
	v_mfma_f32_16x16x32_bf16 v[36:39], v[140:143], v[188:191], v[36:39]
	v_mfma_f32_16x16x32_bf16 v[40:43], v[132:135], v[188:191], v[40:43]
	v_mfma_f32_16x16x32_bf16 v[64:67], v[136:139], v[168:171], v[64:67]
	v_mfma_f32_16x16x32_bf16 v[60:63], v[144:147], v[168:171], v[60:63]
	v_mfma_f32_16x16x32_bf16 v[52:55], v[144:147], v[176:179], v[52:55]
	v_mfma_f32_16x16x32_bf16 v[56:59], v[136:139], v[176:179], v[56:59]
	v_mfma_f32_16x16x32_bf16 v[48:51], v[136:139], v[184:187], v[48:51]
	v_mfma_f32_16x16x32_bf16 v[44:47], v[144:147], v[184:187], v[44:47]
	v_mfma_f32_16x16x32_bf16 v[36:39], v[144:147], v[192:195], v[36:39]
	v_mfma_f32_16x16x32_bf16 v[40:43], v[136:139], v[192:195], v[40:43]
	v_mfma_f32_16x16x32_bf16 v[32:35], v[148:151], v[164:167], v[32:35]
	v_mfma_f32_16x16x32_bf16 v[28:31], v[156:159], v[164:167], v[28:31]
	v_mfma_f32_16x16x32_bf16 v[20:23], v[156:159], v[172:175], v[20:23]
	v_mfma_f32_16x16x32_bf16 v[24:27], v[148:151], v[172:175], v[24:27]
	v_mfma_f32_16x16x32_bf16 v[16:19], v[148:151], v[180:183], v[16:19]
	v_mfma_f32_16x16x32_bf16 v[12:15], v[156:159], v[180:183], v[12:15]
	v_mfma_f32_16x16x32_bf16 v[2:5], v[156:159], v[188:191], v[4:7]
	v_mfma_f32_16x16x32_bf16 v[8:11], v[148:151], v[188:191], v[8:11]
	v_add_u32_e32 v0, 0x18000, v236
	v_mfma_f32_16x16x32_bf16 v[32:35], v[152:155], v[168:171], v[32:35]
	v_mfma_f32_16x16x32_bf16 v[28:31], v[160:163], v[168:171], v[28:31]
	v_mfma_f32_16x16x32_bf16 v[20:23], v[160:163], v[176:179], v[20:23]
	v_mfma_f32_16x16x32_bf16 v[24:27], v[152:155], v[176:179], v[24:27]
	v_mfma_f32_16x16x32_bf16 v[16:19], v[152:155], v[184:187], v[16:19]
	v_mfma_f32_16x16x32_bf16 v[12:15], v[160:163], v[184:187], v[12:15]
	v_mfma_f32_16x16x32_bf16 v[2:5], v[160:163], v[192:195], v[2:5]
	v_mfma_f32_16x16x32_bf16 v[8:11], v[152:155], v[192:195], v[8:11]
	s_barrier
; #define PG8_STAGE(bufoff, gbase, voff) do { const int so_ = (int)(unsigned)((const char*)(gbase) - base_##voff); _Pragma("unroll") for (int _i = 0; _i < 2; ++_i) \
;         __builtin_amdgcn_raw_ptr_buffer_load_lds(rs_##voff, (PG8_LAS unsigned*)(lds + (bufoff) + ldsw + _i * 8192), 16, (int)(voff)[_i], so_, 0, 0); } while (0)
; #define PG8_LDA(dst, b, h) do { _Pragma("unroll") for (int m = 0; m < 4; ++m) _Pragma("unroll") for (int k = 0; k < 2; ++k) dst[m][k] = *(const PG8_LAS bf16x8*)(lds + PG8_SA(b, h) + aoff + m * 2048 + k * 1024); } while (0)
; #define PG8_LDB(dst, b, h) do { _Pragma("unroll") for (int n = 0; n < 2; ++n) _Pragma("unroll") for (int k = 0; k < 2; ++k) dst[n][k] = *(const PG8_LAS bf16x8*)(lds + PG8_SB(b, h) + boff + n * 2048 + k * 1024); } while (0)
; #define PG8_WAIT_V(n) asm volatile("s_waitcnt vmcnt(" #n ")" ::: "memory")
; #define PG8_WAIT_L(n) asm volatile("s_waitcnt lgkmcnt(" #n ")" ::: "memory")
; #define PG8_BAR __builtin_amdgcn_s_barrier()
; #define PG8_SCHED __builtin_amdgcn_sched_barrier(0)
; template <class Epi, class Sched, bool ALIGN_EPI = false, bool SP2 = false>
; __device__ __forceinline__ void gemm_phase(PG8_LAS unsigned char* lds, const Gemm g, const Sched& S, const Epi& E, int tid_in) {
;     ...
;             PG8_LDB(B0, 0, 0); PG8_LDB(B1, 0, 1); PG8_SCHED; PG8_LDA(At, 0, 0); PG8_STAGE(PG8_SA(1, 1), a1 + hstepA, voffA);
;             PG8_WAIT_V(8); PG8_WAIT_L(0); PG8_BAR; PG8_MMA(0, 0, At, B0); PG8_MMA(0, 1, At, B1); PG8_BAR; PG8_SCHED;
;             PG8_LDA(At, 0, 1); PG8_STAGE(PG8_SB(0, 0), b2, voffB); PG8_STAGE(PG8_SB(0, 1), b2 + hstepB, voffB); PG8_STAGE(PG8_SA(0, 0), a2, voffA);
;             PG8_WAIT_V(8); PG8_WAIT_L(0); PG8_BAR; PG8_MMA(1, 0, At, B0); PG8_MMA(1, 1, At, B1); PG8_BAR; PG8_SCHED;
;             PG8_LDB(B0, 1, 0); PG8_LDB(B1, 1, 1); PG8_SCHED; PG8_LDA(At, 1, 0); PG8_STAGE(PG8_SA(0, 1), a2 + hstepA, voffA);
;             PG8_WAIT_V(8); PG8_WAIT_L(0); PG8_BAR; PG8_MMA(0, 0, At, B0); PG8_MMA(0, 1, At, B1); PG8_BAR; PG8_SCHED;
;             PG8_LDA(At, 1, 1); PG8_STAGE(PG8_SB(1, 0), b3, voffB); PG8_STAGE(PG8_SB(1, 1), b3 + hstepB, voffB); PG8_STAGE(PG8_SA(1, 0), a3, voffA);
;             PG8_WAIT_V(8); PG8_WAIT_L(0); PG8_BAR; PG8_MMA(1, 0, At, B0); PG8_MMA(1, 1, At, B1); PG8_BAR; PG8_SCHED;
;     ...
;         if constexpr (ALIGN_EPI) { if (wr == 0) PG8_BAR; }
	s_setprio 0
	ds_read_b128 v[132:135], v0
	ds_read_b128 v[136:139], v0 offset:1024
	ds_read_b128 v[140:143], v0 offset:2048
	ds_read_b128 v[144:147], v0 offset:3072
	v_add_u32_e32 v0, 0x1c000, v236
	ds_read_b128 v[148:151], v0
	ds_read_b128 v[152:155], v0 offset:1024
	ds_read_b128 v[156:159], v0 offset:2048
	ds_read_b128 v[160:163], v0 offset:3072
	s_add_i32 s39, s13, 0xc0000
	s_mov_b32 m0, s63
	ds_read_b128 v[164:167], v237 offset:32768
	ds_read_b128 v[168:171], v237 offset:33792
	ds_read_b128 v[172:175], v237 offset:34816
	ds_read_b128 v[176:179], v237 offset:35840
	ds_read_b128 v[180:183], v237 offset:36864
	ds_read_b128 v[184:187], v237 offset:37888
	ds_read_b128 v[188:191], v237 offset:38912
	ds_read_b128 v[192:195], v237 offset:39936
	s_mov_b32 m0, s62
	s_nop 0
	buffer_load_dwordx4 v222, s[4:7], s13 offen lds
	s_mov_b32 m0, s63
	s_nop 0
	buffer_load_dwordx4 v220, s[4:7], s39 offen lds
	s_mov_b32 m0, s66
	s_nop 0
	buffer_load_dwordx4 v222, s[4:7], s39 offen lds
	s_waitcnt vmcnt(8) lgkmcnt(0)
	s_setprio 1
	s_barrier
	v_mfma_f32_16x16x32_bf16 v[128:131], v[132:135], v[164:167], v[128:131]
	v_mfma_f32_16x16x32_bf16 v[124:127], v[140:143], v[164:167], v[124:127]
	v_mfma_f32_16x16x32_bf16 v[116:119], v[140:143], v[172:175], v[116:119]
	v_mfma_f32_16x16x32_bf16 v[120:123], v[132:135], v[172:175], v[120:123]
	v_mfma_f32_16x16x32_bf16 v[112:115], v[132:135], v[180:183], v[112:115]
	v_mfma_f32_16x16x32_bf16 v[108:111], v[140:143], v[180:183], v[108:111]
	v_mfma_f32_16x16x32_bf16 v[100:103], v[140:143], v[188:191], v[100:103]
	v_mfma_f32_16x16x32_bf16 v[104:107], v[132:135], v[188:191], v[104:107]
	s_mov_b32 m0, s69
	v_mfma_f32_16x16x32_bf16 v[72:75], v[148:151], v[188:191], v[72:75]
	s_add_i32 s39, s12, 0x80
	v_mfma_f32_16x16x32_bf16 v[68:71], v[156:159], v[188:191], v[68:71]
	v_mfma_f32_16x16x32_bf16 v[76:79], v[156:159], v[180:183], v[76:79]
	v_mfma_f32_16x16x32_bf16 v[80:83], v[148:151], v[180:183], v[80:83]
	v_mfma_f32_16x16x32_bf16 v[88:91], v[148:151], v[172:175], v[88:91]
	v_mfma_f32_16x16x32_bf16 v[84:87], v[156:159], v[172:175], v[84:87]
	v_mfma_f32_16x16x32_bf16 v[92:95], v[156:159], v[164:167], v[92:95]
	v_mfma_f32_16x16x32_bf16 v[96:99], v[148:151], v[164:167], v[96:99]
	v_mfma_f32_16x16x32_bf16 v[128:131], v[136:139], v[168:171], v[128:131]
	v_mfma_f32_16x16x32_bf16 v[124:127], v[144:147], v[168:171], v[124:127]
	v_mfma_f32_16x16x32_bf16 v[116:119], v[144:147], v[176:179], v[116:119]
	v_mfma_f32_16x16x32_bf16 v[120:123], v[136:139], v[176:179], v[120:123]
	v_mfma_f32_16x16x32_bf16 v[112:115], v[136:139], v[184:187], v[112:115]
	v_mfma_f32_16x16x32_bf16 v[108:111], v[144:147], v[184:187], v[108:111]
	v_mfma_f32_16x16x32_bf16 v[100:103], v[144:147], v[192:195], v[100:103]
	v_mfma_f32_16x16x32_bf16 v[104:107], v[136:139], v[192:195], v[104:107]
	v_mfma_f32_16x16x32_bf16 v[72:75], v[152:155], v[192:195], v[72:75]
	v_mfma_f32_16x16x32_bf16 v[68:71], v[160:163], v[192:195], v[68:71]
	v_mfma_f32_16x16x32_bf16 v[76:79], v[160:163], v[184:187], v[76:79]
	v_mfma_f32_16x16x32_bf16 v[80:83], v[152:155], v[184:187], v[80:83]
	v_mfma_f32_16x16x32_bf16 v[88:91], v[152:155], v[176:179], v[88:91]
	v_mfma_f32_16x16x32_bf16 v[84:87], v[160:163], v[176:179], v[84:87]
	v_mfma_f32_16x16x32_bf16 v[92:95], v[160:163], v[168:171], v[92:95]
	v_mfma_f32_16x16x32_bf16 v[96:99], v[152:155], v[168:171], v[96:99]
	s_barrier
	s_setprio 0
	ds_read_b128 v[164:167], v237 offset:49152
	ds_read_b128 v[168:171], v237 offset:50176
	ds_read_b128 v[172:175], v237 offset:51200
	ds_read_b128 v[176:179], v237 offset:52224
	ds_read_b128 v[180:183], v237 offset:53248
	ds_read_b128 v[184:187], v237 offset:54272
	ds_read_b128 v[188:191], v237 offset:55296
	ds_read_b128 v[192:195], v237 offset:56320
	buffer_load_dwordx4 v221, s[44:47], s39 offen lds
	s_mov_b32 m0, s71
	s_add_i32 s12, s12, 0x40080
	buffer_load_dwordx4 v223, s[44:47], s39 offen lds
	s_mov_b32 m0, s74
	s_addk_i32 s13, 0x80
	buffer_load_dwordx4 v221, s[44:47], s12 offen lds
	s_mov_b32 m0, s75
	s_nop 0
	buffer_load_dwordx4 v223, s[44:47], s12 offen lds
	s_mov_b32 m0, s72
	s_nop 0
	buffer_load_dwordx4 v220, s[4:7], s13 offen lds
	s_waitcnt vmcnt(7) lgkmcnt(0)
	s_setprio 1
	s_barrier
	v_mfma_f32_16x16x32_bf16 v[64:67], v[132:135], v[164:167], v[64:67]
	v_mfma_f32_16x16x32_bf16 v[60:63], v[140:143], v[164:167], v[60:63]
	v_mfma_f32_16x16x32_bf16 v[52:55], v[140:143], v[172:175], v[52:55]
	v_mfma_f32_16x16x32_bf16 v[56:59], v[132:135], v[172:175], v[56:59]
	v_mfma_f32_16x16x32_bf16 v[48:51], v[132:135], v[180:183], v[48:51]
	v_mfma_f32_16x16x32_bf16 v[44:47], v[140:143], v[180:183], v[44:47]
	v_mfma_f32_16x16x32_bf16 v[36:39], v[140:143], v[188:191], v[36:39]
	v_mfma_f32_16x16x32_bf16 v[40:43], v[132:135], v[188:191], v[40:43]
	s_add_i32 s38, s38, 2
	v_mfma_f32_16x16x32_bf16 v[64:67], v[136:139], v[168:171], v[64:67]
	s_add_u32 s19, s19, 0x100
	v_mfma_f32_16x16x32_bf16 v[60:63], v[144:147], v[168:171], v[60:63]
	s_addc_u32 s23, s23, 0
	v_mfma_f32_16x16x32_bf16 v[52:55], v[144:147], v[176:179], v[52:55]
	s_cmp_gt_u32 s38, 13
	v_mfma_f32_16x16x32_bf16 v[56:59], v[136:139], v[176:179], v[56:59]
	s_mov_b64 s[12:13], s[16:17]
	v_mfma_f32_16x16x32_bf16 v[48:51], v[136:139], v[184:187], v[48:51]
	v_mfma_f32_16x16x32_bf16 v[44:47], v[144:147], v[184:187], v[44:47]
	v_mfma_f32_16x16x32_bf16 v[36:39], v[144:147], v[192:195], v[36:39]
	v_mfma_f32_16x16x32_bf16 v[40:43], v[136:139], v[192:195], v[40:43]
	v_mfma_f32_16x16x32_bf16 v[32:35], v[148:151], v[164:167], v[32:35]
	v_mfma_f32_16x16x32_bf16 v[28:31], v[156:159], v[164:167], v[28:31]
	v_mfma_f32_16x16x32_bf16 v[20:23], v[156:159], v[172:175], v[20:23]
	v_mfma_f32_16x16x32_bf16 v[24:27], v[148:151], v[172:175], v[24:27]
	v_mfma_f32_16x16x32_bf16 v[16:19], v[148:151], v[180:183], v[16:19]
	v_mfma_f32_16x16x32_bf16 v[12:15], v[156:159], v[180:183], v[12:15]
	v_mfma_f32_16x16x32_bf16 v[2:5], v[156:159], v[188:191], v[2:5]
	v_mfma_f32_16x16x32_bf16 v[6:9], v[148:151], v[188:191], v[8:11]
	v_mfma_f32_16x16x32_bf16 v[32:35], v[152:155], v[168:171], v[32:35]
	v_mfma_f32_16x16x32_bf16 v[28:31], v[160:163], v[168:171], v[28:31]
	v_mfma_f32_16x16x32_bf16 v[20:23], v[160:163], v[176:179], v[20:23]
	v_mfma_f32_16x16x32_bf16 v[24:27], v[152:155], v[176:179], v[24:27]
	v_mfma_f32_16x16x32_bf16 v[16:19], v[152:155], v[184:187], v[16:19]
	v_mfma_f32_16x16x32_bf16 v[12:15], v[160:163], v[184:187], v[12:15]
	v_mfma_f32_16x16x32_bf16 v[8:11], v[152:155], v[192:195], v[6:9]
	v_mfma_f32_16x16x32_bf16 v[4:7], v[160:163], v[192:195], v[2:5]
	s_barrier
	s_setprio 0
	s_cbranch_scc0 .LBB0_1037
	s_and_b64 vcc, exec, s[14:15]
	s_cbranch_vccz .LBB0_1040
	s_barrier

; #define PG8_STAGE(bufoff, gbase, voff) do { const int so_ = (int)(unsigned)((const char*)(gbase) - base_##voff); _Pragma("unroll") for (int _i = 0; _i < 2; ++_i) \
;         __builtin_amdgcn_raw_ptr_buffer_load_lds(rs_##voff, (PG8_LAS unsigned*)(lds + (bufoff) + ldsw + _i * 8192), 16, (int)(voff)[_i], so_, 0, 0); } while (0)
; #define PG8_LDA(dst, b, h) do { _Pragma("unroll") for (int m = 0; m < 4; ++m) _Pragma("unroll") for (int k = 0; k < 2; ++k) dst[m][k] = *(const PG8_LAS bf16x8*)(lds + PG8_SA(b, h) + aoff + m * 2048 + k * 1024); } while (0)
; #define PG8_LDB(dst, b, h) do { _Pragma("unroll") for (int n = 0; n < 2; ++n) _Pragma("unroll") for (int k = 0; k < 2; ++k) dst[n][k] = *(const PG8_LAS bf16x8*)(lds + PG8_SB(b, h) + boff + n * 2048 + k * 1024); } while (0)
; #define PG8_MMA(ai, bj, At, Bt) do { __builtin_amdgcn_s_setprio(1); _Pragma("unroll") for (int m = 0; m < 4; ++m) _Pragma("unroll") for (int n = 0; n < 2; ++n) _Pragma("unroll") for (int k = 0; k < 2; ++k) \
;         acc[ai][bj][m][n] = __builtin_amdgcn_mfma_f32_16x16x32_bf16(Bt[n][k], At[m][k], acc[ai][bj][m][n], 0, 0, 0); __builtin_amdgcn_s_setprio(0); } while (0)
; #define PG8_WAIT_V(n) asm volatile("s_waitcnt vmcnt(" #n ")" ::: "memory")
; #define PG8_WAIT_L(n) asm volatile("s_waitcnt lgkmcnt(" #n ")" ::: "memory")
; #define PG8_BAR __builtin_amdgcn_s_barrier()
; #define PG8_SCHED __builtin_amdgcn_sched_barrier(0)
; template <class Epi, class Sched, bool ALIGN_EPI = false, bool SP2 = false>
; __device__ __forceinline__ void gemm_phase(PG8_LAS unsigned char* lds, const Gemm g, const Sched& S, const Epi& E, int tid_in) {
;     ...
;             PG8_LDB(B0, 0, 0); PG8_LDB(B1, 0, 1); PG8_SCHED; PG8_LDA(At, 0, 0); PG8_STAGE(PG8_SA(1, 1), a1 + hstepA, voffA);
;             PG8_WAIT_V(8); PG8_WAIT_L(0); PG8_BAR; PG8_MMA(0, 0, At, B0); PG8_MMA(0, 1, At, B1); PG8_BAR; PG8_SCHED;
;             PG8_LDA(At, 0, 1); PG8_STAGE(PG8_SB(0, 0), b2, voffB); PG8_STAGE(PG8_SB(0, 1), b2 + hstepB, voffB); PG8_STAGE(PG8_SA(0, 0), a2, voffA);
;             PG8_WAIT_V(8); PG8_WAIT_L(0); PG8_BAR; PG8_MMA(1, 0, At, B0); PG8_MMA(1, 1, At, B1); PG8_BAR; PG8_SCHED;
;             PG8_LDB(B0, 1, 0); PG8_LDB(B1, 1, 1); PG8_SCHED; PG8_LDA(At, 1, 0); PG8_STAGE(PG8_SA(0, 1), a2 + hstepA, voffA);
;             PG8_WAIT_V(8); PG8_WAIT_L(0); PG8_BAR; PG8_MMA(0, 0, At, B0); PG8_MMA(0, 1, At, B1); PG8_BAR; PG8_SCHED;
.LBB0_1265:
	v_add_u32_e32 v133, 0x10000, v131
	ds_read_b128 v[134:137], v133
	ds_read_b128 v[138:141], v133 offset:1024
	ds_read_b128 v[142:145], v133 offset:2048
	ds_read_b128 v[146:149], v133 offset:3072
	v_add_u32_e32 v133, 0x14000, v131
	ds_read_b128 v[150:153], v133
	ds_read_b128 v[154:157], v133 offset:1024
	ds_read_b128 v[158:161], v133 offset:2048
	ds_read_b128 v[166:169], v133 offset:3072
	s_add_i32 s42, s18, s44
	s_add_i32 s21, s14, s44
	s_add_i32 s79, s12, s44
	s_addk_i32 s42, 0xff80
	s_sub_i32 vcc_lo, s42, 0x80000
	s_cmp_eq_u32 s19, 28
	s_cselect_b32 s21, s15, s21
	s_mov_b32 m0, s75
	ds_read_b128 v[170:173], v132
	ds_read_b128 v[174:177], v132 offset:1024
	ds_read_b128 v[178:181], v132 offset:2048
	ds_read_b128 v[182:185], v132 offset:3072
	ds_read_b128 v[186:189], v132 offset:4096
	ds_read_b128 v[190:193], v132 offset:5120
	ds_read_b128 v[200:203], v132 offset:6144
	ds_read_b128 v[206:209], v132 offset:7168
	s_mov_b32 m0, s72
	s_nop 0
	buffer_load_dwordx4 v130, s[4:7], vcc_lo offen lds
	s_mov_b32 m0, s75
	s_nop 0
	buffer_load_dwordx4 v0, s[4:7], s42 offen lds
	s_mov_b32 m0, s76
	s_nop 0
	buffer_load_dwordx4 v130, s[4:7], s42 offen lds
	s_waitcnt vmcnt(8) lgkmcnt(0)
	s_setprio 1
	s_barrier
	v_mfma_f32_16x16x32_bf16 v[34:37], v[134:137], v[170:173], v[34:37]
	v_mfma_f32_16x16x32_bf16 v[18:21], v[142:145], v[170:173], v[18:21]
	v_mfma_f32_16x16x32_bf16 v[78:81], v[142:145], v[178:181], v[78:81]
	v_mfma_f32_16x16x32_bf16 v[86:89], v[134:137], v[178:181], v[86:89]
	v_mfma_f32_16x16x32_bf16 v[106:109], v[134:137], v[186:189], v[106:109]
	v_mfma_f32_16x16x32_bf16 v[102:105], v[142:145], v[186:189], v[102:105]
	v_mfma_f32_16x16x32_bf16 v[122:125], v[142:145], v[200:203], v[122:125]
	v_mfma_f32_16x16x32_bf16 v[126:129], v[134:137], v[200:203], v[126:129]
	s_cselect_b32 s79, s17, s79
	v_mfma_f32_16x16x32_bf16 v[118:121], v[150:153], v[200:203], v[118:121]
	s_mov_b32 m0, s49
	v_mfma_f32_16x16x32_bf16 v[114:117], v[158:161], v[200:203], v[114:117]
	s_mov_b32 s42, s6
	v_mfma_f32_16x16x32_bf16 v[110:113], v[158:161], v[186:189], v[110:113]
	s_mov_b32 s43, s7
	v_mfma_f32_16x16x32_bf16 v[98:101], v[150:153], v[186:189], v[98:101]
	s_sub_i32 s79, s79, s40
	v_mfma_f32_16x16x32_bf16 v[74:77], v[150:153], v[178:181], v[74:77]
	v_mfma_f32_16x16x32_bf16 v[90:93], v[158:161], v[178:181], v[90:93]
	v_mfma_f32_16x16x32_bf16 v[38:41], v[158:161], v[170:173], v[38:41]
	v_mfma_f32_16x16x32_bf16 v[14:17], v[150:153], v[170:173], v[14:17]
	v_mfma_f32_16x16x32_bf16 v[34:37], v[138:141], v[174:177], v[34:37]
	v_mfma_f32_16x16x32_bf16 v[18:21], v[146:149], v[174:177], v[18:21]
	v_mfma_f32_16x16x32_bf16 v[78:81], v[146:149], v[182:185], v[78:81]
	v_mfma_f32_16x16x32_bf16 v[86:89], v[138:141], v[182:185], v[86:89]
	v_mfma_f32_16x16x32_bf16 v[106:109], v[138:141], v[190:193], v[106:109]
	v_mfma_f32_16x16x32_bf16 v[102:105], v[146:149], v[190:193], v[102:105]
	v_mfma_f32_16x16x32_bf16 v[122:125], v[146:149], v[206:209], v[122:125]
	v_mfma_f32_16x16x32_bf16 v[126:129], v[138:141], v[206:209], v[126:129]
	v_mfma_f32_16x16x32_bf16 v[118:121], v[154:157], v[206:209], v[118:121]
	v_mfma_f32_16x16x32_bf16 v[114:117], v[166:169], v[206:209], v[114:117]
	v_mfma_f32_16x16x32_bf16 v[110:113], v[166:169], v[190:193], v[110:113]
	v_mfma_f32_16x16x32_bf16 v[98:101], v[154:157], v[190:193], v[98:101]
	v_mfma_f32_16x16x32_bf16 v[74:77], v[154:157], v[182:185], v[74:77]
	v_mfma_f32_16x16x32_bf16 v[90:93], v[166:169], v[182:185], v[90:93]
	v_mfma_f32_16x16x32_bf16 v[38:41], v[166:169], v[174:177], v[38:41]
	v_mfma_f32_16x16x32_bf16 v[14:17], v[154:157], v[174:177], v[14:17]
	s_barrier
	s_setprio 0
	ds_read_b128 v[170:173], v132 offset:16384
	ds_read_b128 v[174:177], v132 offset:17408
	ds_read_b128 v[178:181], v132 offset:18432
	ds_read_b128 v[182:185], v132 offset:19456
	ds_read_b128 v[186:189], v132 offset:20480
	ds_read_b128 v[190:193], v132 offset:21504
	ds_read_b128 v[200:203], v132 offset:22528
	ds_read_b128 v[206:209], v132 offset:23552
	buffer_load_dwordx4 v0, s[40:43], s79 offen lds
	s_mov_b32 m0, s60
	s_add_i32 vcc_lo, s79, 0x80000
	buffer_load_dwordx4 v130, s[40:43], s79 offen lds
	s_mov_b32 m0, s61
	s_sub_i32 s21, s21, s4
	buffer_load_dwordx4 v0, s[40:43], vcc_lo offen lds
	s_mov_b32 m0, s62
	s_nop 0
	buffer_load_dwordx4 v130, s[40:43], vcc_lo offen lds
	s_mov_b32 m0, s35
	s_nop 0
	buffer_load_dwordx4 v0, s[4:7], s21 offen lds
	s_waitcnt vmcnt(7) lgkmcnt(0)
	s_setprio 1
	s_barrier
	v_mfma_f32_16x16x32_bf16 v[50:53], v[134:137], v[170:173], v[50:53]
	v_mfma_f32_16x16x32_bf16 v[30:33], v[142:145], v[170:173], v[30:33]
	v_mfma_f32_16x16x32_bf16 v[58:61], v[142:145], v[178:181], v[58:61]
	v_mfma_f32_16x16x32_bf16 v[62:65], v[134:137], v[178:181], v[62:65]
	v_mfma_f32_16x16x32_bf16 v[94:97], v[134:137], v[186:189], v[94:97]
	v_mfma_f32_16x16x32_bf16 v[82:85], v[142:145], v[186:189], v[82:85]
	v_mfma_f32_16x16x32_bf16 v[26:29], v[142:145], v[200:203], v[26:29]
	v_mfma_f32_16x16x32_bf16 v[46:49], v[134:137], v[200:203], v[46:49]
	v_mfma_f32_16x16x32_bf16 v[6:9], v[150:153], v[200:203], v[6:9]
	v_mfma_f32_16x16x32_bf16 v[2:5], v[158:161], v[200:203], v[2:5]
	v_mfma_f32_16x16x32_bf16 v[42:45], v[158:161], v[186:189], v[42:45]
	v_mfma_f32_16x16x32_bf16 v[70:73], v[150:153], v[186:189], v[70:73]
	v_mfma_f32_16x16x32_bf16 v[54:57], v[150:153], v[178:181], v[54:57]
	v_mfma_f32_16x16x32_bf16 v[66:69], v[158:161], v[178:181], v[66:69]
	v_mfma_f32_16x16x32_bf16 v[10:13], v[158:161], v[170:173], v[10:13]
	v_mfma_f32_16x16x32_bf16 v[22:25], v[150:153], v[170:173], v[22:25]
	v_mfma_f32_16x16x32_bf16 v[50:53], v[138:141], v[174:177], v[50:53]
	v_mfma_f32_16x16x32_bf16 v[30:33], v[146:149], v[174:177], v[30:33]
	v_mfma_f32_16x16x32_bf16 v[58:61], v[146:149], v[182:185], v[58:61]
	v_mfma_f32_16x16x32_bf16 v[62:65], v[138:141], v[182:185], v[62:65]
	v_mfma_f32_16x16x32_bf16 v[94:97], v[138:141], v[190:193], v[94:97]
	v_mfma_f32_16x16x32_bf16 v[82:85], v[146:149], v[190:193], v[82:85]
	v_mfma_f32_16x16x32_bf16 v[26:29], v[146:149], v[206:209], v[26:29]
	v_mfma_f32_16x16x32_bf16 v[46:49], v[138:141], v[206:209], v[46:49]
	v_add_u32_e32 v133, 0x18000, v131
	v_mfma_f32_16x16x32_bf16 v[6:9], v[154:157], v[206:209], v[6:9]
	v_mfma_f32_16x16x32_bf16 v[2:5], v[166:169], v[206:209], v[2:5]
	v_mfma_f32_16x16x32_bf16 v[42:45], v[166:169], v[190:193], v[42:45]
	v_mfma_f32_16x16x32_bf16 v[70:73], v[154:157], v[190:193], v[70:73]
	v_mfma_f32_16x16x32_bf16 v[54:57], v[154:157], v[182:185], v[54:57]
	v_mfma_f32_16x16x32_bf16 v[66:69], v[166:169], v[182:185], v[66:69]
	v_mfma_f32_16x16x32_bf16 v[10:13], v[166:169], v[174:177], v[10:13]
	v_mfma_f32_16x16x32_bf16 v[22:25], v[154:157], v[174:177], v[22:25]
	s_barrier
; #define PG8_STAGE(bufoff, gbase, voff) do { const int so_ = (int)(unsigned)((const char*)(gbase) - base_##voff); _Pragma("unroll") for (int _i = 0; _i < 2; ++_i) \
;         __builtin_amdgcn_raw_ptr_buffer_load_lds(rs_##voff, (PG8_LAS unsigned*)(lds + (bufoff) + ldsw + _i * 8192), 16, (int)(voff)[_i], so_, 0, 0); } while (0)
; #define PG8_LDA(dst, b, h) do { _Pragma("unroll") for (int m = 0; m < 4; ++m) _Pragma("unroll") for (int k = 0; k < 2; ++k) dst[m][k] = *(const PG8_LAS bf16x8*)(lds + PG8_SA(b, h) + aoff + m * 2048 + k * 1024); } while (0)
; #define PG8_LDB(dst, b, h) do { _Pragma("unroll") for (int n = 0; n < 2; ++n) _Pragma("unroll") for (int k = 0; k < 2; ++k) dst[n][k] = *(const PG8_LAS bf16x8*)(lds + PG8_SB(b, h) + boff + n * 2048 + k * 1024); } while (0)
; #define PG8_MMA(ai, bj, At, Bt) do { __builtin_amdgcn_s_setprio(1); _Pragma("unroll") for (int m = 0; m < 4; ++m) _Pragma("unroll") for (int n = 0; n < 2; ++n) _Pragma("unroll") for (int k = 0; k < 2; ++k) \
;         acc[ai][bj][m][n] = __builtin_amdgcn_mfma_f32_16x16x32_bf16(Bt[n][k], At[m][k], acc[ai][bj][m][n], 0, 0, 0); __builtin_amdgcn_s_setprio(0); } while (0)
; #define PG8_WAIT_V(n) asm volatile("s_waitcnt vmcnt(" #n ")" ::: "memory")
; #define PG8_WAIT_L(n) asm volatile("s_waitcnt lgkmcnt(" #n ")" ::: "memory")
; #define PG8_BAR __builtin_amdgcn_s_barrier()
; #define PG8_SCHED __builtin_amdgcn_sched_barrier(0)
; template <class Epi, class Sched, bool ALIGN_EPI = false, bool SP2 = false>
; __device__ __forceinline__ void gemm_phase(PG8_LAS unsigned char* lds, const Gemm g, const Sched& S, const Epi& E, int tid_in) {
;     ...
;             PG8_LDB(B0, 1, 0); PG8_LDB(B1, 1, 1); PG8_SCHED; PG8_LDA(At, 1, 0); PG8_STAGE(PG8_SA(0, 1), a2 + hstepA, voffA);
;             PG8_WAIT_V(8); PG8_WAIT_L(0); PG8_BAR; PG8_MMA(0, 0, At, B0); PG8_MMA(0, 1, At, B1); PG8_BAR; PG8_SCHED;
;             PG8_LDA(At, 1, 1); PG8_STAGE(PG8_SB(1, 0), b3, voffB); PG8_STAGE(PG8_SB(1, 1), b3 + hstepB, voffB); PG8_STAGE(PG8_SA(1, 0), a3, voffA);
;             PG8_WAIT_V(8); PG8_WAIT_L(0); PG8_BAR; PG8_MMA(1, 0, At, B0); PG8_MMA(1, 1, At, B1); PG8_BAR; PG8_SCHED;
	s_setprio 0
	ds_read_b128 v[134:137], v133
	ds_read_b128 v[138:141], v133 offset:1024
	ds_read_b128 v[142:145], v133 offset:2048
	ds_read_b128 v[146:149], v133 offset:3072
	v_add_u32_e32 v133, 0x1c000, v131
	ds_read_b128 v[150:153], v133
	ds_read_b128 v[154:157], v133 offset:1024
	ds_read_b128 v[158:161], v133 offset:2048
	ds_read_b128 v[166:169], v133 offset:3072
	s_add_i32 vcc_lo, s21, 0x80000
	s_mov_b32 m0, s66
	ds_read_b128 v[170:173], v132 offset:32768
	ds_read_b128 v[174:177], v132 offset:33792
	ds_read_b128 v[178:181], v132 offset:34816
	ds_read_b128 v[182:185], v132 offset:35840
	ds_read_b128 v[186:189], v132 offset:36864
	ds_read_b128 v[190:193], v132 offset:37888
	ds_read_b128 v[200:203], v132 offset:38912
	ds_read_b128 v[206:209], v132 offset:39936
	s_mov_b32 m0, s63
	s_nop 0
	buffer_load_dwordx4 v130, s[4:7], s21 offen lds
	s_mov_b32 m0, s66
	s_nop 0
	buffer_load_dwordx4 v0, s[4:7], vcc_lo offen lds
	s_mov_b32 m0, s67
	s_nop 0
	buffer_load_dwordx4 v130, s[4:7], vcc_lo offen lds
	s_waitcnt vmcnt(8) lgkmcnt(0)
	s_setprio 1
	s_barrier
	v_mfma_f32_16x16x32_bf16 v[34:37], v[134:137], v[170:173], v[34:37]
	v_mfma_f32_16x16x32_bf16 v[18:21], v[142:145], v[170:173], v[18:21]
	v_mfma_f32_16x16x32_bf16 v[78:81], v[142:145], v[178:181], v[78:81]
	v_mfma_f32_16x16x32_bf16 v[86:89], v[134:137], v[178:181], v[86:89]
	v_mfma_f32_16x16x32_bf16 v[106:109], v[134:137], v[186:189], v[106:109]
	v_mfma_f32_16x16x32_bf16 v[102:105], v[142:145], v[186:189], v[102:105]
	v_mfma_f32_16x16x32_bf16 v[122:125], v[142:145], v[200:203], v[122:125]
	v_mfma_f32_16x16x32_bf16 v[126:129], v[134:137], v[200:203], v[126:129]
	s_mov_b32 m0, s68
	v_mfma_f32_16x16x32_bf16 v[118:121], v[150:153], v[200:203], v[118:121]
	v_mfma_f32_16x16x32_bf16 v[114:117], v[158:161], v[200:203], v[114:117]
	v_mfma_f32_16x16x32_bf16 v[110:113], v[158:161], v[186:189], v[110:113]
	v_mfma_f32_16x16x32_bf16 v[98:101], v[150:153], v[186:189], v[98:101]
	v_mfma_f32_16x16x32_bf16 v[74:77], v[150:153], v[178:181], v[74:77]
	v_mfma_f32_16x16x32_bf16 v[90:93], v[158:161], v[178:181], v[90:93]
	v_mfma_f32_16x16x32_bf16 v[38:41], v[158:161], v[170:173], v[38:41]
	v_mfma_f32_16x16x32_bf16 v[14:17], v[150:153], v[170:173], v[14:17]
	v_mfma_f32_16x16x32_bf16 v[34:37], v[138:141], v[174:177], v[34:37]
	v_mfma_f32_16x16x32_bf16 v[18:21], v[146:149], v[174:177], v[18:21]
	v_mfma_f32_16x16x32_bf16 v[78:81], v[146:149], v[182:185], v[78:81]
	v_mfma_f32_16x16x32_bf16 v[86:89], v[138:141], v[182:185], v[86:89]
	v_mfma_f32_16x16x32_bf16 v[106:109], v[138:141], v[190:193], v[106:109]
	v_mfma_f32_16x16x32_bf16 v[102:105], v[146:149], v[190:193], v[102:105]
	v_mfma_f32_16x16x32_bf16 v[122:125], v[146:149], v[206:209], v[122:125]
	v_mfma_f32_16x16x32_bf16 v[126:129], v[138:141], v[206:209], v[126:129]
	v_mfma_f32_16x16x32_bf16 v[118:121], v[154:157], v[206:209], v[118:121]
	v_mfma_f32_16x16x32_bf16 v[114:117], v[166:169], v[206:209], v[114:117]
	v_mfma_f32_16x16x32_bf16 v[110:113], v[166:169], v[190:193], v[110:113]
	v_mfma_f32_16x16x32_bf16 v[98:101], v[154:157], v[190:193], v[98:101]
	v_mfma_f32_16x16x32_bf16 v[74:77], v[154:157], v[182:185], v[74:77]
	v_mfma_f32_16x16x32_bf16 v[90:93], v[166:169], v[182:185], v[90:93]
	v_mfma_f32_16x16x32_bf16 v[38:41], v[166:169], v[174:177], v[38:41]
	v_mfma_f32_16x16x32_bf16 v[14:17], v[154:157], v[174:177], v[14:17]
	s_barrier
	s_setprio 0
	s_add_i32 vcc_lo, s79, 0x80
	ds_read_b128 v[170:173], v132 offset:49152
	ds_read_b128 v[174:177], v132 offset:50176
	ds_read_b128 v[178:181], v132 offset:51200
	ds_read_b128 v[182:185], v132 offset:52224
	ds_read_b128 v[186:189], v132 offset:53248
	ds_read_b128 v[190:193], v132 offset:54272
	ds_read_b128 v[200:203], v132 offset:55296
	ds_read_b128 v[206:209], v132 offset:56320
	buffer_load_dwordx4 v0, s[40:43], vcc_lo offen lds
	s_mov_b32 m0, s69
	s_add_i32 s79, s79, 0x80080
	buffer_load_dwordx4 v130, s[40:43], vcc_lo offen lds
	s_mov_b32 m0, s73
	s_addk_i32 s21, 0x80
	buffer_load_dwordx4 v0, s[40:43], s79 offen lds
	s_mov_b32 m0, s74
	s_nop 0
	buffer_load_dwordx4 v130, s[40:43], s79 offen lds
	s_mov_b32 m0, s71
	s_nop 0
	buffer_load_dwordx4 v0, s[4:7], s21 offen lds
	s_waitcnt vmcnt(7) lgkmcnt(0)
	s_setprio 1
	s_barrier
;     static __device__ __forceinline__ bool last_of_chain(const Unit& u) { return (u.pn >> 3) == 2; }
; #define PG8_STAGE(bufoff, gbase, voff) do { const int so_ = (int)(unsigned)((const char*)(gbase) - base_##voff); _Pragma("unroll") for (int _i = 0; _i < 2; ++_i) \
;         __builtin_amdgcn_raw_ptr_buffer_load_lds(rs_##voff, (PG8_LAS unsigned*)(lds + (bufoff) + ldsw + _i * 8192), 16, (int)(voff)[_i], so_, 0, 0); } while (0)
; #define PG8_LDA(dst, b, h) do { _Pragma("unroll") for (int m = 0; m < 4; ++m) _Pragma("unroll") for (int k = 0; k < 2; ++k) dst[m][k] = *(const PG8_LAS bf16x8*)(lds + PG8_SA(b, h) + aoff + m * 2048 + k * 1024); } while (0)
; #define PG8_MMA(ai, bj, At, Bt) do { __builtin_amdgcn_s_setprio(1); _Pragma("unroll") for (int m = 0; m < 4; ++m) _Pragma("unroll") for (int n = 0; n < 2; ++n) _Pragma("unroll") for (int k = 0; k < 2; ++k) \
;         acc[ai][bj][m][n] = __builtin_amdgcn_mfma_f32_16x16x32_bf16(Bt[n][k], At[m][k], acc[ai][bj][m][n], 0, 0, 0); __builtin_amdgcn_s_setprio(0); } while (0)
; #define PG8_WAIT_V(n) asm volatile("s_waitcnt vmcnt(" #n ")" ::: "memory")
; #define PG8_WAIT_L(n) asm volatile("s_waitcnt lgkmcnt(" #n ")" ::: "memory")
; #define PG8_BAR __builtin_amdgcn_s_barrier()
; #define PG8_SCHED __builtin_amdgcn_sched_barrier(0)
; template <class Epi, class Sched, bool ALIGN_EPI = false, bool SP2 = false>
; __device__ __forceinline__ void gemm_phase(PG8_LAS unsigned char* lds, const Gemm g, const Sched& S, const Epi& E, int tid_in) {
;     ...
;             PG8_WAIT_V(8); PG8_WAIT_L(0); PG8_BAR; PG8_MMA(0, 0, At, B0); PG8_MMA(0, 1, At, B1); PG8_BAR; PG8_SCHED;
;             PG8_LDA(At, 1, 1); PG8_STAGE(PG8_SB(1, 0), b3, voffB); PG8_STAGE(PG8_SB(1, 1), b3 + hstepB, voffB); PG8_STAGE(PG8_SA(1, 0), a3, voffA);
;             PG8_WAIT_V(8); PG8_WAIT_L(0); PG8_BAR; PG8_MMA(1, 0, At, B0); PG8_MMA(1, 1, At, B1); PG8_BAR; PG8_SCHED;
;     ...
;         if (!has_next) break;
;         bool zero_acc = true; if constexpr (Epi::CHAIN) zero_acc = Epi::last_of_chain(cur);
;         if (zero_acc) {
; #pragma unroll
;         for (int a = 0; a < 2; ++a)
; #pragma unroll
;             for (int b = 0; b < 2; ++b)
; #pragma unroll
;                 for (int m = 0; m < 4; ++m)
; #pragma unroll
;                     for (int n = 0; n < 2; ++n) acc[a][b][m][n] = (f32x4){0.f, 0.f, 0.f, 0.f};
;         }
;         cur = nxt; cA = nA; cB = nB; ++ui;
	v_mfma_f32_16x16x32_bf16 v[50:53], v[134:137], v[170:173], v[50:53]
	v_mfma_f32_16x16x32_bf16 v[30:33], v[142:145], v[170:173], v[30:33]
	v_mfma_f32_16x16x32_bf16 v[58:61], v[142:145], v[178:181], v[58:61]
	v_mfma_f32_16x16x32_bf16 v[62:65], v[134:137], v[178:181], v[62:65]
	v_mfma_f32_16x16x32_bf16 v[94:97], v[134:137], v[186:189], v[94:97]
	v_mfma_f32_16x16x32_bf16 v[82:85], v[142:145], v[186:189], v[82:85]
	v_mfma_f32_16x16x32_bf16 v[26:29], v[142:145], v[200:203], v[26:29]
	v_mfma_f32_16x16x32_bf16 v[46:49], v[134:137], v[200:203], v[46:49]
	s_add_i32 s19, s19, 2
	v_mfma_f32_16x16x32_bf16 v[6:9], v[150:153], v[200:203], v[6:9]
	s_add_u32 s44, s44, 0x100
	v_mfma_f32_16x16x32_bf16 v[2:5], v[158:161], v[200:203], v[2:5]
	s_addc_u32 s45, s45, 0
	v_mfma_f32_16x16x32_bf16 v[42:45], v[158:161], v[186:189], v[42:45]
	s_cmp_gt_u32 s19, 29
	v_mfma_f32_16x16x32_bf16 v[70:73], v[150:153], v[186:189], v[70:73]
	v_mfma_f32_16x16x32_bf16 v[54:57], v[150:153], v[178:181], v[54:57]
	v_mfma_f32_16x16x32_bf16 v[66:69], v[158:161], v[178:181], v[66:69]
	v_mfma_f32_16x16x32_bf16 v[10:13], v[158:161], v[170:173], v[10:13]
	v_mfma_f32_16x16x32_bf16 v[22:25], v[150:153], v[170:173], v[22:25]
	v_mfma_f32_16x16x32_bf16 v[50:53], v[138:141], v[174:177], v[50:53]
	v_mfma_f32_16x16x32_bf16 v[30:33], v[146:149], v[174:177], v[30:33]
	v_mfma_f32_16x16x32_bf16 v[58:61], v[146:149], v[182:185], v[58:61]
	v_mfma_f32_16x16x32_bf16 v[62:65], v[138:141], v[182:185], v[62:65]
	v_mfma_f32_16x16x32_bf16 v[94:97], v[138:141], v[190:193], v[94:97]
	v_mfma_f32_16x16x32_bf16 v[82:85], v[146:149], v[190:193], v[82:85]
	v_mfma_f32_16x16x32_bf16 v[26:29], v[146:149], v[206:209], v[26:29]
	v_mfma_f32_16x16x32_bf16 v[46:49], v[138:141], v[206:209], v[46:49]
	v_mfma_f32_16x16x32_bf16 v[6:9], v[154:157], v[206:209], v[6:9]
	v_mfma_f32_16x16x32_bf16 v[2:5], v[166:169], v[206:209], v[2:5]
	v_mfma_f32_16x16x32_bf16 v[42:45], v[166:169], v[190:193], v[42:45]
	v_mfma_f32_16x16x32_bf16 v[70:73], v[154:157], v[190:193], v[70:73]
	v_mfma_f32_16x16x32_bf16 v[54:57], v[154:157], v[182:185], v[54:57]
	v_mfma_f32_16x16x32_bf16 v[66:69], v[166:169], v[182:185], v[66:69]
	v_mfma_f32_16x16x32_bf16 v[10:13], v[166:169], v[174:177], v[10:13]
	v_mfma_f32_16x16x32_bf16 v[22:25], v[154:157], v[174:177], v[22:25]
	s_barrier
	s_setprio 0
	s_cbranch_scc0 .LBB0_1265
	s_andn2_b64 vcc, exec, s[38:39]
	s_cbranch_vccnz .LBB0_1257
	v_mov_b32_e32 v2, 0
	s_mov_b64 s[12:13], s[24:25]
	s_mov_b32 s10, s16
	s_mov_b32 s48, s20
	s_mov_b64 s[14:15], s[22:23]
	s_mov_b32 s13, s78
	v_mov_b32_e32 v3, v2
	v_mov_b32_e32 v4, v2
	v_mov_b32_e32 v5, v2
	v_mov_b32_e32 v6, v2
	v_mov_b32_e32 v7, v2
	v_mov_b32_e32 v8, v2
	v_mov_b32_e32 v9, v2
	v_mov_b32_e32 v42, v2
	v_mov_b32_e32 v43, v2
	v_mov_b32_e32 v44, v2
	v_mov_b32_e32 v45, v2
	v_mov_b32_e32 v70, v2
	v_mov_b32_e32 v71, v2
	v_mov_b32_e32 v72, v2
	v_mov_b32_e32 v73, v2
	v_mov_b32_e32 v66, v2
	v_mov_b32_e32 v67, v2
	v_mov_b32_e32 v68, v2
	v_mov_b32_e32 v69, v2
	v_mov_b32_e32 v54, v2
	v_mov_b32_e32 v55, v2
	v_mov_b32_e32 v56, v2
	v_mov_b32_e32 v57, v2
	v_mov_b32_e32 v10, v2
	v_mov_b32_e32 v11, v2
	v_mov_b32_e32 v12, v2
	v_mov_b32_e32 v13, v2
	v_mov_b32_e32 v22, v2
	v_mov_b32_e32 v23, v2
	v_mov_b32_e32 v24, v2
	v_mov_b32_e32 v25, v2
	v_mov_b32_e32 v26, v2
	v_mov_b32_e32 v27, v2
	v_mov_b32_e32 v28, v2
	v_mov_b32_e32 v29, v2
	v_mov_b32_e32 v46, v2
	v_mov_b32_e32 v47, v2
	v_mov_b32_e32 v48, v2
	v_mov_b32_e32 v49, v2
	v_mov_b32_e32 v82, v2
	v_mov_b32_e32 v83, v2
	v_mov_b32_e32 v84, v2
	v_mov_b32_e32 v85, v2
	v_mov_b32_e32 v94, v2
	v_mov_b32_e32 v95, v2
	v_mov_b32_e32 v96, v2
	v_mov_b32_e32 v97, v2
	v_mov_b32_e32 v58, v2
	v_mov_b32_e32 v59, v2
	v_mov_b32_e32 v60, v2
	v_mov_b32_e32 v61, v2
	v_mov_b32_e32 v62, v2
	v_mov_b32_e32 v63, v2
	v_mov_b32_e32 v64, v2
	v_mov_b32_e32 v65, v2
	v_mov_b32_e32 v30, v2
	v_mov_b32_e32 v31, v2
	v_mov_b32_e32 v32, v2
	v_mov_b32_e32 v33, v2
	v_mov_b32_e32 v50, v2
	v_mov_b32_e32 v51, v2
	v_mov_b32_e32 v52, v2
	v_mov_b32_e32 v53, v2
	v_mov_b32_e32 v114, v2
	v_mov_b32_e32 v115, v2
	v_mov_b32_e32 v116, v2
	v_mov_b32_e32 v117, v2
	v_mov_b32_e32 v118, v2
	v_mov_b32_e32 v119, v2
	v_mov_b32_e32 v120, v2
	v_mov_b32_e32 v121, v2
	v_mov_b32_e32 v110, v2
	v_mov_b32_e32 v111, v2
	v_mov_b32_e32 v112, v2
	v_mov_b32_e32 v113, v2
	v_mov_b32_e32 v98, v2
	v_mov_b32_e32 v99, v2
	v_mov_b32_e32 v100, v2
	v_mov_b32_e32 v101, v2
	v_mov_b32_e32 v90, v2
	v_mov_b32_e32 v91, v2
	v_mov_b32_e32 v92, v2
	v_mov_b32_e32 v93, v2
	v_mov_b32_e32 v74, v2
	v_mov_b32_e32 v75, v2
	v_mov_b32_e32 v76, v2
	v_mov_b32_e32 v77, v2
	v_mov_b32_e32 v38, v2
	v_mov_b32_e32 v39, v2
	v_mov_b32_e32 v40, v2
	v_mov_b32_e32 v41, v2
	v_mov_b32_e32 v14, v2
	v_mov_b32_e32 v15, v2
	v_mov_b32_e32 v16, v2
	v_mov_b32_e32 v17, v2
	v_mov_b32_e32 v122, v2
	v_mov_b32_e32 v123, v2
	v_mov_b32_e32 v124, v2
	v_mov_b32_e32 v125, v2
	v_mov_b32_e32 v126, v2
	v_mov_b32_e32 v127, v2
	v_mov_b32_e32 v128, v2
	v_mov_b32_e32 v129, v2
	v_mov_b32_e32 v102, v2
	v_mov_b32_e32 v103, v2
	v_mov_b32_e32 v104, v2
	v_mov_b32_e32 v105, v2
	v_mov_b32_e32 v106, v2
	v_mov_b32_e32 v107, v2
	v_mov_b32_e32 v108, v2
	v_mov_b32_e32 v109, v2
	v_mov_b32_e32 v78, v2
	v_mov_b32_e32 v79, v2
	v_mov_b32_e32 v80, v2
	v_mov_b32_e32 v81, v2
	v_mov_b32_e32 v86, v2
	v_mov_b32_e32 v87, v2
	v_mov_b32_e32 v88, v2
	v_mov_b32_e32 v89, v2
	v_mov_b32_e32 v18, v2
	v_mov_b32_e32 v19, v2
	v_mov_b32_e32 v20, v2
	v_mov_b32_e32 v21, v2
	v_mov_b32_e32 v34, v2
	v_mov_b32_e32 v35, v2
	v_mov_b32_e32 v36, v2
	v_mov_b32_e32 v37, v2
	s_branch .LBB0_1257

;     __host__ __device__ bool next(int i, Unit& u) const { const int t = i / 3, b = i - 3 * t; Unit v; if (!StaticOrder::next(t, v)) return false; u.pm = v.pm; u.pn = 8 * b + v.pn; return true; }
; #define PG8_STAGE(bufoff, gbase, voff) do { const int so_ = (int)(unsigned)((const char*)(gbase) - base_##voff); _Pragma("unroll") for (int _i = 0; _i < 2; ++_i) \
;         __builtin_amdgcn_raw_ptr_buffer_load_lds(rs_##voff, (PG8_LAS unsigned*)(lds + (bufoff) + ldsw + _i * 8192), 16, (int)(voff)[_i], so_, 0, 0); } while (0)
; #define PG8_LDA(dst, b, h) do { _Pragma("unroll") for (int m = 0; m < 4; ++m) _Pragma("unroll") for (int k = 0; k < 2; ++k) dst[m][k] = *(const PG8_LAS bf16x8*)(lds + PG8_SA(b, h) + aoff + m * 2048 + k * 1024); } while (0)
; #define PG8_WAIT_V(n) asm volatile("s_waitcnt vmcnt(" #n ")" ::: "memory")
; #define PG8_WAIT_L(n) asm volatile("s_waitcnt lgkmcnt(" #n ")" ::: "memory")
; #define PG8_BAR __builtin_amdgcn_s_barrier()
; template <class Epi, class Sched, bool ALIGN_EPI = false, bool SP2 = false>
; __device__ __forceinline__ void gemm_phase(PG8_LAS unsigned char* lds, const Gemm g, const Sched& S, const Epi& E, int tid_in) {
;     ...
;         const bool has_next = S.next(ui + 1, nxt);
;         const char* nA = has_next ? (const char*)g.A + (size_t)nxt.pm * tstepA + (g.grp ? (size_t)(nxt.pn / g.grp) * g.agrp : (size_t)0) : cA; const char* nB = has_next ? (const char*)g.Bt + (size_t)nxt.pn * tstepB : cB;
;         for (int t = 0; t < nt; t += 2) {
;             const bool last = (t == nt - 2);
;             const char* a1 = cA + (size_t)(t + 1) * kstep;
;             const char* a2 = last ? nA : cA + (size_t)(t + 2) * kstep; const char* b2 = last ? nB : cB + (size_t)(t + 2) * kstep;
;             const char* a3 = a2 + kstep; const char* b3 = b2 + kstep;
;             if (last && has_next) S.a_ready(nxt);
;             if constexpr (SP2) {
;             PG8_LDB(B0, 0, 0); PG8_LDB(B1, 0, 1); PG8_SCHED; PG8_LDA(At, 0, 0); PG8_STAGE(PG8_SA(1, 1), a1 + hstepA, voffA);
;             PG8_WAIT_V(8); PG8_WAIT_L(0); PG8_BAR; PG8_MMA(0, 0, At, B0); PG8_MMA(0, 1, At, B1); PG8_BAR; PG8_SCHED;
;             PG8_LDA(At, 0, 1); PG8_STAGE(PG8_SB(0, 0), b2, voffB); PG8_STAGE(PG8_SB(0, 1), b2 + hstepB, voffB); PG8_STAGE(PG8_SA(0, 0), a2, voffA);
;             PG8_WAIT_V(8); PG8_WAIT_L(0); PG8_BAR; PG8_MMA(1, 0, At, B0); PG8_MMA(1, 1, At, B1); PG8_BAR; PG8_SCHED;
.LBB0_1513:
	s_ashr_i32 s21, s20, 31
	s_lshl_b64 s[18:19], s[20:21], 20
	s_add_u32 s22, s4, s18
	s_addc_u32 s23, s9, s19
	s_and_b64 s[18:19], s[36:37], exec
	s_cselect_b32 s18, s22, s16
	s_ashr_i32 s15, s14, 31
	s_lshl_b64 s[24:25], s[14:15], 20
	s_add_u32 s24, s40, s24
	s_addc_u32 s25, s26, s25
	s_and_b64 s[42:43], s[36:37], exec
	s_cselect_b32 s15, s24, s38
	s_add_u32 s19, s38, 0x100
	v_mov_b32_e32 v2, 0
	s_addc_u32 s21, s39, 0
	s_mov_b32 s73, -2
	v_add_u32_e32 v141, 0x10000, v139
	ds_read_b128 v[130:133], v141
	ds_read_b128 v[142:145], v141 offset:1024
	ds_read_b128 v[146:149], v141 offset:2048
	ds_read_b128 v[150:153], v141 offset:3072
	v_add_u32_e32 v141, 0x14000, v139
	ds_read_b128 v[154:157], v141
	ds_read_b128 v[158:161], v141 offset:1024
	ds_read_b128 v[162:165], v141 offset:2048
	ds_read_b128 v[166:169], v141 offset:3072
	s_add_u32 s38, s16, 0x100
	s_addc_u32 s39, s17, 0
	s_sub_i32 s16, s16, s4
	s_add_i32 s16, s16, 0x80080
	s_sub_i32 s74, s16, 0x80000
	s_cmp_eq_u32 s73, 28
	s_cselect_b32 s17, s18, s38
	s_mov_b32 m0, s67
	ds_read_b128 v[170:173], v140
	ds_read_b128 v[174:177], v140 offset:1024
	ds_read_b128 v[178:181], v140 offset:2048
	ds_read_b128 v[182:185], v140 offset:3072
	ds_read_b128 v[186:189], v140 offset:4096
	ds_read_b128 v[190:193], v140 offset:5120
	ds_read_b128 v[200:203], v140 offset:6144
	ds_read_b128 v[206:209], v140 offset:7168
	s_mov_b32 m0, s62
	s_nop 0
	buffer_load_dwordx4 v135, s[4:7], s74 offen lds
	s_mov_b32 m0, s67
	s_nop 0
	buffer_load_dwordx4 v0, s[4:7], s16 offen lds
	s_mov_b32 m0, s68
	s_nop 0
	buffer_load_dwordx4 v135, s[4:7], s16 offen lds
	s_waitcnt vmcnt(8) lgkmcnt(0)
	s_setprio 1
	s_barrier
	v_mfma_f32_16x16x32_bf16 v[126:129], v[130:133], v[170:173], 0
	v_mfma_f32_16x16x32_bf16 v[122:125], v[146:149], v[170:173], 0
	v_mfma_f32_16x16x32_bf16 v[106:109], v[146:149], v[178:181], 0
	v_mfma_f32_16x16x32_bf16 v[110:113], v[130:133], v[178:181], 0
	v_mfma_f32_16x16x32_bf16 v[94:97], v[130:133], v[186:189], 0
	v_mfma_f32_16x16x32_bf16 v[90:93], v[146:149], v[186:189], 0
	v_mfma_f32_16x16x32_bf16 v[74:77], v[146:149], v[200:203], 0
	v_mfma_f32_16x16x32_bf16 v[78:81], v[130:133], v[200:203], 0
	s_cselect_b32 s16, s15, s19
	v_mfma_f32_16x16x32_bf16 v[126:129], v[142:145], v[174:177], v[126:129]
	s_mov_b32 m0, s35
	v_mfma_f32_16x16x32_bf16 v[122:125], v[150:153], v[174:177], v[122:125]
	s_mov_b32 s42, s6
	v_mfma_f32_16x16x32_bf16 v[106:109], v[150:153], v[182:185], v[106:109]
	s_mov_b32 s43, s7
	v_mfma_f32_16x16x32_bf16 v[110:113], v[142:145], v[182:185], v[110:113]
	s_sub_i32 s16, s16, s40
	v_mfma_f32_16x16x32_bf16 v[94:97], v[142:145], v[190:193], v[94:97]
	v_mfma_f32_16x16x32_bf16 v[90:93], v[150:153], v[190:193], v[90:93]
	v_mfma_f32_16x16x32_bf16 v[74:77], v[150:153], v[206:209], v[74:77]
	v_mfma_f32_16x16x32_bf16 v[78:81], v[142:145], v[206:209], v[78:81]
	v_mfma_f32_16x16x32_bf16 v[118:121], v[154:157], v[170:173], 0
	v_mfma_f32_16x16x32_bf16 v[114:117], v[162:165], v[170:173], 0
	v_mfma_f32_16x16x32_bf16 v[98:101], v[162:165], v[178:181], 0
	v_mfma_f32_16x16x32_bf16 v[102:105], v[154:157], v[178:181], 0
	v_mfma_f32_16x16x32_bf16 v[86:89], v[154:157], v[186:189], 0
	v_mfma_f32_16x16x32_bf16 v[82:85], v[162:165], v[186:189], 0
	v_mfma_f32_16x16x32_bf16 v[66:69], v[162:165], v[200:203], 0
	v_mfma_f32_16x16x32_bf16 v[70:73], v[154:157], v[200:203], 0
	v_mfma_f32_16x16x32_bf16 v[118:121], v[158:161], v[174:177], v[118:121]
	v_mfma_f32_16x16x32_bf16 v[114:117], v[166:169], v[174:177], v[114:117]
	v_mfma_f32_16x16x32_bf16 v[98:101], v[166:169], v[182:185], v[98:101]
	v_mfma_f32_16x16x32_bf16 v[102:105], v[158:161], v[182:185], v[102:105]
	v_mfma_f32_16x16x32_bf16 v[86:89], v[158:161], v[190:193], v[86:89]
	v_mfma_f32_16x16x32_bf16 v[82:85], v[166:169], v[190:193], v[82:85]
	v_mfma_f32_16x16x32_bf16 v[66:69], v[166:169], v[206:209], v[66:69]
	v_mfma_f32_16x16x32_bf16 v[70:73], v[158:161], v[206:209], v[70:73]
	s_barrier
	s_setprio 0
	ds_read_b128 v[170:173], v140 offset:16384
	ds_read_b128 v[174:177], v140 offset:17408
	ds_read_b128 v[178:181], v140 offset:18432
	ds_read_b128 v[182:185], v140 offset:19456
	ds_read_b128 v[186:189], v140 offset:20480
	ds_read_b128 v[190:193], v140 offset:21504
	ds_read_b128 v[200:203], v140 offset:22528
	ds_read_b128 v[206:209], v140 offset:23552
	buffer_load_dwordx4 v134, s[40:43], s16 offen lds
	s_mov_b32 m0, s44
	s_add_i32 s74, s16, 0x80000
	buffer_load_dwordx4 v136, s[40:43], s16 offen lds
	s_mov_b32 m0, s45
	s_sub_i32 s17, s17, s4
	buffer_load_dwordx4 v134, s[40:43], s74 offen lds
	s_mov_b32 m0, s46
	s_nop 0
	buffer_load_dwordx4 v136, s[40:43], s74 offen lds
	s_mov_b32 m0, s34
	s_nop 0
	buffer_load_dwordx4 v0, s[4:7], s17 offen lds
	s_waitcnt vmcnt(7) lgkmcnt(0)
	s_setprio 1
	s_barrier
; #define PG8_STAGE(bufoff, gbase, voff) do { const int so_ = (int)(unsigned)((const char*)(gbase) - base_##voff); _Pragma("unroll") for (int _i = 0; _i < 2; ++_i) \
;         __builtin_amdgcn_raw_ptr_buffer_load_lds(rs_##voff, (PG8_LAS unsigned*)(lds + (bufoff) + ldsw + _i * 8192), 16, (int)(voff)[_i], so_, 0, 0); } while (0)
; #define PG8_LDA(dst, b, h) do { _Pragma("unroll") for (int m = 0; m < 4; ++m) _Pragma("unroll") for (int k = 0; k < 2; ++k) dst[m][k] = *(const PG8_LAS bf16x8*)(lds + PG8_SA(b, h) + aoff + m * 2048 + k * 1024); } while (0)
; #define PG8_LDB(dst, b, h) do { _Pragma("unroll") for (int n = 0; n < 2; ++n) _Pragma("unroll") for (int k = 0; k < 2; ++k) dst[n][k] = *(const PG8_LAS bf16x8*)(lds + PG8_SB(b, h) + boff + n * 2048 + k * 1024); } while (0)
; #define PG8_MMA(ai, bj, At, Bt) do { __builtin_amdgcn_s_setprio(1); _Pragma("unroll") for (int m = 0; m < 4; ++m) _Pragma("unroll") for (int n = 0; n < 2; ++n) _Pragma("unroll") for (int k = 0; k < 2; ++k) \
;         acc[ai][bj][m][n] = __builtin_amdgcn_mfma_f32_16x16x32_bf16(Bt[n][k], At[m][k], acc[ai][bj][m][n], 0, 0, 0); __builtin_amdgcn_s_setprio(0); } while (0)
; #define PG8_WAIT_V(n) asm volatile("s_waitcnt vmcnt(" #n ")" ::: "memory")
; #define PG8_WAIT_L(n) asm volatile("s_waitcnt lgkmcnt(" #n ")" ::: "memory")
; #define PG8_BAR __builtin_amdgcn_s_barrier()
; #define PG8_SCHED __builtin_amdgcn_sched_barrier(0)
; template <class Epi, class Sched, bool ALIGN_EPI = false, bool SP2 = false>
; __device__ __forceinline__ void gemm_phase(PG8_LAS unsigned char* lds, const Gemm g, const Sched& S, const Epi& E, int tid_in) {
;     ...
;             PG8_LDA(At, 0, 1); PG8_STAGE(PG8_SB(0, 0), b2, voffB); PG8_STAGE(PG8_SB(0, 1), b2 + hstepB, voffB); PG8_STAGE(PG8_SA(0, 0), a2, voffA);
;             PG8_WAIT_V(8); PG8_WAIT_L(0); PG8_BAR; PG8_MMA(1, 0, At, B0); PG8_MMA(1, 1, At, B1); PG8_BAR; PG8_SCHED;
;             PG8_LDB(B0, 1, 0); PG8_LDB(B1, 1, 1); PG8_SCHED; PG8_LDA(At, 1, 0); PG8_STAGE(PG8_SA(0, 1), a2 + hstepA, voffA);
;             PG8_WAIT_V(8); PG8_WAIT_L(0); PG8_BAR; PG8_MMA(0, 0, At, B0); PG8_MMA(0, 1, At, B1); PG8_BAR; PG8_SCHED;
	v_mfma_f32_16x16x32_bf16 v[62:65], v[130:133], v[170:173], 0
	v_mfma_f32_16x16x32_bf16 v[58:61], v[146:149], v[170:173], 0
	v_mfma_f32_16x16x32_bf16 v[42:45], v[146:149], v[178:181], 0
	v_mfma_f32_16x16x32_bf16 v[46:49], v[130:133], v[178:181], 0
	v_mfma_f32_16x16x32_bf16 v[30:33], v[130:133], v[186:189], 0
	v_mfma_f32_16x16x32_bf16 v[26:29], v[146:149], v[186:189], 0
	v_mfma_f32_16x16x32_bf16 v[10:13], v[146:149], v[200:203], 0
	v_mfma_f32_16x16x32_bf16 v[14:17], v[130:133], v[200:203], 0
	v_mfma_f32_16x16x32_bf16 v[62:65], v[142:145], v[174:177], v[62:65]
	v_mfma_f32_16x16x32_bf16 v[58:61], v[150:153], v[174:177], v[58:61]
	v_mfma_f32_16x16x32_bf16 v[42:45], v[150:153], v[182:185], v[42:45]
	v_mfma_f32_16x16x32_bf16 v[46:49], v[142:145], v[182:185], v[46:49]
	v_mfma_f32_16x16x32_bf16 v[30:33], v[142:145], v[190:193], v[30:33]
	v_mfma_f32_16x16x32_bf16 v[26:29], v[150:153], v[190:193], v[26:29]
	v_mfma_f32_16x16x32_bf16 v[10:13], v[150:153], v[206:209], v[10:13]
	v_mfma_f32_16x16x32_bf16 v[14:17], v[142:145], v[206:209], v[14:17]
	v_mfma_f32_16x16x32_bf16 v[54:57], v[154:157], v[170:173], 0
	v_mfma_f32_16x16x32_bf16 v[50:53], v[162:165], v[170:173], 0
	v_mfma_f32_16x16x32_bf16 v[34:37], v[162:165], v[178:181], 0
	v_mfma_f32_16x16x32_bf16 v[38:41], v[154:157], v[178:181], 0
	v_mfma_f32_16x16x32_bf16 v[22:25], v[154:157], v[186:189], 0
	v_mfma_f32_16x16x32_bf16 v[18:21], v[162:165], v[186:189], 0
	v_mfma_f32_16x16x32_bf16 v[2:5], v[162:165], v[200:203], 0
	v_mfma_f32_16x16x32_bf16 v[6:9], v[154:157], v[200:203], 0
	v_add_u32_e32 v141, 0x18000, v139
	v_mfma_f32_16x16x32_bf16 v[54:57], v[158:161], v[174:177], v[54:57]
	v_mfma_f32_16x16x32_bf16 v[50:53], v[166:169], v[174:177], v[50:53]
	v_mfma_f32_16x16x32_bf16 v[34:37], v[166:169], v[182:185], v[34:37]
	v_mfma_f32_16x16x32_bf16 v[38:41], v[158:161], v[182:185], v[38:41]
	v_mfma_f32_16x16x32_bf16 v[22:25], v[158:161], v[190:193], v[22:25]
	v_mfma_f32_16x16x32_bf16 v[18:21], v[166:169], v[190:193], v[18:21]
	v_mfma_f32_16x16x32_bf16 v[2:5], v[166:169], v[206:209], v[2:5]
	v_mfma_f32_16x16x32_bf16 v[6:9], v[158:161], v[206:209], v[6:9]
	s_barrier
	s_setprio 0
	ds_read_b128 v[130:133], v141
	ds_read_b128 v[142:145], v141 offset:1024
	ds_read_b128 v[146:149], v141 offset:2048
	ds_read_b128 v[150:153], v141 offset:3072
	v_add_u32_e32 v141, 0x1c000, v139
	ds_read_b128 v[154:157], v141
	ds_read_b128 v[158:161], v141 offset:1024
	ds_read_b128 v[162:165], v141 offset:2048
	ds_read_b128 v[166:169], v141 offset:3072
	s_add_i32 s74, s17, 0x80000
	s_mov_b32 m0, s48
	ds_read_b128 v[170:173], v140 offset:32768
	ds_read_b128 v[174:177], v140 offset:33792
	ds_read_b128 v[178:181], v140 offset:34816
	ds_read_b128 v[182:185], v140 offset:35840
	ds_read_b128 v[186:189], v140 offset:36864
	ds_read_b128 v[190:193], v140 offset:37888
	ds_read_b128 v[200:203], v140 offset:38912
	ds_read_b128 v[206:209], v140 offset:39936
	s_mov_b32 m0, s47
	s_nop 0
	buffer_load_dwordx4 v135, s[4:7], s17 offen lds
	s_mov_b32 m0, s48
	s_nop 0
	buffer_load_dwordx4 v0, s[4:7], s74 offen lds
	s_mov_b32 m0, s49
	s_nop 0
	buffer_load_dwordx4 v135, s[4:7], s74 offen lds
	s_waitcnt vmcnt(8) lgkmcnt(0)
	s_setprio 1
	s_barrier
	v_mfma_f32_16x16x32_bf16 v[126:129], v[130:133], v[170:173], v[126:129]
	v_mfma_f32_16x16x32_bf16 v[122:125], v[146:149], v[170:173], v[122:125]
	v_mfma_f32_16x16x32_bf16 v[106:109], v[146:149], v[178:181], v[106:109]
	v_mfma_f32_16x16x32_bf16 v[110:113], v[130:133], v[178:181], v[110:113]
	v_mfma_f32_16x16x32_bf16 v[94:97], v[130:133], v[186:189], v[94:97]
	v_mfma_f32_16x16x32_bf16 v[90:93], v[146:149], v[186:189], v[90:93]
	v_mfma_f32_16x16x32_bf16 v[74:77], v[146:149], v[200:203], v[74:77]
	v_mfma_f32_16x16x32_bf16 v[78:81], v[130:133], v[200:203], v[78:81]
	s_mov_b32 m0, s53
	v_mfma_f32_16x16x32_bf16 v[70:73], v[154:157], v[200:203], v[70:73]
	s_add_i32 s74, s16, 0x80
	v_mfma_f32_16x16x32_bf16 v[66:69], v[162:165], v[200:203], v[66:69]
	v_mfma_f32_16x16x32_bf16 v[82:85], v[162:165], v[186:189], v[82:85]
	v_mfma_f32_16x16x32_bf16 v[86:89], v[154:157], v[186:189], v[86:89]
	v_mfma_f32_16x16x32_bf16 v[102:105], v[154:157], v[178:181], v[102:105]
	v_mfma_f32_16x16x32_bf16 v[98:101], v[162:165], v[178:181], v[98:101]
	v_mfma_f32_16x16x32_bf16 v[114:117], v[162:165], v[170:173], v[114:117]
	v_mfma_f32_16x16x32_bf16 v[118:121], v[154:157], v[170:173], v[118:121]
	v_mfma_f32_16x16x32_bf16 v[126:129], v[142:145], v[174:177], v[126:129]
	v_mfma_f32_16x16x32_bf16 v[122:125], v[150:153], v[174:177], v[122:125]
	v_mfma_f32_16x16x32_bf16 v[106:109], v[150:153], v[182:185], v[106:109]
	v_mfma_f32_16x16x32_bf16 v[110:113], v[142:145], v[182:185], v[110:113]
	v_mfma_f32_16x16x32_bf16 v[94:97], v[142:145], v[190:193], v[94:97]
	v_mfma_f32_16x16x32_bf16 v[90:93], v[150:153], v[190:193], v[90:93]
	v_mfma_f32_16x16x32_bf16 v[74:77], v[150:153], v[206:209], v[74:77]
	v_mfma_f32_16x16x32_bf16 v[78:81], v[142:145], v[206:209], v[78:81]
	v_mfma_f32_16x16x32_bf16 v[70:73], v[158:161], v[206:209], v[70:73]
	v_mfma_f32_16x16x32_bf16 v[66:69], v[166:169], v[206:209], v[66:69]
	v_mfma_f32_16x16x32_bf16 v[82:85], v[166:169], v[190:193], v[82:85]
	v_mfma_f32_16x16x32_bf16 v[86:89], v[158:161], v[190:193], v[86:89]
	v_mfma_f32_16x16x32_bf16 v[102:105], v[158:161], v[182:185], v[102:105]
	v_mfma_f32_16x16x32_bf16 v[98:101], v[166:169], v[182:185], v[98:101]
	v_mfma_f32_16x16x32_bf16 v[114:117], v[166:169], v[174:177], v[114:117]
	v_mfma_f32_16x16x32_bf16 v[118:121], v[158:161], v[174:177], v[118:121]
	s_barrier
; #define PG8_STAGE(bufoff, gbase, voff) do { const int so_ = (int)(unsigned)((const char*)(gbase) - base_##voff); _Pragma("unroll") for (int _i = 0; _i < 2; ++_i) \
;         __builtin_amdgcn_raw_ptr_buffer_load_lds(rs_##voff, (PG8_LAS unsigned*)(lds + (bufoff) + ldsw + _i * 8192), 16, (int)(voff)[_i], so_, 0, 0); } while (0)
; #define PG8_LDA(dst, b, h) do { _Pragma("unroll") for (int m = 0; m < 4; ++m) _Pragma("unroll") for (int k = 0; k < 2; ++k) dst[m][k] = *(const PG8_LAS bf16x8*)(lds + PG8_SA(b, h) + aoff + m * 2048 + k * 1024); } while (0)
; #define PG8_LDB(dst, b, h) do { _Pragma("unroll") for (int n = 0; n < 2; ++n) _Pragma("unroll") for (int k = 0; k < 2; ++k) dst[n][k] = *(const PG8_LAS bf16x8*)(lds + PG8_SB(b, h) + boff + n * 2048 + k * 1024); } while (0)
; #define PG8_MMA(ai, bj, At, Bt) do { __builtin_amdgcn_s_setprio(1); _Pragma("unroll") for (int m = 0; m < 4; ++m) _Pragma("unroll") for (int n = 0; n < 2; ++n) _Pragma("unroll") for (int k = 0; k < 2; ++k) \
;         acc[ai][bj][m][n] = __builtin_amdgcn_mfma_f32_16x16x32_bf16(Bt[n][k], At[m][k], acc[ai][bj][m][n], 0, 0, 0); __builtin_amdgcn_s_setprio(0); } while (0)
; template <class Epi, class Sched, bool ALIGN_EPI = false, bool SP2 = false>
; __device__ __forceinline__ void gemm_phase(PG8_LAS unsigned char* lds, const Gemm g, const Sched& S, const Epi& E, int tid_in) {
;     ...
;             PG8_LDB(B0, 0, 0); PG8_LDB(B1, 0, 1); PG8_SCHED; PG8_LDA(At, 0, 0); PG8_STAGE(PG8_SA(1, 1), a1 + hstepA, voffA);
;             PG8_WAIT_V(8); PG8_WAIT_L(0); PG8_BAR; PG8_MMA(0, 0, At, B0); PG8_MMA(0, 1, At, B1); PG8_BAR; PG8_SCHED;
;             PG8_LDA(At, 0, 1); PG8_STAGE(PG8_SB(0, 0), b2, voffB); PG8_STAGE(PG8_SB(0, 1), b2 + hstepB, voffB); PG8_STAGE(PG8_SA(0, 0), a2, voffA);
;             PG8_WAIT_V(8); PG8_WAIT_L(0); PG8_BAR; PG8_MMA(1, 0, At, B0); PG8_MMA(1, 1, At, B1); PG8_BAR; PG8_SCHED;
;             PG8_LDB(B0, 1, 0); PG8_LDB(B1, 1, 1); PG8_SCHED; PG8_LDA(At, 1, 0); PG8_STAGE(PG8_SA(0, 1), a2 + hstepA, voffA);
;             PG8_WAIT_V(8); PG8_WAIT_L(0); PG8_BAR; PG8_MMA(0, 0, At, B0); PG8_MMA(0, 1, At, B1); PG8_BAR; PG8_SCHED;
;             PG8_LDA(At, 1, 1); PG8_STAGE(PG8_SB(1, 0), b3, voffB); PG8_STAGE(PG8_SB(1, 1), b3 + hstepB, voffB); PG8_STAGE(PG8_SA(1, 0), a3, voffA);
;             PG8_WAIT_V(8); PG8_WAIT_L(0); PG8_BAR; PG8_MMA(1, 0, At, B0); PG8_MMA(1, 1, At, B1); PG8_BAR; PG8_SCHED;
	s_setprio 0
	ds_read_b128 v[170:173], v140 offset:49152
	ds_read_b128 v[174:177], v140 offset:50176
	ds_read_b128 v[178:181], v140 offset:51200
	ds_read_b128 v[182:185], v140 offset:52224
	ds_read_b128 v[186:189], v140 offset:53248
	ds_read_b128 v[190:193], v140 offset:54272
	ds_read_b128 v[200:203], v140 offset:55296
	ds_read_b128 v[206:209], v140 offset:56320
	buffer_load_dwordx4 v134, s[40:43], s74 offen lds
	s_mov_b32 m0, s60
	s_add_i32 s16, s16, 0x80080
	buffer_load_dwordx4 v136, s[40:43], s74 offen lds
	s_mov_b32 m0, s63
	s_addk_i32 s17, 0x80
	buffer_load_dwordx4 v134, s[40:43], s16 offen lds
	s_mov_b32 m0, s66
	s_nop 0
	buffer_load_dwordx4 v136, s[40:43], s16 offen lds
	s_mov_b32 m0, s61
	s_nop 0
	buffer_load_dwordx4 v0, s[4:7], s17 offen lds
	s_waitcnt vmcnt(7) lgkmcnt(0)
	s_setprio 1
	s_barrier
	v_mfma_f32_16x16x32_bf16 v[62:65], v[130:133], v[170:173], v[62:65]
	v_mfma_f32_16x16x32_bf16 v[58:61], v[146:149], v[170:173], v[58:61]
	v_mfma_f32_16x16x32_bf16 v[42:45], v[146:149], v[178:181], v[42:45]
	v_mfma_f32_16x16x32_bf16 v[46:49], v[130:133], v[178:181], v[46:49]
	v_mfma_f32_16x16x32_bf16 v[30:33], v[130:133], v[186:189], v[30:33]
	v_mfma_f32_16x16x32_bf16 v[26:29], v[146:149], v[186:189], v[26:29]
	v_mfma_f32_16x16x32_bf16 v[10:13], v[146:149], v[200:203], v[10:13]
	v_mfma_f32_16x16x32_bf16 v[14:17], v[130:133], v[200:203], v[14:17]
	s_add_i32 s73, s73, 2
	v_mfma_f32_16x16x32_bf16 v[6:9], v[154:157], v[200:203], v[6:9]
	s_add_u32 s19, s19, 0x100
	v_mfma_f32_16x16x32_bf16 v[2:5], v[162:165], v[200:203], v[2:5]
	s_addc_u32 s21, s21, 0
	v_mfma_f32_16x16x32_bf16 v[18:21], v[162:165], v[186:189], v[18:21]
	s_cmp_gt_u32 s73, 29
	v_mfma_f32_16x16x32_bf16 v[22:25], v[154:157], v[186:189], v[22:25]
	s_mov_b64 s[16:17], s[38:39]
	v_mfma_f32_16x16x32_bf16 v[38:41], v[154:157], v[178:181], v[38:41]
	v_mfma_f32_16x16x32_bf16 v[34:37], v[162:165], v[178:181], v[34:37]
	v_mfma_f32_16x16x32_bf16 v[50:53], v[162:165], v[170:173], v[50:53]
	v_mfma_f32_16x16x32_bf16 v[54:57], v[154:157], v[170:173], v[54:57]
	v_mfma_f32_16x16x32_bf16 v[62:65], v[142:145], v[174:177], v[62:65]
	v_mfma_f32_16x16x32_bf16 v[58:61], v[150:153], v[174:177], v[58:61]
	v_mfma_f32_16x16x32_bf16 v[42:45], v[150:153], v[182:185], v[42:45]
	v_mfma_f32_16x16x32_bf16 v[46:49], v[142:145], v[182:185], v[46:49]
	v_mfma_f32_16x16x32_bf16 v[30:33], v[142:145], v[190:193], v[30:33]
	v_mfma_f32_16x16x32_bf16 v[26:29], v[150:153], v[190:193], v[26:29]
	v_mfma_f32_16x16x32_bf16 v[10:13], v[150:153], v[206:209], v[10:13]
	v_mfma_f32_16x16x32_bf16 v[14:17], v[142:145], v[206:209], v[14:17]
	v_mfma_f32_16x16x32_bf16 v[6:9], v[158:161], v[206:209], v[6:9]
	v_mfma_f32_16x16x32_bf16 v[2:5], v[166:169], v[206:209], v[2:5]
	v_mfma_f32_16x16x32_bf16 v[18:21], v[166:169], v[190:193], v[18:21]
	v_mfma_f32_16x16x32_bf16 v[22:25], v[158:161], v[190:193], v[22:25]
	v_mfma_f32_16x16x32_bf16 v[38:41], v[158:161], v[182:185], v[38:41]
	v_mfma_f32_16x16x32_bf16 v[34:37], v[166:169], v[182:185], v[34:37]
	v_mfma_f32_16x16x32_bf16 v[50:53], v[166:169], v[174:177], v[50:53]
	v_mfma_f32_16x16x32_bf16 v[54:57], v[158:161], v[174:177], v[54:57]
	s_barrier
	s_setprio 0
.LBB0_1514:
	v_add_u32_e32 v141, 0x10000, v139
	ds_read_b128 v[130:133], v141
	ds_read_b128 v[142:145], v141 offset:1024
	ds_read_b128 v[146:149], v141 offset:2048
	ds_read_b128 v[150:153], v141 offset:3072
	v_add_u32_e32 v141, 0x14000, v139
	ds_read_b128 v[154:157], v141
	ds_read_b128 v[158:161], v141 offset:1024
	ds_read_b128 v[162:165], v141 offset:2048
	ds_read_b128 v[166:169], v141 offset:3072
	s_add_u32 s38, s16, 0x100
	s_addc_u32 s39, s17, 0
	s_sub_i32 s16, s16, s4
	s_add_i32 s16, s16, 0x80080
	s_sub_i32 s74, s16, 0x80000
	s_cmp_eq_u32 s73, 28
	s_cselect_b32 s17, s18, s38
	s_mov_b32 m0, s67
	ds_read_b128 v[170:173], v140
	ds_read_b128 v[174:177], v140 offset:1024
	ds_read_b128 v[178:181], v140 offset:2048
	ds_read_b128 v[182:185], v140 offset:3072
	ds_read_b128 v[186:189], v140 offset:4096
	ds_read_b128 v[190:193], v140 offset:5120
	ds_read_b128 v[200:203], v140 offset:6144
	ds_read_b128 v[206:209], v140 offset:7168
	s_mov_b32 m0, s62
	s_nop 0
	buffer_load_dwordx4 v135, s[4:7], s74 offen lds
	s_mov_b32 m0, s67
	s_nop 0
	buffer_load_dwordx4 v0, s[4:7], s16 offen lds
	s_mov_b32 m0, s68
	s_nop 0
	buffer_load_dwordx4 v135, s[4:7], s16 offen lds
	s_waitcnt vmcnt(8) lgkmcnt(0)
	s_setprio 1
	s_barrier
	v_mfma_f32_16x16x32_bf16 v[126:129], v[130:133], v[170:173], v[126:129]
	v_mfma_f32_16x16x32_bf16 v[122:125], v[146:149], v[170:173], v[122:125]
	v_mfma_f32_16x16x32_bf16 v[106:109], v[146:149], v[178:181], v[106:109]
	v_mfma_f32_16x16x32_bf16 v[110:113], v[130:133], v[178:181], v[110:113]
	v_mfma_f32_16x16x32_bf16 v[94:97], v[130:133], v[186:189], v[94:97]
	v_mfma_f32_16x16x32_bf16 v[90:93], v[146:149], v[186:189], v[90:93]
	v_mfma_f32_16x16x32_bf16 v[74:77], v[146:149], v[200:203], v[74:77]
	v_mfma_f32_16x16x32_bf16 v[78:81], v[130:133], v[200:203], v[78:81]
	s_cselect_b32 s16, s15, s19
	v_mfma_f32_16x16x32_bf16 v[70:73], v[154:157], v[200:203], v[70:73]
	s_mov_b32 m0, s35
	v_mfma_f32_16x16x32_bf16 v[66:69], v[162:165], v[200:203], v[66:69]
	s_mov_b32 s42, s6
	v_mfma_f32_16x16x32_bf16 v[82:85], v[162:165], v[186:189], v[82:85]
	s_mov_b32 s43, s7
	v_mfma_f32_16x16x32_bf16 v[86:89], v[154:157], v[186:189], v[86:89]
	s_sub_i32 s16, s16, s40
	v_mfma_f32_16x16x32_bf16 v[102:105], v[154:157], v[178:181], v[102:105]
	v_mfma_f32_16x16x32_bf16 v[98:101], v[162:165], v[178:181], v[98:101]
	v_mfma_f32_16x16x32_bf16 v[114:117], v[162:165], v[170:173], v[114:117]
	v_mfma_f32_16x16x32_bf16 v[118:121], v[154:157], v[170:173], v[118:121]
	v_mfma_f32_16x16x32_bf16 v[126:129], v[142:145], v[174:177], v[126:129]
	v_mfma_f32_16x16x32_bf16 v[122:125], v[150:153], v[174:177], v[122:125]
	v_mfma_f32_16x16x32_bf16 v[106:109], v[150:153], v[182:185], v[106:109]
	v_mfma_f32_16x16x32_bf16 v[110:113], v[142:145], v[182:185], v[110:113]
	v_mfma_f32_16x16x32_bf16 v[94:97], v[142:145], v[190:193], v[94:97]
	v_mfma_f32_16x16x32_bf16 v[90:93], v[150:153], v[190:193], v[90:93]
	v_mfma_f32_16x16x32_bf16 v[74:77], v[150:153], v[206:209], v[74:77]
	v_mfma_f32_16x16x32_bf16 v[78:81], v[142:145], v[206:209], v[78:81]
	v_mfma_f32_16x16x32_bf16 v[70:73], v[158:161], v[206:209], v[70:73]
	v_mfma_f32_16x16x32_bf16 v[66:69], v[166:169], v[206:209], v[66:69]
	v_mfma_f32_16x16x32_bf16 v[82:85], v[166:169], v[190:193], v[82:85]
	v_mfma_f32_16x16x32_bf16 v[86:89], v[158:161], v[190:193], v[86:89]
	v_mfma_f32_16x16x32_bf16 v[102:105], v[158:161], v[182:185], v[102:105]
	v_mfma_f32_16x16x32_bf16 v[98:101], v[166:169], v[182:185], v[98:101]
	v_mfma_f32_16x16x32_bf16 v[114:117], v[166:169], v[174:177], v[114:117]
	v_mfma_f32_16x16x32_bf16 v[118:121], v[158:161], v[174:177], v[118:121]
	s_barrier
; #define PG8_STAGE(bufoff, gbase, voff) do { const int so_ = (int)(unsigned)((const char*)(gbase) - base_##voff); _Pragma("unroll") for (int _i = 0; _i < 2; ++_i) \
;         __builtin_amdgcn_raw_ptr_buffer_load_lds(rs_##voff, (PG8_LAS unsigned*)(lds + (bufoff) + ldsw + _i * 8192), 16, (int)(voff)[_i], so_, 0, 0); } while (0)
; #define PG8_LDA(dst, b, h) do { _Pragma("unroll") for (int m = 0; m < 4; ++m) _Pragma("unroll") for (int k = 0; k < 2; ++k) dst[m][k] = *(const PG8_LAS bf16x8*)(lds + PG8_SA(b, h) + aoff + m * 2048 + k * 1024); } while (0)
; #define PG8_LDB(dst, b, h) do { _Pragma("unroll") for (int n = 0; n < 2; ++n) _Pragma("unroll") for (int k = 0; k < 2; ++k) dst[n][k] = *(const PG8_LAS bf16x8*)(lds + PG8_SB(b, h) + boff + n * 2048 + k * 1024); } while (0)
; #define PG8_MMA(ai, bj, At, Bt) do { __builtin_amdgcn_s_setprio(1); _Pragma("unroll") for (int m = 0; m < 4; ++m) _Pragma("unroll") for (int n = 0; n < 2; ++n) _Pragma("unroll") for (int k = 0; k < 2; ++k) \
;         acc[ai][bj][m][n] = __builtin_amdgcn_mfma_f32_16x16x32_bf16(Bt[n][k], At[m][k], acc[ai][bj][m][n], 0, 0, 0); __builtin_amdgcn_s_setprio(0); } while (0)
; #define PG8_WAIT_V(n) asm volatile("s_waitcnt vmcnt(" #n ")" ::: "memory")
; #define PG8_WAIT_L(n) asm volatile("s_waitcnt lgkmcnt(" #n ")" ::: "memory")
; #define PG8_BAR __builtin_amdgcn_s_barrier()
; #define PG8_SCHED __builtin_amdgcn_sched_barrier(0)
; template <class Epi, class Sched, bool ALIGN_EPI = false, bool SP2 = false>
; __device__ __forceinline__ void gemm_phase(PG8_LAS unsigned char* lds, const Gemm g, const Sched& S, const Epi& E, int tid_in) {
;     ...
;             PG8_LDA(At, 0, 1); PG8_STAGE(PG8_SB(0, 0), b2, voffB); PG8_STAGE(PG8_SB(0, 1), b2 + hstepB, voffB); PG8_STAGE(PG8_SA(0, 0), a2, voffA);
;             PG8_WAIT_V(8); PG8_WAIT_L(0); PG8_BAR; PG8_MMA(1, 0, At, B0); PG8_MMA(1, 1, At, B1); PG8_BAR; PG8_SCHED;
;             PG8_LDB(B0, 1, 0); PG8_LDB(B1, 1, 1); PG8_SCHED; PG8_LDA(At, 1, 0); PG8_STAGE(PG8_SA(0, 1), a2 + hstepA, voffA);
;             PG8_WAIT_V(8); PG8_WAIT_L(0); PG8_BAR; PG8_MMA(0, 0, At, B0); PG8_MMA(0, 1, At, B1); PG8_BAR; PG8_SCHED;
	s_setprio 0
	ds_read_b128 v[170:173], v140 offset:16384
	ds_read_b128 v[174:177], v140 offset:17408
	ds_read_b128 v[178:181], v140 offset:18432
	ds_read_b128 v[182:185], v140 offset:19456
	ds_read_b128 v[186:189], v140 offset:20480
	ds_read_b128 v[190:193], v140 offset:21504
	ds_read_b128 v[200:203], v140 offset:22528
	ds_read_b128 v[206:209], v140 offset:23552
	buffer_load_dwordx4 v134, s[40:43], s16 offen lds
	s_mov_b32 m0, s44
	s_add_i32 s74, s16, 0x80000
	buffer_load_dwordx4 v136, s[40:43], s16 offen lds
	s_mov_b32 m0, s45
	s_sub_i32 s17, s17, s4
	buffer_load_dwordx4 v134, s[40:43], s74 offen lds
	s_mov_b32 m0, s46
	s_nop 0
	buffer_load_dwordx4 v136, s[40:43], s74 offen lds
	s_mov_b32 m0, s34
	s_nop 0
	buffer_load_dwordx4 v0, s[4:7], s17 offen lds
	s_waitcnt vmcnt(7) lgkmcnt(0)
	s_setprio 1
	s_barrier
	v_mfma_f32_16x16x32_bf16 v[62:65], v[130:133], v[170:173], v[62:65]
	v_mfma_f32_16x16x32_bf16 v[58:61], v[146:149], v[170:173], v[58:61]
	v_mfma_f32_16x16x32_bf16 v[42:45], v[146:149], v[178:181], v[42:45]
	v_mfma_f32_16x16x32_bf16 v[46:49], v[130:133], v[178:181], v[46:49]
	v_mfma_f32_16x16x32_bf16 v[30:33], v[130:133], v[186:189], v[30:33]
	v_mfma_f32_16x16x32_bf16 v[26:29], v[146:149], v[186:189], v[26:29]
	v_mfma_f32_16x16x32_bf16 v[10:13], v[146:149], v[200:203], v[10:13]
	v_mfma_f32_16x16x32_bf16 v[14:17], v[130:133], v[200:203], v[14:17]
	v_mfma_f32_16x16x32_bf16 v[6:9], v[154:157], v[200:203], v[6:9]
	v_mfma_f32_16x16x32_bf16 v[2:5], v[162:165], v[200:203], v[2:5]
	v_mfma_f32_16x16x32_bf16 v[18:21], v[162:165], v[186:189], v[18:21]
	v_mfma_f32_16x16x32_bf16 v[22:25], v[154:157], v[186:189], v[22:25]
	v_mfma_f32_16x16x32_bf16 v[38:41], v[154:157], v[178:181], v[38:41]
	v_mfma_f32_16x16x32_bf16 v[34:37], v[162:165], v[178:181], v[34:37]
	v_mfma_f32_16x16x32_bf16 v[50:53], v[162:165], v[170:173], v[50:53]
	v_mfma_f32_16x16x32_bf16 v[54:57], v[154:157], v[170:173], v[54:57]
	v_mfma_f32_16x16x32_bf16 v[62:65], v[142:145], v[174:177], v[62:65]
	v_mfma_f32_16x16x32_bf16 v[58:61], v[150:153], v[174:177], v[58:61]
	v_mfma_f32_16x16x32_bf16 v[42:45], v[150:153], v[182:185], v[42:45]
	v_mfma_f32_16x16x32_bf16 v[46:49], v[142:145], v[182:185], v[46:49]
	v_mfma_f32_16x16x32_bf16 v[30:33], v[142:145], v[190:193], v[30:33]
	v_mfma_f32_16x16x32_bf16 v[26:29], v[150:153], v[190:193], v[26:29]
	v_mfma_f32_16x16x32_bf16 v[10:13], v[150:153], v[206:209], v[10:13]
	v_mfma_f32_16x16x32_bf16 v[14:17], v[142:145], v[206:209], v[14:17]
	v_add_u32_e32 v141, 0x18000, v139
	v_mfma_f32_16x16x32_bf16 v[6:9], v[158:161], v[206:209], v[6:9]
	v_mfma_f32_16x16x32_bf16 v[2:5], v[166:169], v[206:209], v[2:5]
	v_mfma_f32_16x16x32_bf16 v[18:21], v[166:169], v[190:193], v[18:21]
	v_mfma_f32_16x16x32_bf16 v[22:25], v[158:161], v[190:193], v[22:25]
	v_mfma_f32_16x16x32_bf16 v[38:41], v[158:161], v[182:185], v[38:41]
	v_mfma_f32_16x16x32_bf16 v[34:37], v[166:169], v[182:185], v[34:37]
	v_mfma_f32_16x16x32_bf16 v[50:53], v[166:169], v[174:177], v[50:53]
	v_mfma_f32_16x16x32_bf16 v[54:57], v[158:161], v[174:177], v[54:57]
	s_barrier
	s_setprio 0
	ds_read_b128 v[130:133], v141
	ds_read_b128 v[142:145], v141 offset:1024
	ds_read_b128 v[146:149], v141 offset:2048
	ds_read_b128 v[150:153], v141 offset:3072
	v_add_u32_e32 v141, 0x1c000, v139
	ds_read_b128 v[154:157], v141
	ds_read_b128 v[158:161], v141 offset:1024
	ds_read_b128 v[162:165], v141 offset:2048
	ds_read_b128 v[166:169], v141 offset:3072
	s_add_i32 s74, s17, 0x80000
	s_mov_b32 m0, s48
	ds_read_b128 v[170:173], v140 offset:32768
	ds_read_b128 v[174:177], v140 offset:33792
	ds_read_b128 v[178:181], v140 offset:34816
	ds_read_b128 v[182:185], v140 offset:35840
	ds_read_b128 v[186:189], v140 offset:36864
	ds_read_b128 v[190:193], v140 offset:37888
	ds_read_b128 v[200:203], v140 offset:38912
	ds_read_b128 v[206:209], v140 offset:39936
	s_mov_b32 m0, s47
	s_nop 0
	buffer_load_dwordx4 v135, s[4:7], s17 offen lds
	s_mov_b32 m0, s48
	s_nop 0
	buffer_load_dwordx4 v0, s[4:7], s74 offen lds
	s_mov_b32 m0, s49
	s_nop 0
	buffer_load_dwordx4 v135, s[4:7], s74 offen lds
	s_waitcnt vmcnt(8) lgkmcnt(0)
	s_setprio 1
	s_barrier
; template <class Epi, class Sched, bool ALIGN_EPI = false, bool SP2 = false>
; __device__ __forceinline__ void gemm_phase(PG8_LAS unsigned char* lds, const Gemm g, const Sched& S, const Epi& E, int tid_in) {
;     ...
;             PG8_LDB(B0, 0, 0); PG8_LDB(B1, 0, 1); PG8_SCHED; PG8_LDA(At, 0, 0); PG8_STAGE(PG8_SA(1, 1), a1 + hstepA, voffA);
;             PG8_WAIT_V(8); PG8_WAIT_L(0); PG8_BAR; PG8_MMA(0, 0, At, B0); PG8_MMA(0, 1, At, B1); PG8_BAR; PG8_SCHED;
;             PG8_LDA(At, 0, 1); PG8_STAGE(PG8_SB(0, 0), b2, voffB); PG8_STAGE(PG8_SB(0, 1), b2 + hstepB, voffB); PG8_STAGE(PG8_SA(0, 0), a2, voffA);
;             PG8_WAIT_V(8); PG8_WAIT_L(0); PG8_BAR; PG8_MMA(1, 0, At, B0); PG8_MMA(1, 1, At, B1); PG8_BAR; PG8_SCHED;
;             PG8_LDB(B0, 1, 0); PG8_LDB(B1, 1, 1); PG8_SCHED; PG8_LDA(At, 1, 0); PG8_STAGE(PG8_SA(0, 1), a2 + hstepA, voffA);
;             PG8_WAIT_V(8); PG8_WAIT_L(0); PG8_BAR; PG8_MMA(0, 0, At, B0); PG8_MMA(0, 1, At, B1); PG8_BAR; PG8_SCHED;
;             PG8_LDA(At, 1, 1); PG8_STAGE(PG8_SB(1, 0), b3, voffB); PG8_STAGE(PG8_SB(1, 1), b3 + hstepB, voffB); PG8_STAGE(PG8_SA(1, 0), a3, voffA);
;             PG8_WAIT_V(8); PG8_WAIT_L(0); PG8_BAR; PG8_MMA(1, 0, At, B0); PG8_MMA(1, 1, At, B1); PG8_BAR; PG8_SCHED;
;             } else {
;             PG8_LDB(B0, 0, 0); PG8_SCHED; PG8_LDA(At, 0, 0); PG8_STAGE(PG8_SA(1, 1), a1 + hstepA, voffA);
;             PG8_WAIT_L(8); PG8_BAR; PG8_WAIT_L(0); PG8_MMA(0, 0, At, B0); PG8_BAR; PG8_SCHED;
;             PG8_LDB(B1, 0, 1); PG8_STAGE(PG8_SB(0, 0), b2, voffB);
;             PG8_BAR; PG8_WAIT_L(0); PG8_MMA(0, 1, At, B1); PG8_BAR;
;             PG8_LDA(At, 0, 1); PG8_STAGE(PG8_SA(0, 0), a2, voffA);
;             PG8_BAR; PG8_WAIT_L(0); PG8_MMA(1, 0, At, B0); PG8_BAR; PG8_SCHED;
;             PG8_STAGE(PG8_SB(0, 1), b2 + hstepB, voffB);
;             PG8_WAIT_V(6); PG8_BAR; PG8_MMA(1, 1, At, B1); PG8_BAR;
;             PG8_LDB(B0, 1, 0); PG8_SCHED; PG8_LDA(At, 1, 0); PG8_STAGE(PG8_SA(0, 1), a2 + hstepA, voffA);
;             PG8_WAIT_L(8); PG8_BAR; PG8_WAIT_L(0); PG8_MMA(0, 0, At, B0); PG8_BAR; PG8_SCHED;
;             PG8_LDB(B1, 1, 1); PG8_STAGE(PG8_SB(1, 0), b3, voffB);
;             PG8_BAR; PG8_WAIT_L(0); PG8_MMA(0, 1, At, B1); PG8_BAR;
;             PG8_LDA(At, 1, 1); PG8_STAGE(PG8_SA(1, 0), a3, voffA);
;             PG8_BAR; PG8_WAIT_L(0); PG8_MMA(1, 0, At, B0); PG8_BAR; PG8_SCHED;
	v_mfma_f32_16x16x32_bf16 v[126:129], v[130:133], v[170:173], v[126:129]
	v_mfma_f32_16x16x32_bf16 v[122:125], v[146:149], v[170:173], v[122:125]
	v_mfma_f32_16x16x32_bf16 v[106:109], v[146:149], v[178:181], v[106:109]
	v_mfma_f32_16x16x32_bf16 v[110:113], v[130:133], v[178:181], v[110:113]
	v_mfma_f32_16x16x32_bf16 v[94:97], v[130:133], v[186:189], v[94:97]
	v_mfma_f32_16x16x32_bf16 v[90:93], v[146:149], v[186:189], v[90:93]
	v_mfma_f32_16x16x32_bf16 v[74:77], v[146:149], v[200:203], v[74:77]
	v_mfma_f32_16x16x32_bf16 v[78:81], v[130:133], v[200:203], v[78:81]
	s_mov_b32 m0, s53
	v_mfma_f32_16x16x32_bf16 v[70:73], v[154:157], v[200:203], v[70:73]
	s_add_i32 s74, s16, 0x80
	v_mfma_f32_16x16x32_bf16 v[66:69], v[162:165], v[200:203], v[66:69]
	v_mfma_f32_16x16x32_bf16 v[82:85], v[162:165], v[186:189], v[82:85]
	v_mfma_f32_16x16x32_bf16 v[86:89], v[154:157], v[186:189], v[86:89]
	v_mfma_f32_16x16x32_bf16 v[102:105], v[154:157], v[178:181], v[102:105]
	v_mfma_f32_16x16x32_bf16 v[98:101], v[162:165], v[178:181], v[98:101]
	v_mfma_f32_16x16x32_bf16 v[114:117], v[162:165], v[170:173], v[114:117]
	v_mfma_f32_16x16x32_bf16 v[118:121], v[154:157], v[170:173], v[118:121]
	v_mfma_f32_16x16x32_bf16 v[126:129], v[142:145], v[174:177], v[126:129]
	v_mfma_f32_16x16x32_bf16 v[122:125], v[150:153], v[174:177], v[122:125]
	v_mfma_f32_16x16x32_bf16 v[106:109], v[150:153], v[182:185], v[106:109]
	v_mfma_f32_16x16x32_bf16 v[110:113], v[142:145], v[182:185], v[110:113]
	v_mfma_f32_16x16x32_bf16 v[94:97], v[142:145], v[190:193], v[94:97]
	v_mfma_f32_16x16x32_bf16 v[90:93], v[150:153], v[190:193], v[90:93]
	v_mfma_f32_16x16x32_bf16 v[74:77], v[150:153], v[206:209], v[74:77]
	v_mfma_f32_16x16x32_bf16 v[78:81], v[142:145], v[206:209], v[78:81]
	v_mfma_f32_16x16x32_bf16 v[70:73], v[158:161], v[206:209], v[70:73]
	v_mfma_f32_16x16x32_bf16 v[66:69], v[166:169], v[206:209], v[66:69]
	v_mfma_f32_16x16x32_bf16 v[82:85], v[166:169], v[190:193], v[82:85]
	v_mfma_f32_16x16x32_bf16 v[86:89], v[158:161], v[190:193], v[86:89]
	v_mfma_f32_16x16x32_bf16 v[102:105], v[158:161], v[182:185], v[102:105]
	v_mfma_f32_16x16x32_bf16 v[98:101], v[166:169], v[182:185], v[98:101]
	v_mfma_f32_16x16x32_bf16 v[114:117], v[166:169], v[174:177], v[114:117]
	v_mfma_f32_16x16x32_bf16 v[118:121], v[158:161], v[174:177], v[118:121]
	s_barrier
	s_setprio 0
	ds_read_b128 v[170:173], v140 offset:49152
	ds_read_b128 v[174:177], v140 offset:50176
	ds_read_b128 v[178:181], v140 offset:51200
	ds_read_b128 v[182:185], v140 offset:52224
	ds_read_b128 v[186:189], v140 offset:53248
	ds_read_b128 v[190:193], v140 offset:54272
	ds_read_b128 v[200:203], v140 offset:55296
	ds_read_b128 v[206:209], v140 offset:56320
	buffer_load_dwordx4 v134, s[40:43], s74 offen lds
	s_mov_b32 m0, s60
	s_add_i32 s16, s16, 0x80080
	buffer_load_dwordx4 v136, s[40:43], s74 offen lds
	s_mov_b32 m0, s63
	s_addk_i32 s17, 0x80
	buffer_load_dwordx4 v134, s[40:43], s16 offen lds
	s_mov_b32 m0, s66
	s_nop 0
	buffer_load_dwordx4 v136, s[40:43], s16 offen lds
	s_mov_b32 m0, s61
	s_nop 0
	buffer_load_dwordx4 v0, s[4:7], s17 offen lds
	s_waitcnt vmcnt(7) lgkmcnt(0)
	s_setprio 1
	s_barrier
	v_mfma_f32_16x16x32_bf16 v[62:65], v[130:133], v[170:173], v[62:65]
	v_mfma_f32_16x16x32_bf16 v[58:61], v[146:149], v[170:173], v[58:61]
	v_mfma_f32_16x16x32_bf16 v[42:45], v[146:149], v[178:181], v[42:45]
	v_mfma_f32_16x16x32_bf16 v[46:49], v[130:133], v[178:181], v[46:49]
	v_mfma_f32_16x16x32_bf16 v[30:33], v[130:133], v[186:189], v[30:33]
	v_mfma_f32_16x16x32_bf16 v[26:29], v[146:149], v[186:189], v[26:29]
	v_mfma_f32_16x16x32_bf16 v[10:13], v[146:149], v[200:203], v[10:13]
	v_mfma_f32_16x16x32_bf16 v[14:17], v[130:133], v[200:203], v[14:17]
	s_add_i32 s73, s73, 2
	v_mfma_f32_16x16x32_bf16 v[6:9], v[154:157], v[200:203], v[6:9]
	s_add_u32 s19, s19, 0x100
	v_mfma_f32_16x16x32_bf16 v[2:5], v[162:165], v[200:203], v[2:5]
	s_addc_u32 s21, s21, 0
	v_mfma_f32_16x16x32_bf16 v[18:21], v[162:165], v[186:189], v[18:21]
	s_cmp_gt_u32 s73, 29
	v_mfma_f32_16x16x32_bf16 v[22:25], v[154:157], v[186:189], v[22:25]
	s_mov_b64 s[16:17], s[38:39]
	v_mfma_f32_16x16x32_bf16 v[38:41], v[154:157], v[178:181], v[38:41]
	v_mfma_f32_16x16x32_bf16 v[34:37], v[162:165], v[178:181], v[34:37]
	v_mfma_f32_16x16x32_bf16 v[50:53], v[162:165], v[170:173], v[50:53]
	v_mfma_f32_16x16x32_bf16 v[54:57], v[154:157], v[170:173], v[54:57]
	v_mfma_f32_16x16x32_bf16 v[62:65], v[142:145], v[174:177], v[62:65]
	v_mfma_f32_16x16x32_bf16 v[58:61], v[150:153], v[174:177], v[58:61]
	v_mfma_f32_16x16x32_bf16 v[42:45], v[150:153], v[182:185], v[42:45]
	v_mfma_f32_16x16x32_bf16 v[46:49], v[142:145], v[182:185], v[46:49]
	v_mfma_f32_16x16x32_bf16 v[30:33], v[142:145], v[190:193], v[30:33]
	v_mfma_f32_16x16x32_bf16 v[26:29], v[150:153], v[190:193], v[26:29]
	v_mfma_f32_16x16x32_bf16 v[10:13], v[150:153], v[206:209], v[10:13]
	v_mfma_f32_16x16x32_bf16 v[14:17], v[142:145], v[206:209], v[14:17]
	v_mfma_f32_16x16x32_bf16 v[6:9], v[158:161], v[206:209], v[6:9]
	v_mfma_f32_16x16x32_bf16 v[2:5], v[166:169], v[206:209], v[2:5]
	v_mfma_f32_16x16x32_bf16 v[18:21], v[166:169], v[190:193], v[18:21]
	v_mfma_f32_16x16x32_bf16 v[22:25], v[158:161], v[190:193], v[22:25]
	v_mfma_f32_16x16x32_bf16 v[38:41], v[158:161], v[182:185], v[38:41]
	v_mfma_f32_16x16x32_bf16 v[34:37], v[166:169], v[182:185], v[34:37]
	v_mfma_f32_16x16x32_bf16 v[50:53], v[166:169], v[174:177], v[50:53]
	v_mfma_f32_16x16x32_bf16 v[54:57], v[158:161], v[174:177], v[54:57]
	s_barrier
	s_setprio 0
	s_cbranch_scc0 .LBB0_1514
	s_and_b64 vcc, exec, s[12:13]
	s_cbranch_vccz .LBB0_1517
	s_barrier

; #define PG8_STAGE(bufoff, gbase, voff) do { const int so_ = (int)(unsigned)((const char*)(gbase) - base_##voff); _Pragma("unroll") for (int _i = 0; _i < 2; ++_i) \
;         __builtin_amdgcn_raw_ptr_buffer_load_lds(rs_##voff, (PG8_LAS unsigned*)(lds + (bufoff) + ldsw + _i * 8192), 16, (int)(voff)[_i], so_, 0, 0); } while (0)
; #define PG8_LDA(dst, b, h) do { _Pragma("unroll") for (int m = 0; m < 4; ++m) _Pragma("unroll") for (int k = 0; k < 2; ++k) dst[m][k] = *(const PG8_LAS bf16x8*)(lds + PG8_SA(b, h) + aoff + m * 2048 + k * 1024); } while (0)
; #define PG8_LDB(dst, b, h) do { _Pragma("unroll") for (int n = 0; n < 2; ++n) _Pragma("unroll") for (int k = 0; k < 2; ++k) dst[n][k] = *(const PG8_LAS bf16x8*)(lds + PG8_SB(b, h) + boff + n * 2048 + k * 1024); } while (0)
; #define PG8_MMA(ai, bj, At, Bt) do { __builtin_amdgcn_s_setprio(1); _Pragma("unroll") for (int m = 0; m < 4; ++m) _Pragma("unroll") for (int n = 0; n < 2; ++n) _Pragma("unroll") for (int k = 0; k < 2; ++k) \
;         acc[ai][bj][m][n] = __builtin_amdgcn_mfma_f32_16x16x32_bf16(Bt[n][k], At[m][k], acc[ai][bj][m][n], 0, 0, 0); __builtin_amdgcn_s_setprio(0); } while (0)
; #define PG8_WAIT_V(n) asm volatile("s_waitcnt vmcnt(" #n ")" ::: "memory")
; #define PG8_WAIT_L(n) asm volatile("s_waitcnt lgkmcnt(" #n ")" ::: "memory")
; #define PG8_BAR __builtin_amdgcn_s_barrier()
; #define PG8_SCHED __builtin_amdgcn_sched_barrier(0)
; template <class Epi, class Sched, bool ALIGN_EPI = false, bool SP2 = false>
; __device__ __forceinline__ void gemm_phase(PG8_LAS unsigned char* lds, const Gemm g, const Sched& S, const Epi& E, int tid_in) {
;     ...
;             PG8_LDB(B0, 0, 0); PG8_LDB(B1, 0, 1); PG8_SCHED; PG8_LDA(At, 0, 0); PG8_STAGE(PG8_SA(1, 1), a1 + hstepA, voffA);
;             PG8_WAIT_V(8); PG8_WAIT_L(0); PG8_BAR; PG8_MMA(0, 0, At, B0); PG8_MMA(0, 1, At, B1); PG8_BAR; PG8_SCHED;
;             PG8_LDA(At, 0, 1); PG8_STAGE(PG8_SB(0, 0), b2, voffB); PG8_STAGE(PG8_SB(0, 1), b2 + hstepB, voffB); PG8_STAGE(PG8_SA(0, 0), a2, voffA);
;             PG8_WAIT_V(8); PG8_WAIT_L(0); PG8_BAR; PG8_MMA(1, 0, At, B0); PG8_MMA(1, 1, At, B1); PG8_BAR; PG8_SCHED;
;             PG8_LDB(B0, 1, 0); PG8_LDB(B1, 1, 1); PG8_SCHED; PG8_LDA(At, 1, 0); PG8_STAGE(PG8_SA(0, 1), a2 + hstepA, voffA);
;             PG8_WAIT_V(8); PG8_WAIT_L(0); PG8_BAR; PG8_MMA(0, 0, At, B0); PG8_MMA(0, 1, At, B1); PG8_BAR; PG8_SCHED;
.LBB0_1584:
	v_add_u32_e32 v133, 0x10000, v131
	ds_read_b128 v[134:137], v133
	ds_read_b128 v[138:141], v133 offset:1024
	ds_read_b128 v[142:145], v133 offset:2048
	ds_read_b128 v[146:149], v133 offset:3072
	v_add_u32_e32 v133, 0x14000, v131
	ds_read_b128 v[150:153], v133
	ds_read_b128 v[154:157], v133 offset:1024
	ds_read_b128 v[158:161], v133 offset:2048
	ds_read_b128 v[166:169], v133 offset:3072
	s_add_i32 s43, s38, s22
	s_add_i32 s42, s14, s22
	s_add_i32 s76, s12, s22
	s_addk_i32 s43, 0xff80
	s_sub_i32 s78, s43, 0x160000
	s_cmpk_eq_i32 s39, 0x54
	s_cselect_b32 s77, s16, s42
	s_mov_b32 m0, s68
	ds_read_b128 v[170:173], v132
	ds_read_b128 v[174:177], v132 offset:1024
	ds_read_b128 v[178:181], v132 offset:2048
	ds_read_b128 v[182:185], v132 offset:3072
	ds_read_b128 v[186:189], v132 offset:4096
	ds_read_b128 v[190:193], v132 offset:5120
	ds_read_b128 v[200:203], v132 offset:6144
	ds_read_b128 v[206:209], v132 offset:7168
	s_mov_b32 m0, s63
	s_nop 0
	buffer_load_dwordx4 v130, s[4:7], s78 offen lds
	s_mov_b32 m0, s68
	s_nop 0
	buffer_load_dwordx4 v0, s[4:7], s43 offen lds
	s_mov_b32 m0, s69
	s_nop 0
	buffer_load_dwordx4 v130, s[4:7], s43 offen lds
	s_waitcnt vmcnt(8) lgkmcnt(0)
	s_setprio 1
	s_barrier
	v_mfma_f32_16x16x32_bf16 v[22:25], v[134:137], v[170:173], v[22:25]
	v_mfma_f32_16x16x32_bf16 v[14:17], v[142:145], v[170:173], v[14:17]
	v_mfma_f32_16x16x32_bf16 v[54:57], v[142:145], v[178:181], v[54:57]
	v_mfma_f32_16x16x32_bf16 v[74:77], v[134:137], v[178:181], v[74:77]
	v_mfma_f32_16x16x32_bf16 v[106:109], v[134:137], v[186:189], v[106:109]
	v_mfma_f32_16x16x32_bf16 v[102:105], v[142:145], v[186:189], v[102:105]
	v_mfma_f32_16x16x32_bf16 v[118:121], v[142:145], v[200:203], v[118:121]
	v_mfma_f32_16x16x32_bf16 v[122:125], v[134:137], v[200:203], v[122:125]
	s_cselect_b32 s76, s20, s76
	v_mfma_f32_16x16x32_bf16 v[114:117], v[150:153], v[200:203], v[114:117]
	s_mov_b32 m0, s26
	v_mfma_f32_16x16x32_bf16 v[126:129], v[158:161], v[200:203], v[126:129]
	s_mov_b32 s42, s6
	v_mfma_f32_16x16x32_bf16 v[110:113], v[158:161], v[186:189], v[110:113]
	s_mov_b32 s43, s7
	v_mfma_f32_16x16x32_bf16 v[98:101], v[150:153], v[186:189], v[98:101]
	s_sub_i32 s76, s76, s40
	v_mfma_f32_16x16x32_bf16 v[50:53], v[150:153], v[178:181], v[50:53]
	v_mfma_f32_16x16x32_bf16 v[78:81], v[158:161], v[178:181], v[78:81]
	v_mfma_f32_16x16x32_bf16 v[18:21], v[158:161], v[170:173], v[18:21]
	v_mfma_f32_16x16x32_bf16 v[6:9], v[150:153], v[170:173], v[6:9]
	v_mfma_f32_16x16x32_bf16 v[22:25], v[138:141], v[174:177], v[22:25]
	v_mfma_f32_16x16x32_bf16 v[14:17], v[146:149], v[174:177], v[14:17]
	v_mfma_f32_16x16x32_bf16 v[54:57], v[146:149], v[182:185], v[54:57]
	v_mfma_f32_16x16x32_bf16 v[74:77], v[138:141], v[182:185], v[74:77]
	v_mfma_f32_16x16x32_bf16 v[106:109], v[138:141], v[190:193], v[106:109]
	v_mfma_f32_16x16x32_bf16 v[102:105], v[146:149], v[190:193], v[102:105]
	v_mfma_f32_16x16x32_bf16 v[118:121], v[146:149], v[206:209], v[118:121]
	v_mfma_f32_16x16x32_bf16 v[122:125], v[138:141], v[206:209], v[122:125]
	v_mfma_f32_16x16x32_bf16 v[114:117], v[154:157], v[206:209], v[114:117]
	v_mfma_f32_16x16x32_bf16 v[126:129], v[166:169], v[206:209], v[126:129]
	v_mfma_f32_16x16x32_bf16 v[110:113], v[166:169], v[190:193], v[110:113]
	v_mfma_f32_16x16x32_bf16 v[98:101], v[154:157], v[190:193], v[98:101]
	v_mfma_f32_16x16x32_bf16 v[50:53], v[154:157], v[182:185], v[50:53]
	v_mfma_f32_16x16x32_bf16 v[78:81], v[166:169], v[182:185], v[78:81]
	v_mfma_f32_16x16x32_bf16 v[18:21], v[166:169], v[174:177], v[18:21]
	v_mfma_f32_16x16x32_bf16 v[6:9], v[154:157], v[174:177], v[6:9]
	s_barrier
	s_setprio 0
	ds_read_b128 v[170:173], v132 offset:16384
	ds_read_b128 v[174:177], v132 offset:17408
	ds_read_b128 v[178:181], v132 offset:18432
	ds_read_b128 v[182:185], v132 offset:19456
	ds_read_b128 v[186:189], v132 offset:20480
	ds_read_b128 v[190:193], v132 offset:21504
	ds_read_b128 v[200:203], v132 offset:22528
	ds_read_b128 v[206:209], v132 offset:23552
	buffer_load_dwordx4 v0, s[40:43], s76 offen lds
	s_mov_b32 m0, s44
	s_add_i32 s78, s76, 0x160000
	buffer_load_dwordx4 v130, s[40:43], s76 offen lds
	s_mov_b32 m0, s45
	s_sub_i32 s77, s77, s4
	buffer_load_dwordx4 v0, s[40:43], s78 offen lds
	s_mov_b32 m0, s46
	s_nop 0
	buffer_load_dwordx4 v130, s[40:43], s78 offen lds
	s_mov_b32 m0, s19
	s_nop 0
	buffer_load_dwordx4 v0, s[4:7], s77 offen lds
	s_waitcnt vmcnt(7) lgkmcnt(0)
	s_setprio 1
	s_barrier
	v_mfma_f32_16x16x32_bf16 v[62:65], v[134:137], v[170:173], v[62:65]
	v_mfma_f32_16x16x32_bf16 v[46:49], v[142:145], v[170:173], v[46:49]
	v_mfma_f32_16x16x32_bf16 v[70:73], v[142:145], v[178:181], v[70:73]
	v_mfma_f32_16x16x32_bf16 v[82:85], v[134:137], v[178:181], v[82:85]
	v_mfma_f32_16x16x32_bf16 v[94:97], v[134:137], v[186:189], v[94:97]
	v_mfma_f32_16x16x32_bf16 v[90:93], v[142:145], v[186:189], v[90:93]
	v_mfma_f32_16x16x32_bf16 v[26:29], v[142:145], v[200:203], v[26:29]
	v_mfma_f32_16x16x32_bf16 v[38:41], v[134:137], v[200:203], v[38:41]
	v_mfma_f32_16x16x32_bf16 v[10:13], v[150:153], v[200:203], v[10:13]
	v_mfma_f32_16x16x32_bf16 v[2:5], v[158:161], v[200:203], v[2:5]
	v_mfma_f32_16x16x32_bf16 v[34:37], v[158:161], v[186:189], v[34:37]
	v_mfma_f32_16x16x32_bf16 v[58:61], v[150:153], v[186:189], v[58:61]
	v_mfma_f32_16x16x32_bf16 v[66:69], v[150:153], v[178:181], v[66:69]
	v_mfma_f32_16x16x32_bf16 v[86:89], v[158:161], v[178:181], v[86:89]
	v_mfma_f32_16x16x32_bf16 v[30:33], v[158:161], v[170:173], v[30:33]
	v_mfma_f32_16x16x32_bf16 v[42:45], v[150:153], v[170:173], v[42:45]
	v_mfma_f32_16x16x32_bf16 v[62:65], v[138:141], v[174:177], v[62:65]
	v_mfma_f32_16x16x32_bf16 v[46:49], v[146:149], v[174:177], v[46:49]
	v_mfma_f32_16x16x32_bf16 v[70:73], v[146:149], v[182:185], v[70:73]
	v_mfma_f32_16x16x32_bf16 v[82:85], v[138:141], v[182:185], v[82:85]
	v_mfma_f32_16x16x32_bf16 v[94:97], v[138:141], v[190:193], v[94:97]
	v_mfma_f32_16x16x32_bf16 v[90:93], v[146:149], v[190:193], v[90:93]
	v_mfma_f32_16x16x32_bf16 v[26:29], v[146:149], v[206:209], v[26:29]
	v_mfma_f32_16x16x32_bf16 v[38:41], v[138:141], v[206:209], v[38:41]
	v_add_u32_e32 v133, 0x18000, v131
	v_mfma_f32_16x16x32_bf16 v[10:13], v[154:157], v[206:209], v[10:13]
	v_mfma_f32_16x16x32_bf16 v[2:5], v[166:169], v[206:209], v[2:5]
	v_mfma_f32_16x16x32_bf16 v[34:37], v[166:169], v[190:193], v[34:37]
	v_mfma_f32_16x16x32_bf16 v[58:61], v[154:157], v[190:193], v[58:61]
	v_mfma_f32_16x16x32_bf16 v[66:69], v[154:157], v[182:185], v[66:69]
	v_mfma_f32_16x16x32_bf16 v[86:89], v[166:169], v[182:185], v[86:89]
	v_mfma_f32_16x16x32_bf16 v[30:33], v[166:169], v[174:177], v[30:33]
	v_mfma_f32_16x16x32_bf16 v[42:45], v[154:157], v[174:177], v[42:45]
	s_barrier
; #define PG8_STAGE(bufoff, gbase, voff) do { const int so_ = (int)(unsigned)((const char*)(gbase) - base_##voff); _Pragma("unroll") for (int _i = 0; _i < 2; ++_i) \
;         __builtin_amdgcn_raw_ptr_buffer_load_lds(rs_##voff, (PG8_LAS unsigned*)(lds + (bufoff) + ldsw + _i * 8192), 16, (int)(voff)[_i], so_, 0, 0); } while (0)
; #define PG8_LDA(dst, b, h) do { _Pragma("unroll") for (int m = 0; m < 4; ++m) _Pragma("unroll") for (int k = 0; k < 2; ++k) dst[m][k] = *(const PG8_LAS bf16x8*)(lds + PG8_SA(b, h) + aoff + m * 2048 + k * 1024); } while (0)
; #define PG8_LDB(dst, b, h) do { _Pragma("unroll") for (int n = 0; n < 2; ++n) _Pragma("unroll") for (int k = 0; k < 2; ++k) dst[n][k] = *(const PG8_LAS bf16x8*)(lds + PG8_SB(b, h) + boff + n * 2048 + k * 1024); } while (0)
; #define PG8_MMA(ai, bj, At, Bt) do { __builtin_amdgcn_s_setprio(1); _Pragma("unroll") for (int m = 0; m < 4; ++m) _Pragma("unroll") for (int n = 0; n < 2; ++n) _Pragma("unroll") for (int k = 0; k < 2; ++k) \
;         acc[ai][bj][m][n] = __builtin_amdgcn_mfma_f32_16x16x32_bf16(Bt[n][k], At[m][k], acc[ai][bj][m][n], 0, 0, 0); __builtin_amdgcn_s_setprio(0); } while (0)
; #define PG8_WAIT_V(n) asm volatile("s_waitcnt vmcnt(" #n ")" ::: "memory")
; #define PG8_WAIT_L(n) asm volatile("s_waitcnt lgkmcnt(" #n ")" ::: "memory")
; #define PG8_BAR __builtin_amdgcn_s_barrier()
; #define PG8_SCHED __builtin_amdgcn_sched_barrier(0)
; template <class Epi, class Sched, bool ALIGN_EPI = false, bool SP2 = false>
; __device__ __forceinline__ void gemm_phase(PG8_LAS unsigned char* lds, const Gemm g, const Sched& S, const Epi& E, int tid_in) {
;     ...
;             PG8_LDB(B0, 1, 0); PG8_LDB(B1, 1, 1); PG8_SCHED; PG8_LDA(At, 1, 0); PG8_STAGE(PG8_SA(0, 1), a2 + hstepA, voffA);
;             PG8_WAIT_V(8); PG8_WAIT_L(0); PG8_BAR; PG8_MMA(0, 0, At, B0); PG8_MMA(0, 1, At, B1); PG8_BAR; PG8_SCHED;
;             PG8_LDA(At, 1, 1); PG8_STAGE(PG8_SB(1, 0), b3, voffB); PG8_STAGE(PG8_SB(1, 1), b3 + hstepB, voffB); PG8_STAGE(PG8_SA(1, 0), a3, voffA);
;             PG8_WAIT_V(8); PG8_WAIT_L(0); PG8_BAR; PG8_MMA(1, 0, At, B0); PG8_MMA(1, 1, At, B1); PG8_BAR; PG8_SCHED;
	s_setprio 0
	ds_read_b128 v[134:137], v133
	ds_read_b128 v[138:141], v133 offset:1024
	ds_read_b128 v[142:145], v133 offset:2048
	ds_read_b128 v[146:149], v133 offset:3072
	v_add_u32_e32 v133, 0x1c000, v131
	ds_read_b128 v[150:153], v133
	ds_read_b128 v[154:157], v133 offset:1024
	ds_read_b128 v[158:161], v133 offset:2048
	ds_read_b128 v[166:169], v133 offset:3072
	s_add_i32 s78, s77, 0x160000
	s_mov_b32 m0, s48
	ds_read_b128 v[170:173], v132 offset:32768
	ds_read_b128 v[174:177], v132 offset:33792
	ds_read_b128 v[178:181], v132 offset:34816
	ds_read_b128 v[182:185], v132 offset:35840
	ds_read_b128 v[186:189], v132 offset:36864
	ds_read_b128 v[190:193], v132 offset:37888
	ds_read_b128 v[200:203], v132 offset:38912
	ds_read_b128 v[206:209], v132 offset:39936
	s_mov_b32 m0, s47
	s_nop 0
	buffer_load_dwordx4 v130, s[4:7], s77 offen lds
	s_mov_b32 m0, s48
	s_nop 0
	buffer_load_dwordx4 v0, s[4:7], s78 offen lds
	s_mov_b32 m0, s49
	s_nop 0
	buffer_load_dwordx4 v130, s[4:7], s78 offen lds
	s_waitcnt vmcnt(8) lgkmcnt(0)
	s_setprio 1
	s_barrier
	v_mfma_f32_16x16x32_bf16 v[22:25], v[134:137], v[170:173], v[22:25]
	v_mfma_f32_16x16x32_bf16 v[14:17], v[142:145], v[170:173], v[14:17]
	v_mfma_f32_16x16x32_bf16 v[54:57], v[142:145], v[178:181], v[54:57]
	v_mfma_f32_16x16x32_bf16 v[74:77], v[134:137], v[178:181], v[74:77]
	v_mfma_f32_16x16x32_bf16 v[106:109], v[134:137], v[186:189], v[106:109]
	v_mfma_f32_16x16x32_bf16 v[102:105], v[142:145], v[186:189], v[102:105]
	v_mfma_f32_16x16x32_bf16 v[118:121], v[142:145], v[200:203], v[118:121]
	v_mfma_f32_16x16x32_bf16 v[122:125], v[134:137], v[200:203], v[122:125]
	s_mov_b32 m0, s60
	v_mfma_f32_16x16x32_bf16 v[114:117], v[150:153], v[200:203], v[114:117]
	s_add_i32 s78, s76, 0x80
	v_mfma_f32_16x16x32_bf16 v[126:129], v[158:161], v[200:203], v[126:129]
	v_mfma_f32_16x16x32_bf16 v[110:113], v[158:161], v[186:189], v[110:113]
	v_mfma_f32_16x16x32_bf16 v[98:101], v[150:153], v[186:189], v[98:101]
	v_mfma_f32_16x16x32_bf16 v[50:53], v[150:153], v[178:181], v[50:53]
	v_mfma_f32_16x16x32_bf16 v[78:81], v[158:161], v[178:181], v[78:81]
	v_mfma_f32_16x16x32_bf16 v[18:21], v[158:161], v[170:173], v[18:21]
	v_mfma_f32_16x16x32_bf16 v[6:9], v[150:153], v[170:173], v[6:9]
	v_mfma_f32_16x16x32_bf16 v[22:25], v[138:141], v[174:177], v[22:25]
	v_mfma_f32_16x16x32_bf16 v[14:17], v[146:149], v[174:177], v[14:17]
	v_mfma_f32_16x16x32_bf16 v[54:57], v[146:149], v[182:185], v[54:57]
	v_mfma_f32_16x16x32_bf16 v[74:77], v[138:141], v[182:185], v[74:77]
	v_mfma_f32_16x16x32_bf16 v[106:109], v[138:141], v[190:193], v[106:109]
	v_mfma_f32_16x16x32_bf16 v[102:105], v[146:149], v[190:193], v[102:105]
	v_mfma_f32_16x16x32_bf16 v[118:121], v[146:149], v[206:209], v[118:121]
	v_mfma_f32_16x16x32_bf16 v[122:125], v[138:141], v[206:209], v[122:125]
	v_mfma_f32_16x16x32_bf16 v[114:117], v[154:157], v[206:209], v[114:117]
	v_mfma_f32_16x16x32_bf16 v[126:129], v[166:169], v[206:209], v[126:129]
	v_mfma_f32_16x16x32_bf16 v[110:113], v[166:169], v[190:193], v[110:113]
	v_mfma_f32_16x16x32_bf16 v[98:101], v[154:157], v[190:193], v[98:101]
	v_mfma_f32_16x16x32_bf16 v[50:53], v[154:157], v[182:185], v[50:53]
	v_mfma_f32_16x16x32_bf16 v[78:81], v[166:169], v[182:185], v[78:81]
	v_mfma_f32_16x16x32_bf16 v[18:21], v[166:169], v[174:177], v[18:21]
	v_mfma_f32_16x16x32_bf16 v[6:9], v[154:157], v[174:177], v[6:9]
	s_barrier
	s_setprio 0
	ds_read_b128 v[170:173], v132 offset:49152
	ds_read_b128 v[174:177], v132 offset:50176
	ds_read_b128 v[178:181], v132 offset:51200
	ds_read_b128 v[182:185], v132 offset:52224
	ds_read_b128 v[186:189], v132 offset:53248
	ds_read_b128 v[190:193], v132 offset:54272
	ds_read_b128 v[200:203], v132 offset:55296
	ds_read_b128 v[206:209], v132 offset:56320
	buffer_load_dwordx4 v0, s[40:43], s78 offen lds
	s_mov_b32 m0, s61
	s_add_i32 s76, s76, 0x160080
	buffer_load_dwordx4 v130, s[40:43], s78 offen lds
	s_mov_b32 m0, s66
	s_addk_i32 s77, 0x80
	buffer_load_dwordx4 v0, s[40:43], s76 offen lds
	s_mov_b32 m0, s67
	s_nop 0
	buffer_load_dwordx4 v130, s[40:43], s76 offen lds
	s_mov_b32 m0, s62
	s_nop 0
	buffer_load_dwordx4 v0, s[4:7], s77 offen lds
	s_waitcnt vmcnt(7) lgkmcnt(0)
	s_setprio 1
	s_barrier
;     static __device__ __forceinline__ bool last_of_chain(const Unit& u) { return (u.pn >> 3) == 2; }
; #define PG8_STAGE(bufoff, gbase, voff) do { const int so_ = (int)(unsigned)((const char*)(gbase) - base_##voff); _Pragma("unroll") for (int _i = 0; _i < 2; ++_i) \
;         __builtin_amdgcn_raw_ptr_buffer_load_lds(rs_##voff, (PG8_LAS unsigned*)(lds + (bufoff) + ldsw + _i * 8192), 16, (int)(voff)[_i], so_, 0, 0); } while (0)
; #define PG8_LDA(dst, b, h) do { _Pragma("unroll") for (int m = 0; m < 4; ++m) _Pragma("unroll") for (int k = 0; k < 2; ++k) dst[m][k] = *(const PG8_LAS bf16x8*)(lds + PG8_SA(b, h) + aoff + m * 2048 + k * 1024); } while (0)
; #define PG8_MMA(ai, bj, At, Bt) do { __builtin_amdgcn_s_setprio(1); _Pragma("unroll") for (int m = 0; m < 4; ++m) _Pragma("unroll") for (int n = 0; n < 2; ++n) _Pragma("unroll") for (int k = 0; k < 2; ++k) \
;         acc[ai][bj][m][n] = __builtin_amdgcn_mfma_f32_16x16x32_bf16(Bt[n][k], At[m][k], acc[ai][bj][m][n], 0, 0, 0); __builtin_amdgcn_s_setprio(0); } while (0)
; #define PG8_WAIT_V(n) asm volatile("s_waitcnt vmcnt(" #n ")" ::: "memory")
; #define PG8_WAIT_L(n) asm volatile("s_waitcnt lgkmcnt(" #n ")" ::: "memory")
; #define PG8_BAR __builtin_amdgcn_s_barrier()
; #define PG8_SCHED __builtin_amdgcn_sched_barrier(0)
; template <class Epi, class Sched, bool ALIGN_EPI = false, bool SP2 = false>
; __device__ __forceinline__ void gemm_phase(PG8_LAS unsigned char* lds, const Gemm g, const Sched& S, const Epi& E, int tid_in) {
;     ...
;             PG8_WAIT_V(8); PG8_WAIT_L(0); PG8_BAR; PG8_MMA(0, 0, At, B0); PG8_MMA(0, 1, At, B1); PG8_BAR; PG8_SCHED;
;             PG8_LDA(At, 1, 1); PG8_STAGE(PG8_SB(1, 0), b3, voffB); PG8_STAGE(PG8_SB(1, 1), b3 + hstepB, voffB); PG8_STAGE(PG8_SA(1, 0), a3, voffA);
;             PG8_WAIT_V(8); PG8_WAIT_L(0); PG8_BAR; PG8_MMA(1, 0, At, B0); PG8_MMA(1, 1, At, B1); PG8_BAR; PG8_SCHED;
;     ...
;         if (!has_next) break;
;         bool zero_acc = true; if constexpr (Epi::CHAIN) zero_acc = Epi::last_of_chain(cur);
;         if (zero_acc) {
; #pragma unroll
;         for (int a = 0; a < 2; ++a)
; #pragma unroll
;             for (int b = 0; b < 2; ++b)
; #pragma unroll
;                 for (int m = 0; m < 4; ++m)
; #pragma unroll
;                     for (int n = 0; n < 2; ++n) acc[a][b][m][n] = (f32x4){0.f, 0.f, 0.f, 0.f};
;         }
;         cur = nxt; cA = nA; cB = nB; ++ui;
	v_mfma_f32_16x16x32_bf16 v[62:65], v[134:137], v[170:173], v[62:65]
	v_mfma_f32_16x16x32_bf16 v[46:49], v[142:145], v[170:173], v[46:49]
	v_mfma_f32_16x16x32_bf16 v[70:73], v[142:145], v[178:181], v[70:73]
	v_mfma_f32_16x16x32_bf16 v[82:85], v[134:137], v[178:181], v[82:85]
	v_mfma_f32_16x16x32_bf16 v[94:97], v[134:137], v[186:189], v[94:97]
	v_mfma_f32_16x16x32_bf16 v[90:93], v[142:145], v[186:189], v[90:93]
	v_mfma_f32_16x16x32_bf16 v[26:29], v[142:145], v[200:203], v[26:29]
	v_mfma_f32_16x16x32_bf16 v[38:41], v[134:137], v[200:203], v[38:41]
	s_add_i32 s39, s39, 2
	v_mfma_f32_16x16x32_bf16 v[10:13], v[150:153], v[200:203], v[10:13]
	s_add_u32 s22, s22, 0x100
	v_mfma_f32_16x16x32_bf16 v[2:5], v[158:161], v[200:203], v[2:5]
	s_addc_u32 s23, s23, 0
	v_mfma_f32_16x16x32_bf16 v[34:37], v[158:161], v[186:189], v[34:37]
	v_mfma_f32_16x16x32_bf16 v[58:61], v[150:153], v[186:189], v[58:61]
	v_mfma_f32_16x16x32_bf16 v[66:69], v[150:153], v[178:181], v[66:69]
	v_mfma_f32_16x16x32_bf16 v[86:89], v[158:161], v[178:181], v[86:89]
	v_mfma_f32_16x16x32_bf16 v[30:33], v[158:161], v[170:173], v[30:33]
	v_mfma_f32_16x16x32_bf16 v[42:45], v[150:153], v[170:173], v[42:45]
	v_mfma_f32_16x16x32_bf16 v[62:65], v[138:141], v[174:177], v[62:65]
	v_mfma_f32_16x16x32_bf16 v[46:49], v[146:149], v[174:177], v[46:49]
	v_mfma_f32_16x16x32_bf16 v[70:73], v[146:149], v[182:185], v[70:73]
	v_mfma_f32_16x16x32_bf16 v[82:85], v[138:141], v[182:185], v[82:85]
	v_mfma_f32_16x16x32_bf16 v[94:97], v[138:141], v[190:193], v[94:97]
	v_mfma_f32_16x16x32_bf16 v[90:93], v[146:149], v[190:193], v[90:93]
	v_mfma_f32_16x16x32_bf16 v[26:29], v[146:149], v[206:209], v[26:29]
	v_mfma_f32_16x16x32_bf16 v[38:41], v[138:141], v[206:209], v[38:41]
	v_mfma_f32_16x16x32_bf16 v[10:13], v[154:157], v[206:209], v[10:13]
	v_mfma_f32_16x16x32_bf16 v[2:5], v[166:169], v[206:209], v[2:5]
	v_mfma_f32_16x16x32_bf16 v[34:37], v[166:169], v[190:193], v[34:37]
	v_mfma_f32_16x16x32_bf16 v[58:61], v[154:157], v[190:193], v[58:61]
	v_mfma_f32_16x16x32_bf16 v[66:69], v[154:157], v[182:185], v[66:69]
	v_mfma_f32_16x16x32_bf16 v[86:89], v[166:169], v[182:185], v[86:89]
	v_mfma_f32_16x16x32_bf16 v[30:33], v[166:169], v[174:177], v[30:33]
	v_mfma_f32_16x16x32_bf16 v[42:45], v[154:157], v[174:177], v[42:45]
	s_barrier
	s_setprio 0
	s_cmpk_gt_u32 s39, 0x55
	s_cbranch_scc0 .LBB0_1584
	s_and_b64 vcc, exec, s[36:37]
	s_cbranch_vccnz .LBB0_1572
	v_mov_b32_e32 v2, 0
	s_mov_b32 s10, s73
	s_mov_b32 s25, s74
	s_mov_b64 s[12:13], s[20:21]
	s_mov_b64 s[14:15], s[16:17]
	s_mov_b32 s72, s75
	v_mov_b32_e32 v3, v2
	v_mov_b32_e32 v4, v2
	v_mov_b32_e32 v5, v2
	v_mov_b32_e32 v10, v2
	v_mov_b32_e32 v11, v2
	v_mov_b32_e32 v12, v2
	v_mov_b32_e32 v13, v2
	v_mov_b32_e32 v34, v2
	v_mov_b32_e32 v35, v2
	v_mov_b32_e32 v36, v2
	v_mov_b32_e32 v37, v2
	v_mov_b32_e32 v58, v2
	v_mov_b32_e32 v59, v2
	v_mov_b32_e32 v60, v2
	v_mov_b32_e32 v61, v2
	v_mov_b32_e32 v86, v2
	v_mov_b32_e32 v87, v2
	v_mov_b32_e32 v88, v2
	v_mov_b32_e32 v89, v2
	v_mov_b32_e32 v66, v2
	v_mov_b32_e32 v67, v2
	v_mov_b32_e32 v68, v2
	v_mov_b32_e32 v69, v2
	v_mov_b32_e32 v30, v2
	v_mov_b32_e32 v31, v2
	v_mov_b32_e32 v32, v2
	v_mov_b32_e32 v33, v2
	v_mov_b32_e32 v42, v2
	v_mov_b32_e32 v43, v2
	v_mov_b32_e32 v44, v2
	v_mov_b32_e32 v45, v2
	v_mov_b32_e32 v26, v2
	v_mov_b32_e32 v27, v2
	v_mov_b32_e32 v28, v2
	v_mov_b32_e32 v29, v2
	v_mov_b32_e32 v38, v2
	v_mov_b32_e32 v39, v2
	v_mov_b32_e32 v40, v2
	v_mov_b32_e32 v41, v2
	v_mov_b32_e32 v90, v2
	v_mov_b32_e32 v91, v2
	v_mov_b32_e32 v92, v2
	v_mov_b32_e32 v93, v2
	v_mov_b32_e32 v94, v2
	v_mov_b32_e32 v95, v2
	v_mov_b32_e32 v96, v2
	v_mov_b32_e32 v97, v2
	v_mov_b32_e32 v70, v2
	v_mov_b32_e32 v71, v2
	v_mov_b32_e32 v72, v2
	v_mov_b32_e32 v73, v2
	v_mov_b32_e32 v82, v2
	v_mov_b32_e32 v83, v2
	v_mov_b32_e32 v84, v2
	v_mov_b32_e32 v85, v2
	v_mov_b32_e32 v46, v2
	v_mov_b32_e32 v47, v2
	v_mov_b32_e32 v48, v2
	v_mov_b32_e32 v49, v2
	v_mov_b32_e32 v62, v2
	v_mov_b32_e32 v63, v2
	v_mov_b32_e32 v64, v2
	v_mov_b32_e32 v65, v2
	v_mov_b32_e32 v126, v2
	v_mov_b32_e32 v127, v2
	v_mov_b32_e32 v128, v2
	v_mov_b32_e32 v129, v2
	v_mov_b32_e32 v114, v2
	v_mov_b32_e32 v115, v2
	v_mov_b32_e32 v116, v2
	v_mov_b32_e32 v117, v2
	v_mov_b32_e32 v110, v2
	v_mov_b32_e32 v111, v2
	v_mov_b32_e32 v112, v2
	v_mov_b32_e32 v113, v2
	v_mov_b32_e32 v98, v2
	v_mov_b32_e32 v99, v2
	v_mov_b32_e32 v100, v2
	v_mov_b32_e32 v101, v2
	v_mov_b32_e32 v78, v2
	v_mov_b32_e32 v79, v2
	v_mov_b32_e32 v80, v2
	v_mov_b32_e32 v81, v2
	v_mov_b32_e32 v50, v2
	v_mov_b32_e32 v51, v2
	v_mov_b32_e32 v52, v2
	v_mov_b32_e32 v53, v2
	v_mov_b32_e32 v18, v2
	v_mov_b32_e32 v19, v2
	v_mov_b32_e32 v20, v2
	v_mov_b32_e32 v21, v2
	v_mov_b32_e32 v6, v2
	v_mov_b32_e32 v7, v2
	v_mov_b32_e32 v8, v2
	v_mov_b32_e32 v9, v2
	v_mov_b32_e32 v118, v2
	v_mov_b32_e32 v119, v2
	v_mov_b32_e32 v120, v2
	v_mov_b32_e32 v121, v2
	v_mov_b32_e32 v122, v2
	v_mov_b32_e32 v123, v2
	v_mov_b32_e32 v124, v2
	v_mov_b32_e32 v125, v2
	v_mov_b32_e32 v102, v2
	v_mov_b32_e32 v103, v2
	v_mov_b32_e32 v104, v2
	v_mov_b32_e32 v105, v2
	v_mov_b32_e32 v106, v2
	v_mov_b32_e32 v107, v2
	v_mov_b32_e32 v108, v2
	v_mov_b32_e32 v109, v2
	v_mov_b32_e32 v54, v2
	v_mov_b32_e32 v55, v2
	v_mov_b32_e32 v56, v2
	v_mov_b32_e32 v57, v2
	v_mov_b32_e32 v74, v2
	v_mov_b32_e32 v75, v2
	v_mov_b32_e32 v76, v2
	v_mov_b32_e32 v77, v2
	v_mov_b32_e32 v14, v2
	v_mov_b32_e32 v15, v2
	v_mov_b32_e32 v16, v2
	v_mov_b32_e32 v17, v2
	v_mov_b32_e32 v22, v2
	v_mov_b32_e32 v23, v2
	v_mov_b32_e32 v24, v2
	v_mov_b32_e32 v25, v2
	s_branch .LBB0_1572
